# GEMM peeled first trip: store-aware waits + accumulators start from C=0 in the first MFMA (128 v_mov per unit removed)
# speedup vs baseline: 1.0078x; 1.0078x over previous
; #define PG8_STAGE(bufoff, gbase, voff) do { _Pragma("unroll") for (int _i = 0; _i < 2; ++_i) \
;         __builtin_amdgcn_global_load_lds((const unsigned*)((const char*)(gbase) + (voff)[_i]), (PG8_LAS unsigned*)(lds + (bufoff) + ldsw + _i * 8192), 16, 0, 0); } while (0)
; #define PG8_LDA(dst, b, h) do { _Pragma("unroll") for (int m = 0; m < 4; ++m) _Pragma("unroll") for (int k = 0; k < 2; ++k) dst[m][k] = *(const PG8_LAS bf16x8*)(lds + PG8_SA(b, h) + aoff + m * 2048 + k * 1024); } while (0)
; #define PG8_LDB(dst, b, h) do { _Pragma("unroll") for (int n = 0; n < 2; ++n) _Pragma("unroll") for (int k = 0; k < 2; ++k) dst[n][k] = *(const PG8_LAS bf16x8*)(lds + PG8_SB(b, h) + boff + n * 2048 + k * 1024); } while (0)
; #define PG8_SCHED __builtin_amdgcn_sched_barrier(0)
; template <class Epi, class Sched, bool ALIGN_EPI = false, bool SP2 = false>
; __device__ __forceinline__ void gemm_phase(PG8_LAS unsigned char* lds, const Gemm g, const Sched& S, const Epi& E) {
;     ...
;         const bool has_next = S.next(ui + 1, nxt);
;         const char* nA = has_next ? (const char*)g.A + (size_t)nxt.pm * tstep : cA; const char* nB = has_next ? (const char*)g.Bt + (size_t)nxt.pn * tstep : cB;
; #pragma nounroll
;         for (int t = 0; t < nt; t += 2) {
;             const bool last = (t == nt - 2);
;             const char* a1 = cA + (size_t)(t + 1) * kstep;
;             const char* a2 = last ? nA : cA + (size_t)(t + 2) * kstep; const char* b2 = last ? nB : cB + (size_t)(t + 2) * kstep;
;             const char* a3 = a2 + kstep; const char* b3 = b2 + kstep;
;             if (last && has_next) S.a_ready(nxt);
;             if constexpr (SP2) {
;             PG8_LDB(B0, 0, 0); PG8_LDB(B1, 0, 1); PG8_SCHED; PG8_LDA(At, 0, 0); PG8_STAGE(PG8_SA(1, 1), a1 + hstep, voffA);
;     ...
; #pragma unroll
;         for (int a = 0; a < 2; ++a)
; #pragma unroll
;             for (int b = 0; b < 2; ++b)
; #pragma unroll
;                 for (int m = 0; m < 4; ++m)
; #pragma unroll
;                     for (int n = 0; n < 2; ++n) acc[a][b][m][n] = (f32x4){0.f, 0.f, 0.f, 0.f};
;         cur = nxt; cA = nA; cB = nB; ++ui;
.LBB0_490:
	s_ashr_i32 s11, s10, 31
	s_lshl_b64 s[12:13], s[10:11], 19
	s_add_u32 s12, s24, s12
	s_addc_u32 s13, s25, s13
	s_and_b64 s[14:15], s[2:3], exec
	s_cselect_b32 s11, s13, s19
	s_cselect_b32 s52, s12, s18
	s_ashr_i32 s9, s8, 31
	s_lshl_b64 s[14:15], s[8:9], 19
	s_add_u32 s14, s26, s14
	s_addc_u32 s15, s27, s15
	s_and_b64 s[22:23], s[2:3], exec
	s_cselect_b32 s9, s15, s21
	s_cselect_b32 s53, s14, s20
	s_add_u32 s18, s18, 0x40080
	s_addc_u32 s19, s19, 0
	s_add_u32 s56, s20, 0x100
	s_addc_u32 s57, s21, 0
	s_mov_b32 s60, -2
	ds_read_b128 v[156:159], v151
	ds_read_b128 v[160:163], v151 offset:1024
	ds_read_b128 v[164:167], v151 offset:2048
	ds_read_b128 v[168:171], v151 offset:3072
	ds_read_b128 v[174:177], v152
	ds_read_b128 v[178:181], v152 offset:1024
	ds_read_b128 v[182:185], v152 offset:2048
	ds_read_b128 v[186:189], v152 offset:3072
	s_add_u32 s20, s18, 0xfffc0080
	s_addc_u32 s21, s19, -1
	s_cmp_eq_u32 s60, 12
	s_cselect_b32 s23, s11, s21
	s_cselect_b32 s22, s52, s20
	s_cselect_b32 s21, s9, s57
	s_cselect_b32 s20, s53, s56

; #define PG8_STAGE(bufoff, gbase, voff) do { _Pragma("unroll") for (int _i = 0; _i < 2; ++_i) \
;         __builtin_amdgcn_global_load_lds((const unsigned*)((const char*)(gbase) + (voff)[_i]), (PG8_LAS unsigned*)(lds + (bufoff) + ldsw + _i * 8192), 16, 0, 0); } while (0)
; #define PG8_LDA(dst, b, h) do { _Pragma("unroll") for (int m = 0; m < 4; ++m) _Pragma("unroll") for (int k = 0; k < 2; ++k) dst[m][k] = *(const PG8_LAS bf16x8*)(lds + PG8_SA(b, h) + aoff + m * 2048 + k * 1024); } while (0)
; #define PG8_LDB(dst, b, h) do { _Pragma("unroll") for (int n = 0; n < 2; ++n) _Pragma("unroll") for (int k = 0; k < 2; ++k) dst[n][k] = *(const PG8_LAS bf16x8*)(lds + PG8_SB(b, h) + boff + n * 2048 + k * 1024); } while (0)
; #define PG8_MMA(ai, bj, At, Bt) do { __builtin_amdgcn_s_setprio(1); _Pragma("unroll") for (int m = 0; m < 4; ++m) _Pragma("unroll") for (int n = 0; n < 2; ++n) _Pragma("unroll") for (int k = 0; k < 2; ++k) \
;         acc[ai][bj][m][n] = __builtin_amdgcn_mfma_f32_16x16x32_bf16(Bt[n][k], At[m][k], acc[ai][bj][m][n], 0, 0, 0); __builtin_amdgcn_s_setprio(0); } while (0)
; #define PG8_WAIT_V(n) asm volatile("s_waitcnt vmcnt(" #n ")" ::: "memory")
; #define PG8_WAIT_L(n) asm volatile("s_waitcnt lgkmcnt(" #n ")" ::: "memory")
; #define PG8_BAR __builtin_amdgcn_s_barrier()
; #define PG8_SCHED __builtin_amdgcn_sched_barrier(0)
; template <class Epi, class Sched, bool ALIGN_EPI = false, bool SP2 = false>
; __device__ __forceinline__ void gemm_phase(PG8_LAS unsigned char* lds, const Gemm g, const Sched& S, const Epi& E) {
;     ...
;             PG8_LDB(B0, 0, 0); PG8_LDB(B1, 0, 1); PG8_SCHED; PG8_LDA(At, 0, 0); PG8_STAGE(PG8_SA(1, 1), a1 + hstep, voffA);
;             PG8_WAIT_V(8); PG8_WAIT_L(0); PG8_BAR; PG8_MMA(0, 0, At, B0); PG8_MMA(0, 1, At, B1); PG8_BAR; PG8_SCHED;
	v_lshl_add_u64 v[222:223], s[18:19], 0, v[142:143]
	s_add_i32 m0, s31, 0xc000
	ds_read_b128 v[190:193], v153
	ds_read_b128 v[194:197], v153 offset:1024
	ds_read_b128 v[198:201], v153 offset:2048
	ds_read_b128 v[202:205], v153 offset:3072
	ds_read_b128 v[206:209], v153 offset:4096
	ds_read_b128 v[210:213], v153 offset:5120
	ds_read_b128 v[214:217], v153 offset:6144
	ds_read_b128 v[218:221], v153 offset:7168
	global_load_lds_dwordx4 v[222:223], off
	v_lshl_add_u64 v[222:223], s[18:19], 0, v[144:145]
	s_add_i32 m0, s31, 0xe000
	s_nop 0
	global_load_lds_dwordx4 v[222:223], off
	s_waitcnt vmcnt(24)
	s_waitcnt lgkmcnt(0)
	s_barrier
	s_setprio 1
	s_waitcnt lgkmcnt(0)
	v_mfma_f32_16x16x32_bf16 v[126:129], v[156:159], v[190:193], 0
	v_mfma_f32_16x16x32_bf16 v[122:125], v[164:167], v[190:193], 0
	v_mfma_f32_16x16x32_bf16 v[114:117], v[156:159], v[198:201], 0
	v_mfma_f32_16x16x32_bf16 v[106:109], v[164:167], v[198:201], 0
	v_mfma_f32_16x16x32_bf16 v[98:101], v[156:159], v[206:209], 0
	v_mfma_f32_16x16x32_bf16 v[90:93], v[164:167], v[206:209], 0
	v_mfma_f32_16x16x32_bf16 v[82:85], v[156:159], v[214:217], 0
	v_mfma_f32_16x16x32_bf16 v[74:77], v[164:167], v[214:217], 0
	v_mfma_f32_16x16x32_bf16 v[126:129], v[160:163], v[194:197], v[126:129]
	v_mfma_f32_16x16x32_bf16 v[122:125], v[168:171], v[194:197], v[122:125]
	v_mfma_f32_16x16x32_bf16 v[114:117], v[160:163], v[202:205], v[114:117]
	v_mfma_f32_16x16x32_bf16 v[106:109], v[168:171], v[202:205], v[106:109]
	v_mfma_f32_16x16x32_bf16 v[98:101], v[160:163], v[210:213], v[98:101]
	v_mfma_f32_16x16x32_bf16 v[90:93], v[168:171], v[210:213], v[90:93]
	v_mfma_f32_16x16x32_bf16 v[82:85], v[160:163], v[218:221], v[82:85]
	v_mfma_f32_16x16x32_bf16 v[74:77], v[168:171], v[218:221], v[74:77]
	s_setprio 0
	s_setprio 1
	v_mfma_f32_16x16x32_bf16 v[118:121], v[174:177], v[190:193], 0
	v_mfma_f32_16x16x32_bf16 v[110:113], v[182:185], v[190:193], 0
	v_mfma_f32_16x16x32_bf16 v[102:105], v[174:177], v[198:201], 0
	v_mfma_f32_16x16x32_bf16 v[94:97], v[182:185], v[198:201], 0
	v_mfma_f32_16x16x32_bf16 v[86:89], v[174:177], v[206:209], 0
	v_mfma_f32_16x16x32_bf16 v[78:81], v[182:185], v[206:209], 0
	v_mfma_f32_16x16x32_bf16 v[70:73], v[174:177], v[214:217], 0
	v_mfma_f32_16x16x32_bf16 v[66:69], v[182:185], v[214:217], 0
	v_mfma_f32_16x16x32_bf16 v[118:121], v[178:181], v[194:197], v[118:121]
	v_mfma_f32_16x16x32_bf16 v[110:113], v[186:189], v[194:197], v[110:113]
	v_mfma_f32_16x16x32_bf16 v[102:105], v[178:181], v[202:205], v[102:105]
	v_mfma_f32_16x16x32_bf16 v[94:97], v[186:189], v[202:205], v[94:97]
	v_mfma_f32_16x16x32_bf16 v[86:89], v[178:181], v[210:213], v[86:89]
	v_mfma_f32_16x16x32_bf16 v[78:81], v[186:189], v[210:213], v[78:81]
	v_mfma_f32_16x16x32_bf16 v[70:73], v[178:181], v[218:221], v[70:73]
	v_mfma_f32_16x16x32_bf16 v[66:69], v[186:189], v[218:221], v[66:69]
	s_setprio 0
	s_barrier

; #define PG8_STAGE(bufoff, gbase, voff) do { _Pragma("unroll") for (int _i = 0; _i < 2; ++_i) \
;         __builtin_amdgcn_global_load_lds((const unsigned*)((const char*)(gbase) + (voff)[_i]), (PG8_LAS unsigned*)(lds + (bufoff) + ldsw + _i * 8192), 16, 0, 0); } while (0)
; #define PG8_LDA(dst, b, h) do { _Pragma("unroll") for (int m = 0; m < 4; ++m) _Pragma("unroll") for (int k = 0; k < 2; ++k) dst[m][k] = *(const PG8_LAS bf16x8*)(lds + PG8_SA(b, h) + aoff + m * 2048 + k * 1024); } while (0)
; #define PG8_MMA(ai, bj, At, Bt) do { __builtin_amdgcn_s_setprio(1); _Pragma("unroll") for (int m = 0; m < 4; ++m) _Pragma("unroll") for (int n = 0; n < 2; ++n) _Pragma("unroll") for (int k = 0; k < 2; ++k) \
;         acc[ai][bj][m][n] = __builtin_amdgcn_mfma_f32_16x16x32_bf16(Bt[n][k], At[m][k], acc[ai][bj][m][n], 0, 0, 0); __builtin_amdgcn_s_setprio(0); } while (0)
; #define PG8_WAIT_V(n) asm volatile("s_waitcnt vmcnt(" #n ")" ::: "memory")
; #define PG8_WAIT_L(n) asm volatile("s_waitcnt lgkmcnt(" #n ")" ::: "memory")
; #define PG8_BAR __builtin_amdgcn_s_barrier()
; #define PG8_SCHED __builtin_amdgcn_sched_barrier(0)
; template <class Epi, class Sched, bool ALIGN_EPI = false, bool SP2 = false>
; __device__ __forceinline__ void gemm_phase(PG8_LAS unsigned char* lds, const Gemm g, const Sched& S, const Epi& E) {
;     ...
;             PG8_LDA(At, 0, 1); PG8_STAGE(PG8_SB(0, 0), b2, voffB); PG8_STAGE(PG8_SB(0, 1), b2 + hstep, voffB); PG8_STAGE(PG8_SA(0, 0), a2, voffA);
;             PG8_WAIT_V(8); PG8_WAIT_L(0); PG8_BAR; PG8_MMA(1, 0, At, B0); PG8_MMA(1, 1, At, B1); PG8_BAR; PG8_SCHED;
	s_add_i32 s61, s44, s28
	v_lshl_add_u64 v[222:223], s[20:21], 0, v[134:135]
	s_mov_b32 m0, s61
	ds_read_b128 v[190:193], v153 offset:16384
	ds_read_b128 v[194:197], v153 offset:17408
	ds_read_b128 v[198:201], v153 offset:18432
	ds_read_b128 v[202:205], v153 offset:19456
	ds_read_b128 v[206:209], v153 offset:20480
	ds_read_b128 v[210:213], v153 offset:21504
	ds_read_b128 v[214:217], v153 offset:22528
	ds_read_b128 v[218:221], v153 offset:23552
	global_load_lds_dwordx4 v[222:223], off
	s_add_i32 m0, s61, 0x2000
	s_add_u32 s62, s20, 0x40000
	v_lshl_add_u64 v[224:225], s[20:21], 0, v[130:131]
	s_addc_u32 s63, s21, 0
	s_add_i32 s61, s45, s28
	global_load_lds_dwordx4 v[224:225], off
	v_lshl_add_u64 v[226:227], s[62:63], 0, v[134:135]
	s_mov_b32 m0, s61
	v_lshl_add_u64 v[228:229], s[22:23], 0, v[132:133]
	global_load_lds_dwordx4 v[226:227], off
	v_lshl_add_u64 v[226:227], s[62:63], 0, v[130:131]
	s_add_i32 m0, s61, 0x2000
	s_nop 0
	global_load_lds_dwordx4 v[226:227], off
	v_lshl_add_u64 v[226:227], s[22:23], 0, v[136:137]
	s_mov_b32 m0, s31
	s_nop 0
	global_load_lds_dwordx4 v[226:227], off
	s_mov_b32 m0, s33
	s_nop 0
	global_load_lds_dwordx4 v[228:229], off
	s_waitcnt vmcnt(24)
	s_waitcnt lgkmcnt(0)
	s_barrier
	s_setprio 1
	s_waitcnt lgkmcnt(0)
	v_mfma_f32_16x16x32_bf16 v[62:65], v[156:159], v[190:193], 0
	v_mfma_f32_16x16x32_bf16 v[58:61], v[164:167], v[190:193], 0
	v_mfma_f32_16x16x32_bf16 v[50:53], v[156:159], v[198:201], 0
	v_mfma_f32_16x16x32_bf16 v[42:45], v[164:167], v[198:201], 0
	v_mfma_f32_16x16x32_bf16 v[34:37], v[156:159], v[206:209], 0
	v_mfma_f32_16x16x32_bf16 v[26:29], v[164:167], v[206:209], 0
	v_mfma_f32_16x16x32_bf16 v[18:21], v[156:159], v[214:217], 0
	v_mfma_f32_16x16x32_bf16 v[10:13], v[164:167], v[214:217], 0
	v_mfma_f32_16x16x32_bf16 v[62:65], v[160:163], v[194:197], v[62:65]
	v_mfma_f32_16x16x32_bf16 v[58:61], v[168:171], v[194:197], v[58:61]
	v_mfma_f32_16x16x32_bf16 v[50:53], v[160:163], v[202:205], v[50:53]
	v_mfma_f32_16x16x32_bf16 v[42:45], v[168:171], v[202:205], v[42:45]
	v_mfma_f32_16x16x32_bf16 v[34:37], v[160:163], v[210:213], v[34:37]
	v_mfma_f32_16x16x32_bf16 v[26:29], v[168:171], v[210:213], v[26:29]
	v_mfma_f32_16x16x32_bf16 v[18:21], v[160:163], v[218:221], v[18:21]
	v_mfma_f32_16x16x32_bf16 v[10:13], v[168:171], v[218:221], v[10:13]
	s_setprio 0
	s_setprio 1
	v_mfma_f32_16x16x32_bf16 v[54:57], v[174:177], v[190:193], 0
	v_mfma_f32_16x16x32_bf16 v[46:49], v[182:185], v[190:193], 0
	v_mfma_f32_16x16x32_bf16 v[38:41], v[174:177], v[198:201], 0
	v_mfma_f32_16x16x32_bf16 v[30:33], v[182:185], v[198:201], 0
	v_mfma_f32_16x16x32_bf16 v[22:25], v[174:177], v[206:209], 0
	v_mfma_f32_16x16x32_bf16 v[14:17], v[182:185], v[206:209], 0
	v_mfma_f32_16x16x32_bf16 v[6:9], v[174:177], v[214:217], 0
	v_mfma_f32_16x16x32_bf16 v[2:5], v[182:185], v[214:217], 0
	v_mfma_f32_16x16x32_bf16 v[54:57], v[178:181], v[194:197], v[54:57]
	v_mfma_f32_16x16x32_bf16 v[46:49], v[186:189], v[194:197], v[46:49]
	v_mfma_f32_16x16x32_bf16 v[38:41], v[178:181], v[202:205], v[38:41]
	v_mfma_f32_16x16x32_bf16 v[30:33], v[186:189], v[202:205], v[30:33]
	v_mfma_f32_16x16x32_bf16 v[22:25], v[178:181], v[210:213], v[22:25]
	v_mfma_f32_16x16x32_bf16 v[14:17], v[186:189], v[210:213], v[14:17]
	v_mfma_f32_16x16x32_bf16 v[6:9], v[178:181], v[218:221], v[6:9]
	v_mfma_f32_16x16x32_bf16 v[2:5], v[186:189], v[218:221], v[2:5]
	s_setprio 0
	s_barrier

; #define PG8_STAGE(bufoff, gbase, voff) do { _Pragma("unroll") for (int _i = 0; _i < 2; ++_i) \
;         __builtin_amdgcn_global_load_lds((const unsigned*)((const char*)(gbase) + (voff)[_i]), (PG8_LAS unsigned*)(lds + (bufoff) + ldsw + _i * 8192), 16, 0, 0); } while (0)
; #define PG8_LDA(dst, b, h) do { _Pragma("unroll") for (int m = 0; m < 4; ++m) _Pragma("unroll") for (int k = 0; k < 2; ++k) dst[m][k] = *(const PG8_LAS bf16x8*)(lds + PG8_SA(b, h) + aoff + m * 2048 + k * 1024); } while (0)
; #define PG8_LDB(dst, b, h) do { _Pragma("unroll") for (int n = 0; n < 2; ++n) _Pragma("unroll") for (int k = 0; k < 2; ++k) dst[n][k] = *(const PG8_LAS bf16x8*)(lds + PG8_SB(b, h) + boff + n * 2048 + k * 1024); } while (0)
; #define PG8_SCHED __builtin_amdgcn_sched_barrier(0)
; template <class Epi, class Sched, bool ALIGN_EPI = false, bool SP2 = false>
; __device__ __forceinline__ void gemm_phase(PG8_LAS unsigned char* lds, const Gemm g, const Sched& S, const Epi& E) {
;     ...
;             PG8_LDB(B0, 1, 0); PG8_LDB(B1, 1, 1); PG8_SCHED; PG8_LDA(At, 1, 0); PG8_STAGE(PG8_SA(0, 1), a2 + hstep, voffA);
	s_add_i32 s61, 0, 0x18000
	v_add_u32_e32 v138, s61, v150
	s_add_i32 s62, 0, 0x1c000
	ds_read_b128 v[156:159], v138
	ds_read_b128 v[160:163], v138 offset:1024
	ds_read_b128 v[164:167], v138 offset:2048
	ds_read_b128 v[168:171], v138 offset:3072
	v_add_u32_e32 v138, s62, v150
	ds_read_b128 v[174:177], v138
	ds_read_b128 v[178:181], v138 offset:1024
	ds_read_b128 v[182:185], v138 offset:2048
	ds_read_b128 v[186:189], v138 offset:3072

; #define PG8_STAGE(bufoff, gbase, voff) do { _Pragma("unroll") for (int _i = 0; _i < 2; ++_i) \
;         __builtin_amdgcn_global_load_lds((const unsigned*)((const char*)(gbase) + (voff)[_i]), (PG8_LAS unsigned*)(lds + (bufoff) + ldsw + _i * 8192), 16, 0, 0); } while (0)
; #define PG8_LDA(dst, b, h) do { _Pragma("unroll") for (int m = 0; m < 4; ++m) _Pragma("unroll") for (int k = 0; k < 2; ++k) dst[m][k] = *(const PG8_LAS bf16x8*)(lds + PG8_SA(b, h) + aoff + m * 2048 + k * 1024); } while (0)
; #define PG8_LDB(dst, b, h) do { _Pragma("unroll") for (int n = 0; n < 2; ++n) _Pragma("unroll") for (int k = 0; k < 2; ++k) dst[n][k] = *(const PG8_LAS bf16x8*)(lds + PG8_SB(b, h) + boff + n * 2048 + k * 1024); } while (0)
; #define PG8_MMA(ai, bj, At, Bt) do { __builtin_amdgcn_s_setprio(1); _Pragma("unroll") for (int m = 0; m < 4; ++m) _Pragma("unroll") for (int n = 0; n < 2; ++n) _Pragma("unroll") for (int k = 0; k < 2; ++k) \
;         acc[ai][bj][m][n] = __builtin_amdgcn_mfma_f32_16x16x32_bf16(Bt[n][k], At[m][k], acc[ai][bj][m][n], 0, 0, 0); __builtin_amdgcn_s_setprio(0); } while (0)
; #define PG8_WAIT_V(n) asm volatile("s_waitcnt vmcnt(" #n ")" ::: "memory")
; #define PG8_WAIT_L(n) asm volatile("s_waitcnt lgkmcnt(" #n ")" ::: "memory")
; #define PG8_BAR __builtin_amdgcn_s_barrier()
; #define PG8_SCHED __builtin_amdgcn_sched_barrier(0)
; template <class Epi, class Sched, bool ALIGN_EPI = false, bool SP2 = false>
; __device__ __forceinline__ void gemm_phase(PG8_LAS unsigned char* lds, const Gemm g, const Sched& S, const Epi& E) {
;     ...
;             PG8_LDB(B0, 1, 0); PG8_LDB(B1, 1, 1); PG8_SCHED; PG8_LDA(At, 1, 0); PG8_STAGE(PG8_SA(0, 1), a2 + hstep, voffA);
;             PG8_WAIT_V(8); PG8_WAIT_L(0); PG8_BAR; PG8_MMA(0, 0, At, B0); PG8_MMA(0, 1, At, B1); PG8_BAR; PG8_SCHED;
	s_add_u32 s22, s22, 0x40000
	s_addc_u32 s23, s23, 0
	s_mov_b32 m0, s34
	v_lshl_add_u64 v[230:231], s[22:23], 0, v[136:137]
	ds_read_b128 v[190:193], v153 offset:32768
	ds_read_b128 v[194:197], v153 offset:33792
	ds_read_b128 v[198:201], v153 offset:34816
	ds_read_b128 v[202:205], v153 offset:35840
	ds_read_b128 v[206:209], v153 offset:36864
	ds_read_b128 v[210:213], v153 offset:37888
	ds_read_b128 v[214:217], v153 offset:38912
	ds_read_b128 v[218:221], v153 offset:39936
	global_load_lds_dwordx4 v[230:231], off
	v_lshl_add_u64 v[230:231], s[22:23], 0, v[132:133]
	s_mov_b32 m0, s35
	s_nop 0
	global_load_lds_dwordx4 v[230:231], off
	s_waitcnt vmcnt(8)
	s_waitcnt lgkmcnt(0)
	s_barrier
	s_setprio 1
	s_waitcnt lgkmcnt(0)
	v_mfma_f32_16x16x32_bf16 v[126:129], v[156:159], v[190:193], v[126:129]
	v_mfma_f32_16x16x32_bf16 v[122:125], v[164:167], v[190:193], v[122:125]
	v_mfma_f32_16x16x32_bf16 v[114:117], v[156:159], v[198:201], v[114:117]
	v_mfma_f32_16x16x32_bf16 v[106:109], v[164:167], v[198:201], v[106:109]
	v_mfma_f32_16x16x32_bf16 v[98:101], v[156:159], v[206:209], v[98:101]
	v_mfma_f32_16x16x32_bf16 v[90:93], v[164:167], v[206:209], v[90:93]
	v_mfma_f32_16x16x32_bf16 v[82:85], v[156:159], v[214:217], v[82:85]
	v_mfma_f32_16x16x32_bf16 v[74:77], v[164:167], v[214:217], v[74:77]
	v_mfma_f32_16x16x32_bf16 v[126:129], v[160:163], v[194:197], v[126:129]
	v_mfma_f32_16x16x32_bf16 v[122:125], v[168:171], v[194:197], v[122:125]
	v_mfma_f32_16x16x32_bf16 v[114:117], v[160:163], v[202:205], v[114:117]
	v_mfma_f32_16x16x32_bf16 v[106:109], v[168:171], v[202:205], v[106:109]
	v_mfma_f32_16x16x32_bf16 v[98:101], v[160:163], v[210:213], v[98:101]
	v_mfma_f32_16x16x32_bf16 v[90:93], v[168:171], v[210:213], v[90:93]
	v_mfma_f32_16x16x32_bf16 v[82:85], v[160:163], v[218:221], v[82:85]
	v_mfma_f32_16x16x32_bf16 v[74:77], v[168:171], v[218:221], v[74:77]
	s_setprio 0
	s_setprio 1
	v_mfma_f32_16x16x32_bf16 v[118:121], v[174:177], v[190:193], v[118:121]
	v_mfma_f32_16x16x32_bf16 v[110:113], v[182:185], v[190:193], v[110:113]
	v_mfma_f32_16x16x32_bf16 v[102:105], v[174:177], v[198:201], v[102:105]
	v_mfma_f32_16x16x32_bf16 v[94:97], v[182:185], v[198:201], v[94:97]
	v_mfma_f32_16x16x32_bf16 v[86:89], v[174:177], v[206:209], v[86:89]
	v_mfma_f32_16x16x32_bf16 v[78:81], v[182:185], v[206:209], v[78:81]
	v_mfma_f32_16x16x32_bf16 v[70:73], v[174:177], v[214:217], v[70:73]
	v_mfma_f32_16x16x32_bf16 v[66:69], v[182:185], v[214:217], v[66:69]
	v_mfma_f32_16x16x32_bf16 v[118:121], v[178:181], v[194:197], v[118:121]
	v_mfma_f32_16x16x32_bf16 v[110:113], v[186:189], v[194:197], v[110:113]
	v_mfma_f32_16x16x32_bf16 v[102:105], v[178:181], v[202:205], v[102:105]
	v_mfma_f32_16x16x32_bf16 v[94:97], v[186:189], v[202:205], v[94:97]
	v_mfma_f32_16x16x32_bf16 v[86:89], v[178:181], v[210:213], v[86:89]
	v_mfma_f32_16x16x32_bf16 v[78:81], v[186:189], v[210:213], v[78:81]
	v_mfma_f32_16x16x32_bf16 v[70:73], v[178:181], v[218:221], v[70:73]
	v_mfma_f32_16x16x32_bf16 v[66:69], v[186:189], v[218:221], v[66:69]
	s_setprio 0
	s_barrier

; #define PG8_STAGE(bufoff, gbase, voff) do { _Pragma("unroll") for (int _i = 0; _i < 2; ++_i) \
;         __builtin_amdgcn_global_load_lds((const unsigned*)((const char*)(gbase) + (voff)[_i]), (PG8_LAS unsigned*)(lds + (bufoff) + ldsw + _i * 8192), 16, 0, 0); } while (0)
; #define PG8_LDA(dst, b, h) do { _Pragma("unroll") for (int m = 0; m < 4; ++m) _Pragma("unroll") for (int k = 0; k < 2; ++k) dst[m][k] = *(const PG8_LAS bf16x8*)(lds + PG8_SA(b, h) + aoff + m * 2048 + k * 1024); } while (0)
; #define PG8_MMA(ai, bj, At, Bt) do { __builtin_amdgcn_s_setprio(1); _Pragma("unroll") for (int m = 0; m < 4; ++m) _Pragma("unroll") for (int n = 0; n < 2; ++n) _Pragma("unroll") for (int k = 0; k < 2; ++k) \
;         acc[ai][bj][m][n] = __builtin_amdgcn_mfma_f32_16x16x32_bf16(Bt[n][k], At[m][k], acc[ai][bj][m][n], 0, 0, 0); __builtin_amdgcn_s_setprio(0); } while (0)
; #define PG8_WAIT_V(n) asm volatile("s_waitcnt vmcnt(" #n ")" ::: "memory")
; #define PG8_WAIT_L(n) asm volatile("s_waitcnt lgkmcnt(" #n ")" ::: "memory")
; #define PG8_BAR __builtin_amdgcn_s_barrier()
; #define PG8_SCHED __builtin_amdgcn_sched_barrier(0)
; template <class Epi, class Sched, bool ALIGN_EPI = false, bool SP2 = false>
; __device__ __forceinline__ void gemm_phase(PG8_LAS unsigned char* lds, const Gemm g, const Sched& S, const Epi& E) {
;     ...
;             PG8_LDA(At, 1, 1); PG8_STAGE(PG8_SB(1, 0), b3, voffB); PG8_STAGE(PG8_SB(1, 1), b3 + hstep, voffB); PG8_STAGE(PG8_SA(1, 0), a3, voffA);
;             PG8_WAIT_V(8); PG8_WAIT_L(0); PG8_BAR; PG8_MMA(1, 0, At, B0); PG8_MMA(1, 1, At, B1); PG8_BAR; PG8_SCHED;
	s_add_i32 s22, s61, s28
	v_lshl_add_u64 v[222:223], v[222:223], 0, s[4:5]
	s_mov_b32 m0, s22
	ds_read_b128 v[190:193], v153 offset:49152
	ds_read_b128 v[194:197], v153 offset:50176
	ds_read_b128 v[198:201], v153 offset:51200
	ds_read_b128 v[202:205], v153 offset:52224
	ds_read_b128 v[206:209], v153 offset:53248
	ds_read_b128 v[210:213], v153 offset:54272
	ds_read_b128 v[214:217], v153 offset:55296
	ds_read_b128 v[218:221], v153 offset:56320
	global_load_lds_dwordx4 v[222:223], off
	s_add_i32 m0, s22, 0x2000
	s_add_u32 s20, s20, 0x40080
	v_lshl_add_u64 v[222:223], v[224:225], 0, s[4:5]
	s_addc_u32 s21, s21, 0
	s_add_i32 s22, s62, s28
	global_load_lds_dwordx4 v[222:223], off
	v_lshl_add_u64 v[222:223], s[20:21], 0, v[134:135]
	s_mov_b32 m0, s22
	s_nop 0
	global_load_lds_dwordx4 v[222:223], off
	v_lshl_add_u64 v[222:223], s[20:21], 0, v[130:131]
	s_add_i32 m0, s22, 0x2000
	s_nop 0
	global_load_lds_dwordx4 v[222:223], off
	v_lshl_add_u64 v[222:223], v[226:227], 0, s[4:5]
	s_mov_b32 m0, s39
	s_nop 0
	global_load_lds_dwordx4 v[222:223], off
	v_lshl_add_u64 v[222:223], v[228:229], 0, s[4:5]
	s_mov_b32 m0, s40
	s_nop 0
	global_load_lds_dwordx4 v[222:223], off
	s_waitcnt vmcnt(8)
	s_waitcnt lgkmcnt(0)
	s_barrier
	s_setprio 1
	s_waitcnt lgkmcnt(0)
	v_mfma_f32_16x16x32_bf16 v[62:65], v[156:159], v[190:193], v[62:65]
	v_mfma_f32_16x16x32_bf16 v[58:61], v[164:167], v[190:193], v[58:61]
	v_mfma_f32_16x16x32_bf16 v[50:53], v[156:159], v[198:201], v[50:53]
	v_mfma_f32_16x16x32_bf16 v[42:45], v[164:167], v[198:201], v[42:45]
	v_mfma_f32_16x16x32_bf16 v[34:37], v[156:159], v[206:209], v[34:37]
	v_mfma_f32_16x16x32_bf16 v[26:29], v[164:167], v[206:209], v[26:29]
	v_mfma_f32_16x16x32_bf16 v[18:21], v[156:159], v[214:217], v[18:21]
	v_mfma_f32_16x16x32_bf16 v[10:13], v[164:167], v[214:217], v[10:13]
	v_mfma_f32_16x16x32_bf16 v[62:65], v[160:163], v[194:197], v[62:65]
	v_mfma_f32_16x16x32_bf16 v[58:61], v[168:171], v[194:197], v[58:61]
	v_mfma_f32_16x16x32_bf16 v[50:53], v[160:163], v[202:205], v[50:53]
	v_mfma_f32_16x16x32_bf16 v[42:45], v[168:171], v[202:205], v[42:45]
	v_mfma_f32_16x16x32_bf16 v[34:37], v[160:163], v[210:213], v[34:37]
	v_mfma_f32_16x16x32_bf16 v[26:29], v[168:171], v[210:213], v[26:29]
	v_mfma_f32_16x16x32_bf16 v[18:21], v[160:163], v[218:221], v[18:21]
	v_mfma_f32_16x16x32_bf16 v[10:13], v[168:171], v[218:221], v[10:13]
	s_setprio 0
	s_setprio 1
	v_mfma_f32_16x16x32_bf16 v[54:57], v[174:177], v[190:193], v[54:57]
	v_mfma_f32_16x16x32_bf16 v[46:49], v[182:185], v[190:193], v[46:49]
	v_mfma_f32_16x16x32_bf16 v[38:41], v[174:177], v[198:201], v[38:41]
	v_mfma_f32_16x16x32_bf16 v[30:33], v[182:185], v[198:201], v[30:33]
	v_mfma_f32_16x16x32_bf16 v[22:25], v[174:177], v[206:209], v[22:25]
	v_mfma_f32_16x16x32_bf16 v[14:17], v[182:185], v[206:209], v[14:17]
	v_mfma_f32_16x16x32_bf16 v[6:9], v[174:177], v[214:217], v[6:9]
	v_mfma_f32_16x16x32_bf16 v[2:5], v[182:185], v[214:217], v[2:5]
	v_mfma_f32_16x16x32_bf16 v[54:57], v[178:181], v[194:197], v[54:57]
	v_mfma_f32_16x16x32_bf16 v[46:49], v[186:189], v[194:197], v[46:49]
	v_mfma_f32_16x16x32_bf16 v[38:41], v[178:181], v[202:205], v[38:41]
	v_mfma_f32_16x16x32_bf16 v[30:33], v[186:189], v[202:205], v[30:33]
	v_mfma_f32_16x16x32_bf16 v[22:25], v[178:181], v[210:213], v[22:25]
	v_mfma_f32_16x16x32_bf16 v[14:17], v[186:189], v[210:213], v[14:17]
	v_mfma_f32_16x16x32_bf16 v[6:9], v[178:181], v[218:221], v[6:9]
	v_mfma_f32_16x16x32_bf16 v[2:5], v[186:189], v[218:221], v[2:5]
	s_setprio 0
	s_barrier

; template <class Epi, class Sched, bool ALIGN_EPI = false, bool SP2 = false>
; __device__ __forceinline__ void gemm_phase(PG8_LAS unsigned char* lds, const Gemm g, const Sched& S, const Epi& E) {
;     ...
;         for (int t = 0; t < nt; t += 2) {
;             const bool last = (t == nt - 2);
;             const char* a1 = cA + (size_t)(t + 1) * kstep;
;             const char* a2 = last ? nA : cA + (size_t)(t + 2) * kstep; const char* b2 = last ? nB : cB + (size_t)(t + 2) * kstep;
;             const char* a3 = a2 + kstep; const char* b3 = b2 + kstep;
	s_add_i32 s60, s60, 2
	s_add_u32 s18, s18, 0x100
	s_addc_u32 s19, s19, 0
	s_add_u32 s56, s56, 0x100
	s_addc_u32 s57, s57, 0

; #define PG8_STAGE(bufoff, gbase, voff) do { _Pragma("unroll") for (int _i = 0; _i < 2; ++_i) \
;         __builtin_amdgcn_global_load_lds((const unsigned*)((const char*)(gbase) + (voff)[_i]), (PG8_LAS unsigned*)(lds + (bufoff) + ldsw + _i * 8192), 16, 0, 0); } while (0)
; #define PG8_LDA(dst, b, h) do { _Pragma("unroll") for (int m = 0; m < 4; ++m) _Pragma("unroll") for (int k = 0; k < 2; ++k) dst[m][k] = *(const PG8_LAS bf16x8*)(lds + PG8_SA(b, h) + aoff + m * 2048 + k * 1024); } while (0)
; #define PG8_LDB(dst, b, h) do { _Pragma("unroll") for (int n = 0; n < 2; ++n) _Pragma("unroll") for (int k = 0; k < 2; ++k) dst[n][k] = *(const PG8_LAS bf16x8*)(lds + PG8_SB(b, h) + boff + n * 2048 + k * 1024); } while (0)
; #define PG8_SCHED __builtin_amdgcn_sched_barrier(0)
; template <class Epi, class Sched, bool ALIGN_EPI = false, bool SP2 = false>
; __device__ __forceinline__ void gemm_phase(PG8_LAS unsigned char* lds, const Gemm g, const Sched& S, const Epi& E) {
;     ...
;         const bool has_next = S.next(ui + 1, nxt);
;         const char* nA = has_next ? (const char*)g.A + (size_t)nxt.pm * tstep : cA; const char* nB = has_next ? (const char*)g.Bt + (size_t)nxt.pn * tstep : cB;
; #pragma nounroll
;         for (int t = 0; t < nt; t += 2) {
;             const bool last = (t == nt - 2);
;             const char* a1 = cA + (size_t)(t + 1) * kstep;
;             const char* a2 = last ? nA : cA + (size_t)(t + 2) * kstep; const char* b2 = last ? nB : cB + (size_t)(t + 2) * kstep;
;             const char* a3 = a2 + kstep; const char* b3 = b2 + kstep;
;             if (last && has_next) S.a_ready(nxt);
;             if constexpr (SP2) {
;             PG8_LDB(B0, 0, 0); PG8_LDB(B1, 0, 1); PG8_SCHED; PG8_LDA(At, 0, 0); PG8_STAGE(PG8_SA(1, 1), a1 + hstep, voffA);
;     ...
; #pragma unroll
;         for (int a = 0; a < 2; ++a)
; #pragma unroll
;             for (int b = 0; b < 2; ++b)
; #pragma unroll
;                 for (int m = 0; m < 4; ++m)
; #pragma unroll
;                     for (int n = 0; n < 2; ++n) acc[a][b][m][n] = (f32x4){0.f, 0.f, 0.f, 0.f};
;         cur = nxt; cA = nA; cB = nB; ++ui;
.LBB0_688:
	s_ashr_i32 s23, s22, 31
	s_lshl_b64 s[24:25], s[22:23], 19
	s_add_u32 s24, s33, s24
	s_addc_u32 s25, s38, s25
	s_and_b64 s[26:27], s[2:3], exec
	s_cselect_b32 s23, s25, s29
	s_cselect_b32 s70, s24, s28
	s_ashr_i32 s21, s20, 31
	s_lshl_b64 s[26:27], s[20:21], 19
	s_add_u32 s26, s39, s26
	s_addc_u32 s27, s40, s27
	s_and_b64 s[34:35], s[2:3], exec
	s_cselect_b32 s21, s27, s31
	s_cselect_b32 s71, s26, s30
	s_add_u32 s28, s28, 0x40080
	s_addc_u32 s29, s29, 0
	s_add_u32 s72, s30, 0x100
	s_addc_u32 s73, s31, 0
	s_mov_b32 s74, -2
	ds_read_b128 v[148:151], v157
	ds_read_b128 v[152:155], v157 offset:1024
	ds_read_b128 v[160:163], v157 offset:2048
	ds_read_b128 v[164:167], v157 offset:3072
	ds_read_b128 v[168:171], v158
	ds_read_b128 v[174:177], v158 offset:1024
	ds_read_b128 v[178:181], v158 offset:2048
	ds_read_b128 v[182:185], v158 offset:3072
	s_add_u32 s30, s28, 0xfffc0080
	s_addc_u32 s31, s29, -1
	s_cmp_eq_u32 s74, 12
	s_cselect_b32 s35, s23, s31
	s_cselect_b32 s34, s70, s30
	s_cselect_b32 s31, s21, s73
	s_cselect_b32 s30, s71, s72

; #define PG8_STAGE(bufoff, gbase, voff) do { _Pragma("unroll") for (int _i = 0; _i < 2; ++_i) \
;         __builtin_amdgcn_global_load_lds((const unsigned*)((const char*)(gbase) + (voff)[_i]), (PG8_LAS unsigned*)(lds + (bufoff) + ldsw + _i * 8192), 16, 0, 0); } while (0)
; #define PG8_LDA(dst, b, h) do { _Pragma("unroll") for (int m = 0; m < 4; ++m) _Pragma("unroll") for (int k = 0; k < 2; ++k) dst[m][k] = *(const PG8_LAS bf16x8*)(lds + PG8_SA(b, h) + aoff + m * 2048 + k * 1024); } while (0)
; #define PG8_LDB(dst, b, h) do { _Pragma("unroll") for (int n = 0; n < 2; ++n) _Pragma("unroll") for (int k = 0; k < 2; ++k) dst[n][k] = *(const PG8_LAS bf16x8*)(lds + PG8_SB(b, h) + boff + n * 2048 + k * 1024); } while (0)
; #define PG8_MMA(ai, bj, At, Bt) do { __builtin_amdgcn_s_setprio(1); _Pragma("unroll") for (int m = 0; m < 4; ++m) _Pragma("unroll") for (int n = 0; n < 2; ++n) _Pragma("unroll") for (int k = 0; k < 2; ++k) \
;         acc[ai][bj][m][n] = __builtin_amdgcn_mfma_f32_16x16x32_bf16(Bt[n][k], At[m][k], acc[ai][bj][m][n], 0, 0, 0); __builtin_amdgcn_s_setprio(0); } while (0)
; #define PG8_WAIT_V(n) asm volatile("s_waitcnt vmcnt(" #n ")" ::: "memory")
; #define PG8_WAIT_L(n) asm volatile("s_waitcnt lgkmcnt(" #n ")" ::: "memory")
; #define PG8_BAR __builtin_amdgcn_s_barrier()
; #define PG8_SCHED __builtin_amdgcn_sched_barrier(0)
; template <class Epi, class Sched, bool ALIGN_EPI = false, bool SP2 = false>
; __device__ __forceinline__ void gemm_phase(PG8_LAS unsigned char* lds, const Gemm g, const Sched& S, const Epi& E) {
;     ...
;             PG8_LDB(B0, 0, 0); PG8_LDB(B1, 0, 1); PG8_SCHED; PG8_LDA(At, 0, 0); PG8_STAGE(PG8_SA(1, 1), a1 + hstep, voffA);
;             PG8_WAIT_V(8); PG8_WAIT_L(0); PG8_BAR; PG8_MMA(0, 0, At, B0); PG8_MMA(0, 1, At, B1); PG8_BAR; PG8_SCHED;
	v_lshl_add_u64 v[218:219], s[28:29], 0, v[140:141]
	s_add_i32 m0, s44, 0xc000
	ds_read_b128 v[186:189], v159
	ds_read_b128 v[190:193], v159 offset:1024
	ds_read_b128 v[194:197], v159 offset:2048
	ds_read_b128 v[198:201], v159 offset:3072
	ds_read_b128 v[202:205], v159 offset:4096
	ds_read_b128 v[206:209], v159 offset:5120
	ds_read_b128 v[210:213], v159 offset:6144
	ds_read_b128 v[214:217], v159 offset:7168
	global_load_lds_dwordx4 v[218:219], off
	v_lshl_add_u64 v[218:219], s[28:29], 0, v[142:143]
	s_add_i32 m0, s44, 0xe000
	s_nop 0
	global_load_lds_dwordx4 v[218:219], off
	s_waitcnt vmcnt(24)
	s_waitcnt lgkmcnt(0)
	s_barrier
	s_setprio 1
	s_waitcnt lgkmcnt(0)
	v_mfma_f32_16x16x32_bf16 v[126:129], v[148:151], v[186:189], 0
	v_mfma_f32_16x16x32_bf16 v[122:125], v[160:163], v[186:189], 0
	v_mfma_f32_16x16x32_bf16 v[114:117], v[148:151], v[194:197], 0
	v_mfma_f32_16x16x32_bf16 v[106:109], v[160:163], v[194:197], 0
	v_mfma_f32_16x16x32_bf16 v[98:101], v[148:151], v[202:205], 0
	v_mfma_f32_16x16x32_bf16 v[90:93], v[160:163], v[202:205], 0
	v_mfma_f32_16x16x32_bf16 v[82:85], v[148:151], v[210:213], 0
	v_mfma_f32_16x16x32_bf16 v[74:77], v[160:163], v[210:213], 0
	v_mfma_f32_16x16x32_bf16 v[126:129], v[152:155], v[190:193], v[126:129]
	v_mfma_f32_16x16x32_bf16 v[122:125], v[164:167], v[190:193], v[122:125]
	v_mfma_f32_16x16x32_bf16 v[114:117], v[152:155], v[198:201], v[114:117]
	v_mfma_f32_16x16x32_bf16 v[106:109], v[164:167], v[198:201], v[106:109]
	v_mfma_f32_16x16x32_bf16 v[98:101], v[152:155], v[206:209], v[98:101]
	v_mfma_f32_16x16x32_bf16 v[90:93], v[164:167], v[206:209], v[90:93]
	v_mfma_f32_16x16x32_bf16 v[82:85], v[152:155], v[214:217], v[82:85]
	v_mfma_f32_16x16x32_bf16 v[74:77], v[164:167], v[214:217], v[74:77]
	s_setprio 0
	s_setprio 1
	v_mfma_f32_16x16x32_bf16 v[118:121], v[168:171], v[186:189], 0
	v_mfma_f32_16x16x32_bf16 v[110:113], v[178:181], v[186:189], 0
	v_mfma_f32_16x16x32_bf16 v[102:105], v[168:171], v[194:197], 0
	v_mfma_f32_16x16x32_bf16 v[94:97], v[178:181], v[194:197], 0
	v_mfma_f32_16x16x32_bf16 v[86:89], v[168:171], v[202:205], 0
	v_mfma_f32_16x16x32_bf16 v[78:81], v[178:181], v[202:205], 0
	v_mfma_f32_16x16x32_bf16 v[70:73], v[168:171], v[210:213], 0
	v_mfma_f32_16x16x32_bf16 v[66:69], v[178:181], v[210:213], 0
	v_mfma_f32_16x16x32_bf16 v[118:121], v[174:177], v[190:193], v[118:121]
	v_mfma_f32_16x16x32_bf16 v[110:113], v[182:185], v[190:193], v[110:113]
	v_mfma_f32_16x16x32_bf16 v[102:105], v[174:177], v[198:201], v[102:105]
	v_mfma_f32_16x16x32_bf16 v[94:97], v[182:185], v[198:201], v[94:97]
	v_mfma_f32_16x16x32_bf16 v[86:89], v[174:177], v[206:209], v[86:89]
	v_mfma_f32_16x16x32_bf16 v[78:81], v[182:185], v[206:209], v[78:81]
	v_mfma_f32_16x16x32_bf16 v[70:73], v[174:177], v[214:217], v[70:73]
	v_mfma_f32_16x16x32_bf16 v[66:69], v[182:185], v[214:217], v[66:69]
	s_setprio 0
	s_barrier

; #define PG8_STAGE(bufoff, gbase, voff) do { _Pragma("unroll") for (int _i = 0; _i < 2; ++_i) \
;         __builtin_amdgcn_global_load_lds((const unsigned*)((const char*)(gbase) + (voff)[_i]), (PG8_LAS unsigned*)(lds + (bufoff) + ldsw + _i * 8192), 16, 0, 0); } while (0)
; #define PG8_LDA(dst, b, h) do { _Pragma("unroll") for (int m = 0; m < 4; ++m) _Pragma("unroll") for (int k = 0; k < 2; ++k) dst[m][k] = *(const PG8_LAS bf16x8*)(lds + PG8_SA(b, h) + aoff + m * 2048 + k * 1024); } while (0)
; #define PG8_MMA(ai, bj, At, Bt) do { __builtin_amdgcn_s_setprio(1); _Pragma("unroll") for (int m = 0; m < 4; ++m) _Pragma("unroll") for (int n = 0; n < 2; ++n) _Pragma("unroll") for (int k = 0; k < 2; ++k) \
;         acc[ai][bj][m][n] = __builtin_amdgcn_mfma_f32_16x16x32_bf16(Bt[n][k], At[m][k], acc[ai][bj][m][n], 0, 0, 0); __builtin_amdgcn_s_setprio(0); } while (0)
; #define PG8_WAIT_V(n) asm volatile("s_waitcnt vmcnt(" #n ")" ::: "memory")
; #define PG8_WAIT_L(n) asm volatile("s_waitcnt lgkmcnt(" #n ")" ::: "memory")
; #define PG8_BAR __builtin_amdgcn_s_barrier()
; #define PG8_SCHED __builtin_amdgcn_sched_barrier(0)
; template <class Epi, class Sched, bool ALIGN_EPI = false, bool SP2 = false>
; __device__ __forceinline__ void gemm_phase(PG8_LAS unsigned char* lds, const Gemm g, const Sched& S, const Epi& E) {
;     ...
;             PG8_LDA(At, 0, 1); PG8_STAGE(PG8_SB(0, 0), b2, voffB); PG8_STAGE(PG8_SB(0, 1), b2 + hstep, voffB); PG8_STAGE(PG8_SA(0, 0), a2, voffA);
;             PG8_WAIT_V(8); PG8_WAIT_L(0); PG8_BAR; PG8_MMA(1, 0, At, B0); PG8_MMA(1, 1, At, B1); PG8_BAR; PG8_SCHED;
	s_add_i32 s75, s63, s41
	v_lshl_add_u64 v[218:219], s[30:31], 0, v[136:137]
	s_mov_b32 m0, s75
	ds_read_b128 v[186:189], v159 offset:16384
	ds_read_b128 v[190:193], v159 offset:17408
	ds_read_b128 v[194:197], v159 offset:18432
	ds_read_b128 v[198:201], v159 offset:19456
	ds_read_b128 v[202:205], v159 offset:20480
	ds_read_b128 v[206:209], v159 offset:21504
	ds_read_b128 v[210:213], v159 offset:22528
	ds_read_b128 v[214:217], v159 offset:23552
	global_load_lds_dwordx4 v[218:219], off
	s_add_i32 m0, s75, 0x2000
	s_add_u32 s76, s30, 0x40000
	v_lshl_add_u64 v[220:221], s[30:31], 0, v[132:133]
	s_addc_u32 s77, s31, 0
	s_add_i32 s75, s66, s41
	global_load_lds_dwordx4 v[220:221], off
	v_lshl_add_u64 v[222:223], s[76:77], 0, v[136:137]
	s_mov_b32 m0, s75
	v_lshl_add_u64 v[224:225], s[34:35], 0, v[134:135]
	global_load_lds_dwordx4 v[222:223], off
	v_lshl_add_u64 v[222:223], s[76:77], 0, v[132:133]
	s_add_i32 m0, s75, 0x2000
	s_nop 0
	global_load_lds_dwordx4 v[222:223], off
	v_lshl_add_u64 v[222:223], s[34:35], 0, v[138:139]
	s_mov_b32 m0, s44
	s_nop 0
	global_load_lds_dwordx4 v[222:223], off
	s_mov_b32 m0, s45
	s_nop 0
	global_load_lds_dwordx4 v[224:225], off
	s_waitcnt vmcnt(24)
	s_waitcnt lgkmcnt(0)
	s_barrier
	s_setprio 1
	s_waitcnt lgkmcnt(0)
	v_mfma_f32_16x16x32_bf16 v[62:65], v[148:151], v[186:189], 0
	v_mfma_f32_16x16x32_bf16 v[58:61], v[160:163], v[186:189], 0
	v_mfma_f32_16x16x32_bf16 v[50:53], v[148:151], v[194:197], 0
	v_mfma_f32_16x16x32_bf16 v[42:45], v[160:163], v[194:197], 0
	v_mfma_f32_16x16x32_bf16 v[34:37], v[148:151], v[202:205], 0
	v_mfma_f32_16x16x32_bf16 v[26:29], v[160:163], v[202:205], 0
	v_mfma_f32_16x16x32_bf16 v[18:21], v[148:151], v[210:213], 0
	v_mfma_f32_16x16x32_bf16 v[10:13], v[160:163], v[210:213], 0
	v_mfma_f32_16x16x32_bf16 v[62:65], v[152:155], v[190:193], v[62:65]
	v_mfma_f32_16x16x32_bf16 v[58:61], v[164:167], v[190:193], v[58:61]
	v_mfma_f32_16x16x32_bf16 v[50:53], v[152:155], v[198:201], v[50:53]
	v_mfma_f32_16x16x32_bf16 v[42:45], v[164:167], v[198:201], v[42:45]
	v_mfma_f32_16x16x32_bf16 v[34:37], v[152:155], v[206:209], v[34:37]
	v_mfma_f32_16x16x32_bf16 v[26:29], v[164:167], v[206:209], v[26:29]
	v_mfma_f32_16x16x32_bf16 v[18:21], v[152:155], v[214:217], v[18:21]
	v_mfma_f32_16x16x32_bf16 v[10:13], v[164:167], v[214:217], v[10:13]
	s_setprio 0
	s_setprio 1
	v_mfma_f32_16x16x32_bf16 v[54:57], v[168:171], v[186:189], 0
	v_mfma_f32_16x16x32_bf16 v[46:49], v[178:181], v[186:189], 0
	v_mfma_f32_16x16x32_bf16 v[38:41], v[168:171], v[194:197], 0
	v_mfma_f32_16x16x32_bf16 v[30:33], v[178:181], v[194:197], 0
	v_mfma_f32_16x16x32_bf16 v[22:25], v[168:171], v[202:205], 0
	v_mfma_f32_16x16x32_bf16 v[14:17], v[178:181], v[202:205], 0
	v_mfma_f32_16x16x32_bf16 v[6:9], v[168:171], v[210:213], 0
	v_mfma_f32_16x16x32_bf16 v[2:5], v[178:181], v[210:213], 0
	v_mfma_f32_16x16x32_bf16 v[54:57], v[174:177], v[190:193], v[54:57]
	v_mfma_f32_16x16x32_bf16 v[46:49], v[182:185], v[190:193], v[46:49]
	v_mfma_f32_16x16x32_bf16 v[38:41], v[174:177], v[198:201], v[38:41]
	v_mfma_f32_16x16x32_bf16 v[30:33], v[182:185], v[198:201], v[30:33]
	v_mfma_f32_16x16x32_bf16 v[22:25], v[174:177], v[206:209], v[22:25]
	v_mfma_f32_16x16x32_bf16 v[14:17], v[182:185], v[206:209], v[14:17]
	v_mfma_f32_16x16x32_bf16 v[6:9], v[174:177], v[214:217], v[6:9]
	v_mfma_f32_16x16x32_bf16 v[2:5], v[182:185], v[214:217], v[2:5]
	s_setprio 0
	s_barrier

; #define PG8_STAGE(bufoff, gbase, voff) do { _Pragma("unroll") for (int _i = 0; _i < 2; ++_i) \
;         __builtin_amdgcn_global_load_lds((const unsigned*)((const char*)(gbase) + (voff)[_i]), (PG8_LAS unsigned*)(lds + (bufoff) + ldsw + _i * 8192), 16, 0, 0); } while (0)
; #define PG8_LDA(dst, b, h) do { _Pragma("unroll") for (int m = 0; m < 4; ++m) _Pragma("unroll") for (int k = 0; k < 2; ++k) dst[m][k] = *(const PG8_LAS bf16x8*)(lds + PG8_SA(b, h) + aoff + m * 2048 + k * 1024); } while (0)
; #define PG8_LDB(dst, b, h) do { _Pragma("unroll") for (int n = 0; n < 2; ++n) _Pragma("unroll") for (int k = 0; k < 2; ++k) dst[n][k] = *(const PG8_LAS bf16x8*)(lds + PG8_SB(b, h) + boff + n * 2048 + k * 1024); } while (0)
; #define PG8_SCHED __builtin_amdgcn_sched_barrier(0)
; template <class Epi, class Sched, bool ALIGN_EPI = false, bool SP2 = false>
; __device__ __forceinline__ void gemm_phase(PG8_LAS unsigned char* lds, const Gemm g, const Sched& S, const Epi& E) {
;     ...
;             PG8_LDB(B0, 1, 0); PG8_LDB(B1, 1, 1); PG8_SCHED; PG8_LDA(At, 1, 0); PG8_STAGE(PG8_SA(0, 1), a2 + hstep, voffA);
	s_add_i32 s75, 0, 0x18000
	s_add_i32 s76, 0, 0x1c000
	v_add_u32_e32 v164, s75, v131
	v_add_u32_e32 v182, s76, v131
	ds_read_b128 v[148:151], v164
	ds_read_b128 v[152:155], v164 offset:1024
	ds_read_b128 v[160:163], v164 offset:2048
	ds_read_b128 v[164:167], v164 offset:3072
	ds_read_b128 v[168:171], v182
	ds_read_b128 v[174:177], v182 offset:1024
	ds_read_b128 v[178:181], v182 offset:2048
	ds_read_b128 v[182:185], v182 offset:3072

; #define PG8_STAGE(bufoff, gbase, voff) do { _Pragma("unroll") for (int _i = 0; _i < 2; ++_i) \
;         __builtin_amdgcn_global_load_lds((const unsigned*)((const char*)(gbase) + (voff)[_i]), (PG8_LAS unsigned*)(lds + (bufoff) + ldsw + _i * 8192), 16, 0, 0); } while (0)
; #define PG8_LDA(dst, b, h) do { _Pragma("unroll") for (int m = 0; m < 4; ++m) _Pragma("unroll") for (int k = 0; k < 2; ++k) dst[m][k] = *(const PG8_LAS bf16x8*)(lds + PG8_SA(b, h) + aoff + m * 2048 + k * 1024); } while (0)
; #define PG8_LDB(dst, b, h) do { _Pragma("unroll") for (int n = 0; n < 2; ++n) _Pragma("unroll") for (int k = 0; k < 2; ++k) dst[n][k] = *(const PG8_LAS bf16x8*)(lds + PG8_SB(b, h) + boff + n * 2048 + k * 1024); } while (0)
; #define PG8_MMA(ai, bj, At, Bt) do { __builtin_amdgcn_s_setprio(1); _Pragma("unroll") for (int m = 0; m < 4; ++m) _Pragma("unroll") for (int n = 0; n < 2; ++n) _Pragma("unroll") for (int k = 0; k < 2; ++k) \
;         acc[ai][bj][m][n] = __builtin_amdgcn_mfma_f32_16x16x32_bf16(Bt[n][k], At[m][k], acc[ai][bj][m][n], 0, 0, 0); __builtin_amdgcn_s_setprio(0); } while (0)
; #define PG8_WAIT_V(n) asm volatile("s_waitcnt vmcnt(" #n ")" ::: "memory")
; #define PG8_WAIT_L(n) asm volatile("s_waitcnt lgkmcnt(" #n ")" ::: "memory")
; #define PG8_BAR __builtin_amdgcn_s_barrier()
; #define PG8_SCHED __builtin_amdgcn_sched_barrier(0)
; template <class Epi, class Sched, bool ALIGN_EPI = false, bool SP2 = false>
; __device__ __forceinline__ void gemm_phase(PG8_LAS unsigned char* lds, const Gemm g, const Sched& S, const Epi& E) {
;     ...
;             PG8_LDB(B0, 1, 0); PG8_LDB(B1, 1, 1); PG8_SCHED; PG8_LDA(At, 1, 0); PG8_STAGE(PG8_SA(0, 1), a2 + hstep, voffA);
;             PG8_WAIT_V(8); PG8_WAIT_L(0); PG8_BAR; PG8_MMA(0, 0, At, B0); PG8_MMA(0, 1, At, B1); PG8_BAR; PG8_SCHED;
	s_add_u32 s34, s34, 0x40000
	s_addc_u32 s35, s35, 0
	s_mov_b32 m0, s52
	v_lshl_add_u64 v[226:227], s[34:35], 0, v[138:139]
	ds_read_b128 v[186:189], v159 offset:32768
	ds_read_b128 v[190:193], v159 offset:33792
	ds_read_b128 v[194:197], v159 offset:34816
	ds_read_b128 v[198:201], v159 offset:35840
	ds_read_b128 v[202:205], v159 offset:36864
	ds_read_b128 v[206:209], v159 offset:37888
	ds_read_b128 v[210:213], v159 offset:38912
	ds_read_b128 v[214:217], v159 offset:39936
	global_load_lds_dwordx4 v[226:227], off
	v_lshl_add_u64 v[226:227], s[34:35], 0, v[134:135]
	s_mov_b32 m0, s53
	s_nop 0
	global_load_lds_dwordx4 v[226:227], off
	s_waitcnt vmcnt(8)
	s_waitcnt lgkmcnt(0)
	s_barrier
	s_setprio 1
	s_waitcnt lgkmcnt(0)
	v_mfma_f32_16x16x32_bf16 v[126:129], v[148:151], v[186:189], v[126:129]
	v_mfma_f32_16x16x32_bf16 v[122:125], v[160:163], v[186:189], v[122:125]
	v_mfma_f32_16x16x32_bf16 v[114:117], v[148:151], v[194:197], v[114:117]
	v_mfma_f32_16x16x32_bf16 v[106:109], v[160:163], v[194:197], v[106:109]
	v_mfma_f32_16x16x32_bf16 v[98:101], v[148:151], v[202:205], v[98:101]
	v_mfma_f32_16x16x32_bf16 v[90:93], v[160:163], v[202:205], v[90:93]
	v_mfma_f32_16x16x32_bf16 v[82:85], v[148:151], v[210:213], v[82:85]
	v_mfma_f32_16x16x32_bf16 v[74:77], v[160:163], v[210:213], v[74:77]
	v_mfma_f32_16x16x32_bf16 v[126:129], v[152:155], v[190:193], v[126:129]
	v_mfma_f32_16x16x32_bf16 v[122:125], v[164:167], v[190:193], v[122:125]
	v_mfma_f32_16x16x32_bf16 v[114:117], v[152:155], v[198:201], v[114:117]
	v_mfma_f32_16x16x32_bf16 v[106:109], v[164:167], v[198:201], v[106:109]
	v_mfma_f32_16x16x32_bf16 v[98:101], v[152:155], v[206:209], v[98:101]
	v_mfma_f32_16x16x32_bf16 v[90:93], v[164:167], v[206:209], v[90:93]
	v_mfma_f32_16x16x32_bf16 v[82:85], v[152:155], v[214:217], v[82:85]
	v_mfma_f32_16x16x32_bf16 v[74:77], v[164:167], v[214:217], v[74:77]
	s_setprio 0
	s_setprio 1
	v_mfma_f32_16x16x32_bf16 v[118:121], v[168:171], v[186:189], v[118:121]
	v_mfma_f32_16x16x32_bf16 v[110:113], v[178:181], v[186:189], v[110:113]
	v_mfma_f32_16x16x32_bf16 v[102:105], v[168:171], v[194:197], v[102:105]
	v_mfma_f32_16x16x32_bf16 v[94:97], v[178:181], v[194:197], v[94:97]
	v_mfma_f32_16x16x32_bf16 v[86:89], v[168:171], v[202:205], v[86:89]
	v_mfma_f32_16x16x32_bf16 v[78:81], v[178:181], v[202:205], v[78:81]
	v_mfma_f32_16x16x32_bf16 v[70:73], v[168:171], v[210:213], v[70:73]
	v_mfma_f32_16x16x32_bf16 v[66:69], v[178:181], v[210:213], v[66:69]
	v_mfma_f32_16x16x32_bf16 v[118:121], v[174:177], v[190:193], v[118:121]
	v_mfma_f32_16x16x32_bf16 v[110:113], v[182:185], v[190:193], v[110:113]
	v_mfma_f32_16x16x32_bf16 v[102:105], v[174:177], v[198:201], v[102:105]
	v_mfma_f32_16x16x32_bf16 v[94:97], v[182:185], v[198:201], v[94:97]
	v_mfma_f32_16x16x32_bf16 v[86:89], v[174:177], v[206:209], v[86:89]
	v_mfma_f32_16x16x32_bf16 v[78:81], v[182:185], v[206:209], v[78:81]
	v_mfma_f32_16x16x32_bf16 v[70:73], v[174:177], v[214:217], v[70:73]
	v_mfma_f32_16x16x32_bf16 v[66:69], v[182:185], v[214:217], v[66:69]
	s_setprio 0
	s_barrier

; #define PG8_STAGE(bufoff, gbase, voff) do { _Pragma("unroll") for (int _i = 0; _i < 2; ++_i) \
;         __builtin_amdgcn_global_load_lds((const unsigned*)((const char*)(gbase) + (voff)[_i]), (PG8_LAS unsigned*)(lds + (bufoff) + ldsw + _i * 8192), 16, 0, 0); } while (0)
; #define PG8_LDA(dst, b, h) do { _Pragma("unroll") for (int m = 0; m < 4; ++m) _Pragma("unroll") for (int k = 0; k < 2; ++k) dst[m][k] = *(const PG8_LAS bf16x8*)(lds + PG8_SA(b, h) + aoff + m * 2048 + k * 1024); } while (0)
; #define PG8_MMA(ai, bj, At, Bt) do { __builtin_amdgcn_s_setprio(1); _Pragma("unroll") for (int m = 0; m < 4; ++m) _Pragma("unroll") for (int n = 0; n < 2; ++n) _Pragma("unroll") for (int k = 0; k < 2; ++k) \
;         acc[ai][bj][m][n] = __builtin_amdgcn_mfma_f32_16x16x32_bf16(Bt[n][k], At[m][k], acc[ai][bj][m][n], 0, 0, 0); __builtin_amdgcn_s_setprio(0); } while (0)
; #define PG8_WAIT_V(n) asm volatile("s_waitcnt vmcnt(" #n ")" ::: "memory")
; #define PG8_WAIT_L(n) asm volatile("s_waitcnt lgkmcnt(" #n ")" ::: "memory")
; #define PG8_BAR __builtin_amdgcn_s_barrier()
; #define PG8_SCHED __builtin_amdgcn_sched_barrier(0)
; template <class Epi, class Sched, bool ALIGN_EPI = false, bool SP2 = false>
; __device__ __forceinline__ void gemm_phase(PG8_LAS unsigned char* lds, const Gemm g, const Sched& S, const Epi& E) {
;     ...
;             PG8_LDA(At, 1, 1); PG8_STAGE(PG8_SB(1, 0), b3, voffB); PG8_STAGE(PG8_SB(1, 1), b3 + hstep, voffB); PG8_STAGE(PG8_SA(1, 0), a3, voffA);
;             PG8_WAIT_V(8); PG8_WAIT_L(0); PG8_BAR; PG8_MMA(1, 0, At, B0); PG8_MMA(1, 1, At, B1); PG8_BAR; PG8_SCHED;
	s_add_i32 s34, s75, s41
	v_lshl_add_u64 v[218:219], v[218:219], 0, s[10:11]
	s_mov_b32 m0, s34
	ds_read_b128 v[186:189], v159 offset:49152
	ds_read_b128 v[190:193], v159 offset:50176
	ds_read_b128 v[194:197], v159 offset:51200
	ds_read_b128 v[198:201], v159 offset:52224
	ds_read_b128 v[202:205], v159 offset:53248
	ds_read_b128 v[206:209], v159 offset:54272
	ds_read_b128 v[210:213], v159 offset:55296
	ds_read_b128 v[214:217], v159 offset:56320
	global_load_lds_dwordx4 v[218:219], off
	s_add_i32 m0, s34, 0x2000
	s_add_u32 s30, s30, 0x40080
	v_lshl_add_u64 v[218:219], v[220:221], 0, s[10:11]
	s_addc_u32 s31, s31, 0
	s_add_i32 s34, s76, s41
	global_load_lds_dwordx4 v[218:219], off
	v_lshl_add_u64 v[218:219], s[30:31], 0, v[136:137]
	s_mov_b32 m0, s34
	s_nop 0
	global_load_lds_dwordx4 v[218:219], off
	v_lshl_add_u64 v[218:219], s[30:31], 0, v[132:133]
	s_add_i32 m0, s34, 0x2000
	s_nop 0
	global_load_lds_dwordx4 v[218:219], off
	v_lshl_add_u64 v[218:219], v[222:223], 0, s[10:11]
	s_mov_b32 m0, s57
	s_nop 0
	global_load_lds_dwordx4 v[218:219], off
	v_lshl_add_u64 v[218:219], v[224:225], 0, s[10:11]
	s_mov_b32 m0, s60
	s_nop 0
	global_load_lds_dwordx4 v[218:219], off
	s_waitcnt vmcnt(8)
	s_waitcnt lgkmcnt(0)
	s_barrier
	s_setprio 1
	s_waitcnt lgkmcnt(0)
	v_mfma_f32_16x16x32_bf16 v[62:65], v[148:151], v[186:189], v[62:65]
	v_mfma_f32_16x16x32_bf16 v[58:61], v[160:163], v[186:189], v[58:61]
	v_mfma_f32_16x16x32_bf16 v[50:53], v[148:151], v[194:197], v[50:53]
	v_mfma_f32_16x16x32_bf16 v[42:45], v[160:163], v[194:197], v[42:45]
	v_mfma_f32_16x16x32_bf16 v[34:37], v[148:151], v[202:205], v[34:37]
	v_mfma_f32_16x16x32_bf16 v[26:29], v[160:163], v[202:205], v[26:29]
	v_mfma_f32_16x16x32_bf16 v[18:21], v[148:151], v[210:213], v[18:21]
	v_mfma_f32_16x16x32_bf16 v[10:13], v[160:163], v[210:213], v[10:13]
	v_mfma_f32_16x16x32_bf16 v[62:65], v[152:155], v[190:193], v[62:65]
	v_mfma_f32_16x16x32_bf16 v[58:61], v[164:167], v[190:193], v[58:61]
	v_mfma_f32_16x16x32_bf16 v[50:53], v[152:155], v[198:201], v[50:53]
	v_mfma_f32_16x16x32_bf16 v[42:45], v[164:167], v[198:201], v[42:45]
	v_mfma_f32_16x16x32_bf16 v[34:37], v[152:155], v[206:209], v[34:37]
	v_mfma_f32_16x16x32_bf16 v[26:29], v[164:167], v[206:209], v[26:29]
	v_mfma_f32_16x16x32_bf16 v[18:21], v[152:155], v[214:217], v[18:21]
	v_mfma_f32_16x16x32_bf16 v[10:13], v[164:167], v[214:217], v[10:13]
	s_setprio 0
	s_setprio 1
	v_mfma_f32_16x16x32_bf16 v[54:57], v[168:171], v[186:189], v[54:57]
	v_mfma_f32_16x16x32_bf16 v[46:49], v[178:181], v[186:189], v[46:49]
	v_mfma_f32_16x16x32_bf16 v[38:41], v[168:171], v[194:197], v[38:41]
	v_mfma_f32_16x16x32_bf16 v[30:33], v[178:181], v[194:197], v[30:33]
	v_mfma_f32_16x16x32_bf16 v[22:25], v[168:171], v[202:205], v[22:25]
	v_mfma_f32_16x16x32_bf16 v[14:17], v[178:181], v[202:205], v[14:17]
	v_mfma_f32_16x16x32_bf16 v[6:9], v[168:171], v[210:213], v[6:9]
	v_mfma_f32_16x16x32_bf16 v[2:5], v[178:181], v[210:213], v[2:5]
	v_mfma_f32_16x16x32_bf16 v[54:57], v[174:177], v[190:193], v[54:57]
	v_mfma_f32_16x16x32_bf16 v[46:49], v[182:185], v[190:193], v[46:49]
	v_mfma_f32_16x16x32_bf16 v[38:41], v[174:177], v[198:201], v[38:41]
	v_mfma_f32_16x16x32_bf16 v[30:33], v[182:185], v[198:201], v[30:33]
	v_mfma_f32_16x16x32_bf16 v[22:25], v[174:177], v[206:209], v[22:25]
	v_mfma_f32_16x16x32_bf16 v[14:17], v[182:185], v[206:209], v[14:17]
	v_mfma_f32_16x16x32_bf16 v[6:9], v[174:177], v[214:217], v[6:9]
	v_mfma_f32_16x16x32_bf16 v[2:5], v[182:185], v[214:217], v[2:5]
	s_setprio 0
	s_barrier

; template <class Epi, class Sched, bool ALIGN_EPI = false, bool SP2 = false>
; __device__ __forceinline__ void gemm_phase(PG8_LAS unsigned char* lds, const Gemm g, const Sched& S, const Epi& E) {
;     ...
;         for (int t = 0; t < nt; t += 2) {
;             const bool last = (t == nt - 2);
;             const char* a1 = cA + (size_t)(t + 1) * kstep;
;             const char* a2 = last ? nA : cA + (size_t)(t + 2) * kstep; const char* b2 = last ? nB : cB + (size_t)(t + 2) * kstep;
;             const char* a3 = a2 + kstep; const char* b3 = b2 + kstep;
	s_add_i32 s74, s74, 2
	s_add_u32 s28, s28, 0x100
	s_addc_u32 s29, s29, 0
	s_add_u32 s72, s72, 0x100
	s_addc_u32 s73, s73, 0

; #define PG8_STAGE(bufoff, gbase, voff) do { _Pragma("unroll") for (int _i = 0; _i < 2; ++_i) \
;         __builtin_amdgcn_global_load_lds((const unsigned*)((const char*)(gbase) + (voff)[_i]), (PG8_LAS unsigned*)(lds + (bufoff) + ldsw + _i * 8192), 16, 0, 0); } while (0)
; #define PG8_LDA(dst, b, h) do { _Pragma("unroll") for (int m = 0; m < 4; ++m) _Pragma("unroll") for (int k = 0; k < 2; ++k) dst[m][k] = *(const PG8_LAS bf16x8*)(lds + PG8_SA(b, h) + aoff + m * 2048 + k * 1024); } while (0)
; #define PG8_LDB(dst, b, h) do { _Pragma("unroll") for (int n = 0; n < 2; ++n) _Pragma("unroll") for (int k = 0; k < 2; ++k) dst[n][k] = *(const PG8_LAS bf16x8*)(lds + PG8_SB(b, h) + boff + n * 2048 + k * 1024); } while (0)
; #define PG8_SCHED __builtin_amdgcn_sched_barrier(0)
; template <class Epi, class Sched, bool ALIGN_EPI = false, bool SP2 = false>
; __device__ __forceinline__ void gemm_phase(PG8_LAS unsigned char* lds, const Gemm g, const Sched& S, const Epi& E) {
;     ...
;         const bool has_next = S.next(ui + 1, nxt);
;         const char* nA = has_next ? (const char*)g.A + (size_t)nxt.pm * tstep : cA; const char* nB = has_next ? (const char*)g.Bt + (size_t)nxt.pn * tstep : cB;
; #pragma nounroll
;         for (int t = 0; t < nt; t += 2) {
;             const bool last = (t == nt - 2);
;             const char* a1 = cA + (size_t)(t + 1) * kstep;
;             const char* a2 = last ? nA : cA + (size_t)(t + 2) * kstep; const char* b2 = last ? nB : cB + (size_t)(t + 2) * kstep;
;             const char* a3 = a2 + kstep; const char* b3 = b2 + kstep;
;             if (last && has_next) S.a_ready(nxt);
;             if constexpr (SP2) {
;             PG8_LDB(B0, 0, 0); PG8_LDB(B1, 0, 1); PG8_SCHED; PG8_LDA(At, 0, 0); PG8_STAGE(PG8_SA(1, 1), a1 + hstep, voffA);
;     ...
; #pragma unroll
;         for (int a = 0; a < 2; ++a)
; #pragma unroll
;             for (int b = 0; b < 2; ++b)
; #pragma unroll
;                 for (int m = 0; m < 4; ++m)
; #pragma unroll
;                     for (int n = 0; n < 2; ++n) acc[a][b][m][n] = (f32x4){0.f, 0.f, 0.f, 0.f};
;         cur = nxt; cA = nA; cB = nB; ++ui;
.LBB0_1220:
	s_ashr_i32 s29, s28, 31
	s_lshl_b64 s[30:31], s[28:29], 19
	s_add_u32 s30, s44, s30
	s_addc_u32 s31, s45, s31
	s_and_b64 s[34:35], s[2:3], exec
	s_cselect_b32 s29, s31, s39
	s_cselect_b32 s67, s30, s38
	s_ashr_i32 s27, s26, 31
	s_lshl_b64 s[34:35], s[26:27], 19
	s_add_u32 s34, s52, s34
	s_addc_u32 s35, s53, s35
	s_and_b64 s[42:43], s[2:3], exec
	s_cselect_b32 s27, s35, s41
	s_cselect_b32 s68, s34, s40
	s_add_u32 s38, s38, 0x40080
	s_addc_u32 s39, s39, 0
	s_add_u32 s69, s40, 0x100
	s_addc_u32 s70, s41, 0
	s_mov_b32 s71, -2
	ds_read_b128 v[154:157], v150
	ds_read_b128 v[158:161], v150 offset:1024
	ds_read_b128 v[162:165], v150 offset:2048
	ds_read_b128 v[166:169], v150 offset:3072
	ds_read_b128 v[174:177], v151
	ds_read_b128 v[178:181], v151 offset:1024
	ds_read_b128 v[182:185], v151 offset:2048
	ds_read_b128 v[186:189], v151 offset:3072
	s_add_u32 s40, s38, 0xfffc0080
	s_addc_u32 s41, s39, -1
	s_cmp_eq_u32 s71, 12
	s_cselect_b32 s43, s29, s41
	s_cselect_b32 s42, s67, s40
	s_cselect_b32 s41, s27, s70
	s_cselect_b32 s40, s68, s69

; #define PG8_STAGE(bufoff, gbase, voff) do { _Pragma("unroll") for (int _i = 0; _i < 2; ++_i) \
;         __builtin_amdgcn_global_load_lds((const unsigned*)((const char*)(gbase) + (voff)[_i]), (PG8_LAS unsigned*)(lds + (bufoff) + ldsw + _i * 8192), 16, 0, 0); } while (0)
; #define PG8_LDA(dst, b, h) do { _Pragma("unroll") for (int m = 0; m < 4; ++m) _Pragma("unroll") for (int k = 0; k < 2; ++k) dst[m][k] = *(const PG8_LAS bf16x8*)(lds + PG8_SA(b, h) + aoff + m * 2048 + k * 1024); } while (0)
; #define PG8_LDB(dst, b, h) do { _Pragma("unroll") for (int n = 0; n < 2; ++n) _Pragma("unroll") for (int k = 0; k < 2; ++k) dst[n][k] = *(const PG8_LAS bf16x8*)(lds + PG8_SB(b, h) + boff + n * 2048 + k * 1024); } while (0)
; #define PG8_MMA(ai, bj, At, Bt) do { __builtin_amdgcn_s_setprio(1); _Pragma("unroll") for (int m = 0; m < 4; ++m) _Pragma("unroll") for (int n = 0; n < 2; ++n) _Pragma("unroll") for (int k = 0; k < 2; ++k) \
;         acc[ai][bj][m][n] = __builtin_amdgcn_mfma_f32_16x16x32_bf16(Bt[n][k], At[m][k], acc[ai][bj][m][n], 0, 0, 0); __builtin_amdgcn_s_setprio(0); } while (0)
; #define PG8_WAIT_V(n) asm volatile("s_waitcnt vmcnt(" #n ")" ::: "memory")
; #define PG8_WAIT_L(n) asm volatile("s_waitcnt lgkmcnt(" #n ")" ::: "memory")
; #define PG8_BAR __builtin_amdgcn_s_barrier()
; #define PG8_SCHED __builtin_amdgcn_sched_barrier(0)
; template <class Epi, class Sched, bool ALIGN_EPI = false, bool SP2 = false>
; __device__ __forceinline__ void gemm_phase(PG8_LAS unsigned char* lds, const Gemm g, const Sched& S, const Epi& E) {
;     ...
;             PG8_LDB(B0, 0, 0); PG8_LDB(B1, 0, 1); PG8_SCHED; PG8_LDA(At, 0, 0); PG8_STAGE(PG8_SA(1, 1), a1 + hstep, voffA);
;             PG8_WAIT_V(8); PG8_WAIT_L(0); PG8_BAR; PG8_MMA(0, 0, At, B0); PG8_MMA(0, 1, At, B1); PG8_BAR; PG8_SCHED;
	v_lshl_add_u64 v[146:147], s[38:39], 0, v[138:139]
	s_add_i32 m0, s55, 0xc000
	ds_read_b128 v[190:193], v152
	ds_read_b128 v[194:197], v152 offset:1024
	ds_read_b128 v[198:201], v152 offset:2048
	ds_read_b128 v[202:205], v152 offset:3072
	ds_read_b128 v[206:209], v152 offset:4096
	ds_read_b128 v[210:213], v152 offset:5120
	ds_read_b128 v[214:217], v152 offset:6144
	ds_read_b128 v[218:221], v152 offset:7168
	global_load_lds_dwordx4 v[146:147], off
	v_lshl_add_u64 v[146:147], s[38:39], 0, v[140:141]
	s_add_i32 m0, s55, 0xe000
	s_nop 0
	global_load_lds_dwordx4 v[146:147], off
	s_waitcnt vmcnt(24)
	s_waitcnt lgkmcnt(0)
	s_barrier
	s_setprio 1
	s_waitcnt lgkmcnt(0)
	v_mfma_f32_16x16x32_bf16 v[126:129], v[154:157], v[190:193], 0
	v_mfma_f32_16x16x32_bf16 v[122:125], v[162:165], v[190:193], 0
	v_mfma_f32_16x16x32_bf16 v[110:113], v[154:157], v[198:201], 0
	v_mfma_f32_16x16x32_bf16 v[106:109], v[162:165], v[198:201], 0
	v_mfma_f32_16x16x32_bf16 v[94:97], v[154:157], v[206:209], 0
	v_mfma_f32_16x16x32_bf16 v[90:93], v[162:165], v[206:209], 0
	v_mfma_f32_16x16x32_bf16 v[78:81], v[154:157], v[214:217], 0
	v_mfma_f32_16x16x32_bf16 v[74:77], v[162:165], v[214:217], 0
	v_mfma_f32_16x16x32_bf16 v[126:129], v[158:161], v[194:197], v[126:129]
	v_mfma_f32_16x16x32_bf16 v[122:125], v[166:169], v[194:197], v[122:125]
	v_mfma_f32_16x16x32_bf16 v[110:113], v[158:161], v[202:205], v[110:113]
	v_mfma_f32_16x16x32_bf16 v[106:109], v[166:169], v[202:205], v[106:109]
	v_mfma_f32_16x16x32_bf16 v[94:97], v[158:161], v[210:213], v[94:97]
	v_mfma_f32_16x16x32_bf16 v[90:93], v[166:169], v[210:213], v[90:93]
	v_mfma_f32_16x16x32_bf16 v[78:81], v[158:161], v[218:221], v[78:81]
	v_mfma_f32_16x16x32_bf16 v[74:77], v[166:169], v[218:221], v[74:77]
	s_setprio 0
	s_setprio 1
	v_mfma_f32_16x16x32_bf16 v[118:121], v[174:177], v[190:193], 0
	v_mfma_f32_16x16x32_bf16 v[114:117], v[182:185], v[190:193], 0
	v_mfma_f32_16x16x32_bf16 v[102:105], v[174:177], v[198:201], 0
	v_mfma_f32_16x16x32_bf16 v[98:101], v[182:185], v[198:201], 0
	v_mfma_f32_16x16x32_bf16 v[86:89], v[174:177], v[206:209], 0
	v_mfma_f32_16x16x32_bf16 v[82:85], v[182:185], v[206:209], 0
	v_mfma_f32_16x16x32_bf16 v[70:73], v[174:177], v[214:217], 0
	v_mfma_f32_16x16x32_bf16 v[66:69], v[182:185], v[214:217], 0
	v_mfma_f32_16x16x32_bf16 v[118:121], v[178:181], v[194:197], v[118:121]
	v_mfma_f32_16x16x32_bf16 v[114:117], v[186:189], v[194:197], v[114:117]
	v_mfma_f32_16x16x32_bf16 v[102:105], v[178:181], v[202:205], v[102:105]
	v_mfma_f32_16x16x32_bf16 v[98:101], v[186:189], v[202:205], v[98:101]
	v_mfma_f32_16x16x32_bf16 v[86:89], v[178:181], v[210:213], v[86:89]
	v_mfma_f32_16x16x32_bf16 v[82:85], v[186:189], v[210:213], v[82:85]
	v_mfma_f32_16x16x32_bf16 v[70:73], v[178:181], v[218:221], v[70:73]
	v_mfma_f32_16x16x32_bf16 v[66:69], v[186:189], v[218:221], v[66:69]
	s_setprio 0
	s_barrier

; #define PG8_STAGE(bufoff, gbase, voff) do { _Pragma("unroll") for (int _i = 0; _i < 2; ++_i) \
;         __builtin_amdgcn_global_load_lds((const unsigned*)((const char*)(gbase) + (voff)[_i]), (PG8_LAS unsigned*)(lds + (bufoff) + ldsw + _i * 8192), 16, 0, 0); } while (0)
; #define PG8_LDA(dst, b, h) do { _Pragma("unroll") for (int m = 0; m < 4; ++m) _Pragma("unroll") for (int k = 0; k < 2; ++k) dst[m][k] = *(const PG8_LAS bf16x8*)(lds + PG8_SA(b, h) + aoff + m * 2048 + k * 1024); } while (0)
; #define PG8_MMA(ai, bj, At, Bt) do { __builtin_amdgcn_s_setprio(1); _Pragma("unroll") for (int m = 0; m < 4; ++m) _Pragma("unroll") for (int n = 0; n < 2; ++n) _Pragma("unroll") for (int k = 0; k < 2; ++k) \
;         acc[ai][bj][m][n] = __builtin_amdgcn_mfma_f32_16x16x32_bf16(Bt[n][k], At[m][k], acc[ai][bj][m][n], 0, 0, 0); __builtin_amdgcn_s_setprio(0); } while (0)
; #define PG8_WAIT_V(n) asm volatile("s_waitcnt vmcnt(" #n ")" ::: "memory")
; #define PG8_WAIT_L(n) asm volatile("s_waitcnt lgkmcnt(" #n ")" ::: "memory")
; #define PG8_BAR __builtin_amdgcn_s_barrier()
; #define PG8_SCHED __builtin_amdgcn_sched_barrier(0)
; template <class Epi, class Sched, bool ALIGN_EPI = false, bool SP2 = false>
; __device__ __forceinline__ void gemm_phase(PG8_LAS unsigned char* lds, const Gemm g, const Sched& S, const Epi& E) {
;     ...
;             PG8_LDA(At, 0, 1); PG8_STAGE(PG8_SB(0, 0), b2, voffB); PG8_STAGE(PG8_SB(0, 1), b2 + hstep, voffB); PG8_STAGE(PG8_SA(0, 0), a2, voffA);
;             PG8_WAIT_V(8); PG8_WAIT_L(0); PG8_BAR; PG8_MMA(1, 0, At, B0); PG8_MMA(1, 1, At, B1); PG8_BAR; PG8_SCHED;
	s_add_i32 s72, s64, s54
	v_lshl_add_u64 v[146:147], s[40:41], 0, v[132:133]
	s_mov_b32 m0, s72
	ds_read_b128 v[190:193], v152 offset:16384
	ds_read_b128 v[194:197], v152 offset:17408
	ds_read_b128 v[198:201], v152 offset:18432
	ds_read_b128 v[202:205], v152 offset:19456
	ds_read_b128 v[206:209], v152 offset:20480
	ds_read_b128 v[210:213], v152 offset:21504
	ds_read_b128 v[214:217], v152 offset:22528
	ds_read_b128 v[218:221], v152 offset:23552
	global_load_lds_dwordx4 v[146:147], off
	s_add_i32 m0, s72, 0x2000
	s_add_u32 s72, s40, 0x40000
	v_lshl_add_u64 v[170:171], s[40:41], 0, v[136:137]
	s_addc_u32 s73, s41, 0
	s_add_i32 s74, s65, s54
	global_load_lds_dwordx4 v[170:171], off
	v_lshl_add_u64 v[222:223], s[72:73], 0, v[132:133]
	s_mov_b32 m0, s74
	v_lshl_add_u64 v[224:225], s[42:43], 0, v[134:135]
	global_load_lds_dwordx4 v[222:223], off
	v_lshl_add_u64 v[222:223], s[72:73], 0, v[136:137]
	s_add_i32 m0, s74, 0x2000
	s_nop 0
	global_load_lds_dwordx4 v[222:223], off
	v_lshl_add_u64 v[222:223], s[42:43], 0, v[130:131]
	s_mov_b32 m0, s55
	s_nop 0
	global_load_lds_dwordx4 v[222:223], off
	s_mov_b32 m0, s56
	s_nop 0
	global_load_lds_dwordx4 v[224:225], off
	s_waitcnt vmcnt(24)
	s_waitcnt lgkmcnt(0)
	s_barrier
	s_setprio 1
	s_waitcnt lgkmcnt(0)
	v_mfma_f32_16x16x32_bf16 v[62:65], v[154:157], v[190:193], 0
	v_mfma_f32_16x16x32_bf16 v[58:61], v[162:165], v[190:193], 0
	v_mfma_f32_16x16x32_bf16 v[46:49], v[154:157], v[198:201], 0
	v_mfma_f32_16x16x32_bf16 v[42:45], v[162:165], v[198:201], 0
	v_mfma_f32_16x16x32_bf16 v[30:33], v[154:157], v[206:209], 0
	v_mfma_f32_16x16x32_bf16 v[26:29], v[162:165], v[206:209], 0
	v_mfma_f32_16x16x32_bf16 v[14:17], v[154:157], v[214:217], 0
	v_mfma_f32_16x16x32_bf16 v[10:13], v[162:165], v[214:217], 0
	v_mfma_f32_16x16x32_bf16 v[62:65], v[158:161], v[194:197], v[62:65]
	v_mfma_f32_16x16x32_bf16 v[58:61], v[166:169], v[194:197], v[58:61]
	v_mfma_f32_16x16x32_bf16 v[46:49], v[158:161], v[202:205], v[46:49]
	v_mfma_f32_16x16x32_bf16 v[42:45], v[166:169], v[202:205], v[42:45]
	v_mfma_f32_16x16x32_bf16 v[30:33], v[158:161], v[210:213], v[30:33]
	v_mfma_f32_16x16x32_bf16 v[26:29], v[166:169], v[210:213], v[26:29]
	v_mfma_f32_16x16x32_bf16 v[14:17], v[158:161], v[218:221], v[14:17]
	v_mfma_f32_16x16x32_bf16 v[10:13], v[166:169], v[218:221], v[10:13]
	s_setprio 0
	s_setprio 1
	v_mfma_f32_16x16x32_bf16 v[54:57], v[174:177], v[190:193], 0
	v_mfma_f32_16x16x32_bf16 v[50:53], v[182:185], v[190:193], 0
	v_mfma_f32_16x16x32_bf16 v[38:41], v[174:177], v[198:201], 0
	v_mfma_f32_16x16x32_bf16 v[34:37], v[182:185], v[198:201], 0
	v_mfma_f32_16x16x32_bf16 v[22:25], v[174:177], v[206:209], 0
	v_mfma_f32_16x16x32_bf16 v[18:21], v[182:185], v[206:209], 0
	v_mfma_f32_16x16x32_bf16 v[6:9], v[174:177], v[214:217], 0
	v_mfma_f32_16x16x32_bf16 v[2:5], v[182:185], v[214:217], 0
	v_mfma_f32_16x16x32_bf16 v[54:57], v[178:181], v[194:197], v[54:57]
	v_mfma_f32_16x16x32_bf16 v[50:53], v[186:189], v[194:197], v[50:53]
	v_mfma_f32_16x16x32_bf16 v[38:41], v[178:181], v[202:205], v[38:41]
	v_mfma_f32_16x16x32_bf16 v[34:37], v[186:189], v[202:205], v[34:37]
	v_mfma_f32_16x16x32_bf16 v[22:25], v[178:181], v[210:213], v[22:25]
	v_mfma_f32_16x16x32_bf16 v[18:21], v[186:189], v[210:213], v[18:21]
	v_mfma_f32_16x16x32_bf16 v[6:9], v[178:181], v[218:221], v[6:9]
	v_mfma_f32_16x16x32_bf16 v[2:5], v[186:189], v[218:221], v[2:5]
	s_setprio 0
	s_barrier

; #define PG8_STAGE(bufoff, gbase, voff) do { _Pragma("unroll") for (int _i = 0; _i < 2; ++_i) \
;         __builtin_amdgcn_global_load_lds((const unsigned*)((const char*)(gbase) + (voff)[_i]), (PG8_LAS unsigned*)(lds + (bufoff) + ldsw + _i * 8192), 16, 0, 0); } while (0)
; #define PG8_LDA(dst, b, h) do { _Pragma("unroll") for (int m = 0; m < 4; ++m) _Pragma("unroll") for (int k = 0; k < 2; ++k) dst[m][k] = *(const PG8_LAS bf16x8*)(lds + PG8_SA(b, h) + aoff + m * 2048 + k * 1024); } while (0)
; #define PG8_LDB(dst, b, h) do { _Pragma("unroll") for (int n = 0; n < 2; ++n) _Pragma("unroll") for (int k = 0; k < 2; ++k) dst[n][k] = *(const PG8_LAS bf16x8*)(lds + PG8_SB(b, h) + boff + n * 2048 + k * 1024); } while (0)
; #define PG8_SCHED __builtin_amdgcn_sched_barrier(0)
; template <class Epi, class Sched, bool ALIGN_EPI = false, bool SP2 = false>
; __device__ __forceinline__ void gemm_phase(PG8_LAS unsigned char* lds, const Gemm g, const Sched& S, const Epi& E) {
;     ...
;             PG8_LDB(B0, 1, 0); PG8_LDB(B1, 1, 1); PG8_SCHED; PG8_LDA(At, 1, 0); PG8_STAGE(PG8_SA(0, 1), a2 + hstep, voffA);
	s_add_i32 s72, 0, 0x18000
	v_add_u32_e32 v153, s72, v148
	s_add_i32 s73, 0, 0x1c000
	ds_read_b128 v[154:157], v153
	ds_read_b128 v[158:161], v153 offset:1024
	ds_read_b128 v[162:165], v153 offset:2048
	ds_read_b128 v[166:169], v153 offset:3072
	v_add_u32_e32 v153, s73, v148
	ds_read_b128 v[174:177], v153
	ds_read_b128 v[178:181], v153 offset:1024
	ds_read_b128 v[182:185], v153 offset:2048
	ds_read_b128 v[186:189], v153 offset:3072

; #define PG8_STAGE(bufoff, gbase, voff) do { _Pragma("unroll") for (int _i = 0; _i < 2; ++_i) \
;         __builtin_amdgcn_global_load_lds((const unsigned*)((const char*)(gbase) + (voff)[_i]), (PG8_LAS unsigned*)(lds + (bufoff) + ldsw + _i * 8192), 16, 0, 0); } while (0)
; #define PG8_LDA(dst, b, h) do { _Pragma("unroll") for (int m = 0; m < 4; ++m) _Pragma("unroll") for (int k = 0; k < 2; ++k) dst[m][k] = *(const PG8_LAS bf16x8*)(lds + PG8_SA(b, h) + aoff + m * 2048 + k * 1024); } while (0)
; #define PG8_LDB(dst, b, h) do { _Pragma("unroll") for (int n = 0; n < 2; ++n) _Pragma("unroll") for (int k = 0; k < 2; ++k) dst[n][k] = *(const PG8_LAS bf16x8*)(lds + PG8_SB(b, h) + boff + n * 2048 + k * 1024); } while (0)
; #define PG8_MMA(ai, bj, At, Bt) do { __builtin_amdgcn_s_setprio(1); _Pragma("unroll") for (int m = 0; m < 4; ++m) _Pragma("unroll") for (int n = 0; n < 2; ++n) _Pragma("unroll") for (int k = 0; k < 2; ++k) \
;         acc[ai][bj][m][n] = __builtin_amdgcn_mfma_f32_16x16x32_bf16(Bt[n][k], At[m][k], acc[ai][bj][m][n], 0, 0, 0); __builtin_amdgcn_s_setprio(0); } while (0)
; #define PG8_WAIT_V(n) asm volatile("s_waitcnt vmcnt(" #n ")" ::: "memory")
; #define PG8_WAIT_L(n) asm volatile("s_waitcnt lgkmcnt(" #n ")" ::: "memory")
; #define PG8_BAR __builtin_amdgcn_s_barrier()
; #define PG8_SCHED __builtin_amdgcn_sched_barrier(0)
; template <class Epi, class Sched, bool ALIGN_EPI = false, bool SP2 = false>
; __device__ __forceinline__ void gemm_phase(PG8_LAS unsigned char* lds, const Gemm g, const Sched& S, const Epi& E) {
;     ...
;             PG8_LDB(B0, 1, 0); PG8_LDB(B1, 1, 1); PG8_SCHED; PG8_LDA(At, 1, 0); PG8_STAGE(PG8_SA(0, 1), a2 + hstep, voffA);
;             PG8_WAIT_V(8); PG8_WAIT_L(0); PG8_BAR; PG8_MMA(0, 0, At, B0); PG8_MMA(0, 1, At, B1); PG8_BAR; PG8_SCHED;
	s_add_u32 s42, s42, 0x40000
	s_addc_u32 s43, s43, 0
	s_mov_b32 m0, s57
	v_lshl_add_u64 v[226:227], s[42:43], 0, v[130:131]
	ds_read_b128 v[190:193], v152 offset:32768
	ds_read_b128 v[194:197], v152 offset:33792
	ds_read_b128 v[198:201], v152 offset:34816
	ds_read_b128 v[202:205], v152 offset:35840
	ds_read_b128 v[206:209], v152 offset:36864
	ds_read_b128 v[210:213], v152 offset:37888
	ds_read_b128 v[214:217], v152 offset:38912
	ds_read_b128 v[218:221], v152 offset:39936
	global_load_lds_dwordx4 v[226:227], off
	v_lshl_add_u64 v[226:227], s[42:43], 0, v[134:135]
	s_mov_b32 m0, s58
	s_nop 0
	global_load_lds_dwordx4 v[226:227], off
	s_waitcnt vmcnt(8)
	s_waitcnt lgkmcnt(0)
	s_barrier
	s_setprio 1
	s_waitcnt lgkmcnt(0)
	v_mfma_f32_16x16x32_bf16 v[126:129], v[154:157], v[190:193], v[126:129]
	v_mfma_f32_16x16x32_bf16 v[122:125], v[162:165], v[190:193], v[122:125]
	v_mfma_f32_16x16x32_bf16 v[110:113], v[154:157], v[198:201], v[110:113]
	v_mfma_f32_16x16x32_bf16 v[106:109], v[162:165], v[198:201], v[106:109]
	v_mfma_f32_16x16x32_bf16 v[94:97], v[154:157], v[206:209], v[94:97]
	v_mfma_f32_16x16x32_bf16 v[90:93], v[162:165], v[206:209], v[90:93]
	v_mfma_f32_16x16x32_bf16 v[78:81], v[154:157], v[214:217], v[78:81]
	v_mfma_f32_16x16x32_bf16 v[74:77], v[162:165], v[214:217], v[74:77]
	v_mfma_f32_16x16x32_bf16 v[126:129], v[158:161], v[194:197], v[126:129]
	v_mfma_f32_16x16x32_bf16 v[122:125], v[166:169], v[194:197], v[122:125]
	v_mfma_f32_16x16x32_bf16 v[110:113], v[158:161], v[202:205], v[110:113]
	v_mfma_f32_16x16x32_bf16 v[106:109], v[166:169], v[202:205], v[106:109]
	v_mfma_f32_16x16x32_bf16 v[94:97], v[158:161], v[210:213], v[94:97]
	v_mfma_f32_16x16x32_bf16 v[90:93], v[166:169], v[210:213], v[90:93]
	v_mfma_f32_16x16x32_bf16 v[78:81], v[158:161], v[218:221], v[78:81]
	v_mfma_f32_16x16x32_bf16 v[74:77], v[166:169], v[218:221], v[74:77]
	s_setprio 0
	s_setprio 1
	v_mfma_f32_16x16x32_bf16 v[118:121], v[174:177], v[190:193], v[118:121]
	v_mfma_f32_16x16x32_bf16 v[114:117], v[182:185], v[190:193], v[114:117]
	v_mfma_f32_16x16x32_bf16 v[102:105], v[174:177], v[198:201], v[102:105]
	v_mfma_f32_16x16x32_bf16 v[98:101], v[182:185], v[198:201], v[98:101]
	v_mfma_f32_16x16x32_bf16 v[86:89], v[174:177], v[206:209], v[86:89]
	v_mfma_f32_16x16x32_bf16 v[82:85], v[182:185], v[206:209], v[82:85]
	v_mfma_f32_16x16x32_bf16 v[70:73], v[174:177], v[214:217], v[70:73]
	v_mfma_f32_16x16x32_bf16 v[66:69], v[182:185], v[214:217], v[66:69]
	v_mfma_f32_16x16x32_bf16 v[118:121], v[178:181], v[194:197], v[118:121]
	v_mfma_f32_16x16x32_bf16 v[114:117], v[186:189], v[194:197], v[114:117]
	v_mfma_f32_16x16x32_bf16 v[102:105], v[178:181], v[202:205], v[102:105]
	v_mfma_f32_16x16x32_bf16 v[98:101], v[186:189], v[202:205], v[98:101]
	v_mfma_f32_16x16x32_bf16 v[86:89], v[178:181], v[210:213], v[86:89]
	v_mfma_f32_16x16x32_bf16 v[82:85], v[186:189], v[210:213], v[82:85]
	v_mfma_f32_16x16x32_bf16 v[70:73], v[178:181], v[218:221], v[70:73]
	v_mfma_f32_16x16x32_bf16 v[66:69], v[186:189], v[218:221], v[66:69]
	s_setprio 0
	s_barrier

; #define PG8_STAGE(bufoff, gbase, voff) do { _Pragma("unroll") for (int _i = 0; _i < 2; ++_i) \
;         __builtin_amdgcn_global_load_lds((const unsigned*)((const char*)(gbase) + (voff)[_i]), (PG8_LAS unsigned*)(lds + (bufoff) + ldsw + _i * 8192), 16, 0, 0); } while (0)
; #define PG8_LDA(dst, b, h) do { _Pragma("unroll") for (int m = 0; m < 4; ++m) _Pragma("unroll") for (int k = 0; k < 2; ++k) dst[m][k] = *(const PG8_LAS bf16x8*)(lds + PG8_SA(b, h) + aoff + m * 2048 + k * 1024); } while (0)
; #define PG8_MMA(ai, bj, At, Bt) do { __builtin_amdgcn_s_setprio(1); _Pragma("unroll") for (int m = 0; m < 4; ++m) _Pragma("unroll") for (int n = 0; n < 2; ++n) _Pragma("unroll") for (int k = 0; k < 2; ++k) \
;         acc[ai][bj][m][n] = __builtin_amdgcn_mfma_f32_16x16x32_bf16(Bt[n][k], At[m][k], acc[ai][bj][m][n], 0, 0, 0); __builtin_amdgcn_s_setprio(0); } while (0)
; #define PG8_WAIT_V(n) asm volatile("s_waitcnt vmcnt(" #n ")" ::: "memory")
; #define PG8_WAIT_L(n) asm volatile("s_waitcnt lgkmcnt(" #n ")" ::: "memory")
; #define PG8_BAR __builtin_amdgcn_s_barrier()
; #define PG8_SCHED __builtin_amdgcn_sched_barrier(0)
; template <class Epi, class Sched, bool ALIGN_EPI = false, bool SP2 = false>
; __device__ __forceinline__ void gemm_phase(PG8_LAS unsigned char* lds, const Gemm g, const Sched& S, const Epi& E) {
;     ...
;             PG8_LDA(At, 1, 1); PG8_STAGE(PG8_SB(1, 0), b3, voffB); PG8_STAGE(PG8_SB(1, 1), b3 + hstep, voffB); PG8_STAGE(PG8_SA(1, 0), a3, voffA);
;             PG8_WAIT_V(8); PG8_WAIT_L(0); PG8_BAR; PG8_MMA(1, 0, At, B0); PG8_MMA(1, 1, At, B1); PG8_BAR; PG8_SCHED;
	s_add_i32 s42, s72, s54
	v_lshl_add_u64 v[146:147], v[146:147], 0, s[10:11]
	s_mov_b32 m0, s42
	ds_read_b128 v[190:193], v152 offset:49152
	ds_read_b128 v[194:197], v152 offset:50176
	ds_read_b128 v[198:201], v152 offset:51200
	ds_read_b128 v[202:205], v152 offset:52224
	ds_read_b128 v[206:209], v152 offset:53248
	ds_read_b128 v[210:213], v152 offset:54272
	ds_read_b128 v[214:217], v152 offset:55296
	ds_read_b128 v[218:221], v152 offset:56320
	global_load_lds_dwordx4 v[146:147], off
	s_add_i32 m0, s42, 0x2000
	s_add_u32 s40, s40, 0x40080
	v_lshl_add_u64 v[146:147], v[170:171], 0, s[10:11]
	s_addc_u32 s41, s41, 0
	s_add_i32 s42, s73, s54
	global_load_lds_dwordx4 v[146:147], off
	v_lshl_add_u64 v[146:147], s[40:41], 0, v[132:133]
	s_mov_b32 m0, s42
	s_nop 0
	global_load_lds_dwordx4 v[146:147], off
	v_lshl_add_u64 v[146:147], s[40:41], 0, v[136:137]
	s_add_i32 m0, s42, 0x2000
	s_nop 0
	global_load_lds_dwordx4 v[146:147], off
	v_lshl_add_u64 v[146:147], v[222:223], 0, s[10:11]
	s_mov_b32 m0, s60
	s_nop 0
	global_load_lds_dwordx4 v[146:147], off
	v_lshl_add_u64 v[146:147], v[224:225], 0, s[10:11]
	s_mov_b32 m0, s61
	s_nop 0
	global_load_lds_dwordx4 v[146:147], off
	s_waitcnt vmcnt(8)
	s_waitcnt lgkmcnt(0)
	s_barrier
	s_setprio 1
	s_waitcnt lgkmcnt(0)
	v_mfma_f32_16x16x32_bf16 v[62:65], v[154:157], v[190:193], v[62:65]
	v_mfma_f32_16x16x32_bf16 v[58:61], v[162:165], v[190:193], v[58:61]
	v_mfma_f32_16x16x32_bf16 v[46:49], v[154:157], v[198:201], v[46:49]
	v_mfma_f32_16x16x32_bf16 v[42:45], v[162:165], v[198:201], v[42:45]
	v_mfma_f32_16x16x32_bf16 v[30:33], v[154:157], v[206:209], v[30:33]
	v_mfma_f32_16x16x32_bf16 v[26:29], v[162:165], v[206:209], v[26:29]
	v_mfma_f32_16x16x32_bf16 v[14:17], v[154:157], v[214:217], v[14:17]
	v_mfma_f32_16x16x32_bf16 v[10:13], v[162:165], v[214:217], v[10:13]
	v_mfma_f32_16x16x32_bf16 v[62:65], v[158:161], v[194:197], v[62:65]
	v_mfma_f32_16x16x32_bf16 v[58:61], v[166:169], v[194:197], v[58:61]
	v_mfma_f32_16x16x32_bf16 v[46:49], v[158:161], v[202:205], v[46:49]
	v_mfma_f32_16x16x32_bf16 v[42:45], v[166:169], v[202:205], v[42:45]
	v_mfma_f32_16x16x32_bf16 v[30:33], v[158:161], v[210:213], v[30:33]
	v_mfma_f32_16x16x32_bf16 v[26:29], v[166:169], v[210:213], v[26:29]
	v_mfma_f32_16x16x32_bf16 v[14:17], v[158:161], v[218:221], v[14:17]
	v_mfma_f32_16x16x32_bf16 v[10:13], v[166:169], v[218:221], v[10:13]
	s_setprio 0
	s_setprio 1
	v_mfma_f32_16x16x32_bf16 v[54:57], v[174:177], v[190:193], v[54:57]
	v_mfma_f32_16x16x32_bf16 v[50:53], v[182:185], v[190:193], v[50:53]
	v_mfma_f32_16x16x32_bf16 v[38:41], v[174:177], v[198:201], v[38:41]
	v_mfma_f32_16x16x32_bf16 v[34:37], v[182:185], v[198:201], v[34:37]
	v_mfma_f32_16x16x32_bf16 v[22:25], v[174:177], v[206:209], v[22:25]
	v_mfma_f32_16x16x32_bf16 v[18:21], v[182:185], v[206:209], v[18:21]
	v_mfma_f32_16x16x32_bf16 v[6:9], v[174:177], v[214:217], v[6:9]
	v_mfma_f32_16x16x32_bf16 v[2:5], v[182:185], v[214:217], v[2:5]
	v_mfma_f32_16x16x32_bf16 v[54:57], v[178:181], v[194:197], v[54:57]
	v_mfma_f32_16x16x32_bf16 v[50:53], v[186:189], v[194:197], v[50:53]
	v_mfma_f32_16x16x32_bf16 v[38:41], v[178:181], v[202:205], v[38:41]
	v_mfma_f32_16x16x32_bf16 v[34:37], v[186:189], v[202:205], v[34:37]
	v_mfma_f32_16x16x32_bf16 v[22:25], v[178:181], v[210:213], v[22:25]
	v_mfma_f32_16x16x32_bf16 v[18:21], v[186:189], v[210:213], v[18:21]
	v_mfma_f32_16x16x32_bf16 v[6:9], v[178:181], v[218:221], v[6:9]
	v_mfma_f32_16x16x32_bf16 v[2:5], v[186:189], v[218:221], v[2:5]
	s_setprio 0
	s_barrier

; template <class Epi, class Sched, bool ALIGN_EPI = false, bool SP2 = false>
; __device__ __forceinline__ void gemm_phase(PG8_LAS unsigned char* lds, const Gemm g, const Sched& S, const Epi& E) {
;     ...
;         for (int t = 0; t < nt; t += 2) {
;             const bool last = (t == nt - 2);
;             const char* a1 = cA + (size_t)(t + 1) * kstep;
;             const char* a2 = last ? nA : cA + (size_t)(t + 2) * kstep; const char* b2 = last ? nB : cB + (size_t)(t + 2) * kstep;
;             const char* a3 = a2 + kstep; const char* b3 = b2 + kstep;
	s_add_i32 s71, s71, 2
	s_add_u32 s38, s38, 0x100
	s_addc_u32 s39, s39, 0
	s_add_u32 s69, s69, 0x100
	s_addc_u32 s70, s70, 0

; #define PG8_STAGE(bufoff, gbase, voff) do { _Pragma("unroll") for (int _i = 0; _i < 2; ++_i) \
;         __builtin_amdgcn_global_load_lds((const unsigned*)((const char*)(gbase) + (voff)[_i]), (PG8_LAS unsigned*)(lds + (bufoff) + ldsw + _i * 8192), 16, 0, 0); } while (0)
; #define PG8_LDA(dst, b, h) do { _Pragma("unroll") for (int m = 0; m < 4; ++m) _Pragma("unroll") for (int k = 0; k < 2; ++k) dst[m][k] = *(const PG8_LAS bf16x8*)(lds + PG8_SA(b, h) + aoff + m * 2048 + k * 1024); } while (0)
; #define PG8_LDB(dst, b, h) do { _Pragma("unroll") for (int n = 0; n < 2; ++n) _Pragma("unroll") for (int k = 0; k < 2; ++k) dst[n][k] = *(const PG8_LAS bf16x8*)(lds + PG8_SB(b, h) + boff + n * 2048 + k * 1024); } while (0)
; #define PG8_SCHED __builtin_amdgcn_sched_barrier(0)
; template <class Epi, class Sched, bool ALIGN_EPI = false, bool SP2 = false>
; __device__ __forceinline__ void gemm_phase(PG8_LAS unsigned char* lds, const Gemm g, const Sched& S, const Epi& E) {
;     ...
;         const bool has_next = S.next(ui + 1, nxt);
;         const char* nA = has_next ? (const char*)g.A + (size_t)nxt.pm * tstep : cA; const char* nB = has_next ? (const char*)g.Bt + (size_t)nxt.pn * tstep : cB;
; #pragma nounroll
;         for (int t = 0; t < nt; t += 2) {
;             const bool last = (t == nt - 2);
;             const char* a1 = cA + (size_t)(t + 1) * kstep;
;             const char* a2 = last ? nA : cA + (size_t)(t + 2) * kstep; const char* b2 = last ? nB : cB + (size_t)(t + 2) * kstep;
;             const char* a3 = a2 + kstep; const char* b3 = b2 + kstep;
;             if (last && has_next) S.a_ready(nxt);
;             if constexpr (SP2) {
;             PG8_LDB(B0, 0, 0); PG8_LDB(B1, 0, 1); PG8_SCHED; PG8_LDA(At, 0, 0); PG8_STAGE(PG8_SA(1, 1), a1 + hstep, voffA);
;     ...
; #pragma unroll
;         for (int a = 0; a < 2; ++a)
; #pragma unroll
;             for (int b = 0; b < 2; ++b)
; #pragma unroll
;                 for (int m = 0; m < 4; ++m)
; #pragma unroll
;                     for (int n = 0; n < 2; ++n) acc[a][b][m][n] = (f32x4){0.f, 0.f, 0.f, 0.f};
;         cur = nxt; cA = nA; cB = nB; ++ui;
.LBB0_1431:
	s_ashr_i32 s21, s20, 31
	s_lshl_b64 s[22:23], s[20:21], 19
	s_add_u32 s22, s38, s22
	s_addc_u32 s23, s39, s23
	s_and_b64 s[24:25], s[2:3], exec
	s_cselect_b32 s21, s23, s29
	s_cselect_b32 s64, s22, s28
	s_ashr_i32 s19, s18, 31
	s_lshl_b64 s[24:25], s[18:19], 19
	s_add_u32 s24, s40, s24
	s_addc_u32 s25, s41, s25
	s_and_b64 s[34:35], s[2:3], exec
	s_cselect_b32 s19, s25, s31
	s_cselect_b32 s65, s24, s30
	s_add_u32 s28, s28, 0x40080
	s_addc_u32 s29, s29, 0
	s_add_u32 s66, s30, 0x100
	s_addc_u32 s67, s31, 0
	s_mov_b32 s68, -2
	ds_read_b128 v[154:157], v150
	ds_read_b128 v[158:161], v150 offset:1024
	ds_read_b128 v[162:165], v150 offset:2048
	ds_read_b128 v[166:169], v150 offset:3072
	ds_read_b128 v[174:177], v151
	ds_read_b128 v[178:181], v151 offset:1024
	ds_read_b128 v[182:185], v151 offset:2048
	ds_read_b128 v[186:189], v151 offset:3072
	s_add_u32 s30, s28, 0xfffc0080
	s_addc_u32 s31, s29, -1
	s_cmp_eq_u32 s68, 12
	s_cselect_b32 s35, s21, s31
	s_cselect_b32 s34, s64, s30
	s_cselect_b32 s31, s19, s67
	s_cselect_b32 s30, s65, s66

; #define PG8_STAGE(bufoff, gbase, voff) do { _Pragma("unroll") for (int _i = 0; _i < 2; ++_i) \
;         __builtin_amdgcn_global_load_lds((const unsigned*)((const char*)(gbase) + (voff)[_i]), (PG8_LAS unsigned*)(lds + (bufoff) + ldsw + _i * 8192), 16, 0, 0); } while (0)
; #define PG8_LDA(dst, b, h) do { _Pragma("unroll") for (int m = 0; m < 4; ++m) _Pragma("unroll") for (int k = 0; k < 2; ++k) dst[m][k] = *(const PG8_LAS bf16x8*)(lds + PG8_SA(b, h) + aoff + m * 2048 + k * 1024); } while (0)
; #define PG8_LDB(dst, b, h) do { _Pragma("unroll") for (int n = 0; n < 2; ++n) _Pragma("unroll") for (int k = 0; k < 2; ++k) dst[n][k] = *(const PG8_LAS bf16x8*)(lds + PG8_SB(b, h) + boff + n * 2048 + k * 1024); } while (0)
; #define PG8_MMA(ai, bj, At, Bt) do { __builtin_amdgcn_s_setprio(1); _Pragma("unroll") for (int m = 0; m < 4; ++m) _Pragma("unroll") for (int n = 0; n < 2; ++n) _Pragma("unroll") for (int k = 0; k < 2; ++k) \
;         acc[ai][bj][m][n] = __builtin_amdgcn_mfma_f32_16x16x32_bf16(Bt[n][k], At[m][k], acc[ai][bj][m][n], 0, 0, 0); __builtin_amdgcn_s_setprio(0); } while (0)
; #define PG8_WAIT_V(n) asm volatile("s_waitcnt vmcnt(" #n ")" ::: "memory")
; #define PG8_WAIT_L(n) asm volatile("s_waitcnt lgkmcnt(" #n ")" ::: "memory")
; #define PG8_BAR __builtin_amdgcn_s_barrier()
; #define PG8_SCHED __builtin_amdgcn_sched_barrier(0)
; template <class Epi, class Sched, bool ALIGN_EPI = false, bool SP2 = false>
; __device__ __forceinline__ void gemm_phase(PG8_LAS unsigned char* lds, const Gemm g, const Sched& S, const Epi& E) {
;     ...
;             PG8_LDB(B0, 0, 0); PG8_LDB(B1, 0, 1); PG8_SCHED; PG8_LDA(At, 0, 0); PG8_STAGE(PG8_SA(1, 1), a1 + hstep, voffA);
;             PG8_WAIT_V(8); PG8_WAIT_L(0); PG8_BAR; PG8_MMA(0, 0, At, B0); PG8_MMA(0, 1, At, B1); PG8_BAR; PG8_SCHED;
	v_lshl_add_u64 v[146:147], s[28:29], 0, v[138:139]
	s_add_i32 m0, s27, 0xc000
	ds_read_b128 v[190:193], v152
	ds_read_b128 v[194:197], v152 offset:1024
	ds_read_b128 v[198:201], v152 offset:2048
	ds_read_b128 v[202:205], v152 offset:3072
	ds_read_b128 v[206:209], v152 offset:4096
	ds_read_b128 v[210:213], v152 offset:5120
	ds_read_b128 v[214:217], v152 offset:6144
	ds_read_b128 v[218:221], v152 offset:7168
	global_load_lds_dwordx4 v[146:147], off
	v_lshl_add_u64 v[146:147], s[28:29], 0, v[140:141]
	s_add_i32 m0, s27, 0xe000
	s_nop 0
	global_load_lds_dwordx4 v[146:147], off
	s_waitcnt vmcnt(24)
	s_waitcnt lgkmcnt(0)
	s_barrier
	s_setprio 1
	s_waitcnt lgkmcnt(0)
	v_mfma_f32_16x16x32_bf16 v[126:129], v[154:157], v[190:193], 0
	v_mfma_f32_16x16x32_bf16 v[122:125], v[162:165], v[190:193], 0
	v_mfma_f32_16x16x32_bf16 v[118:121], v[154:157], v[198:201], 0
	v_mfma_f32_16x16x32_bf16 v[110:113], v[162:165], v[198:201], 0
	v_mfma_f32_16x16x32_bf16 v[102:105], v[154:157], v[206:209], 0
	v_mfma_f32_16x16x32_bf16 v[94:97], v[162:165], v[206:209], 0
	v_mfma_f32_16x16x32_bf16 v[86:89], v[154:157], v[214:217], 0
	v_mfma_f32_16x16x32_bf16 v[78:81], v[162:165], v[214:217], 0
	v_mfma_f32_16x16x32_bf16 v[126:129], v[158:161], v[194:197], v[126:129]
	v_mfma_f32_16x16x32_bf16 v[122:125], v[166:169], v[194:197], v[122:125]
	v_mfma_f32_16x16x32_bf16 v[118:121], v[158:161], v[202:205], v[118:121]
	v_mfma_f32_16x16x32_bf16 v[110:113], v[166:169], v[202:205], v[110:113]
	v_mfma_f32_16x16x32_bf16 v[102:105], v[158:161], v[210:213], v[102:105]
	v_mfma_f32_16x16x32_bf16 v[94:97], v[166:169], v[210:213], v[94:97]
	v_mfma_f32_16x16x32_bf16 v[86:89], v[158:161], v[218:221], v[86:89]
	v_mfma_f32_16x16x32_bf16 v[78:81], v[166:169], v[218:221], v[78:81]
	s_setprio 0
	s_setprio 1
	v_mfma_f32_16x16x32_bf16 v[114:117], v[174:177], v[190:193], 0
	v_mfma_f32_16x16x32_bf16 v[106:109], v[182:185], v[190:193], 0
	v_mfma_f32_16x16x32_bf16 v[98:101], v[174:177], v[198:201], 0
	v_mfma_f32_16x16x32_bf16 v[90:93], v[182:185], v[198:201], 0
	v_mfma_f32_16x16x32_bf16 v[82:85], v[174:177], v[206:209], 0
	v_mfma_f32_16x16x32_bf16 v[74:77], v[182:185], v[206:209], 0
	v_mfma_f32_16x16x32_bf16 v[70:73], v[174:177], v[214:217], 0
	v_mfma_f32_16x16x32_bf16 v[66:69], v[182:185], v[214:217], 0
	v_mfma_f32_16x16x32_bf16 v[114:117], v[178:181], v[194:197], v[114:117]
	v_mfma_f32_16x16x32_bf16 v[106:109], v[186:189], v[194:197], v[106:109]
	v_mfma_f32_16x16x32_bf16 v[98:101], v[178:181], v[202:205], v[98:101]
	v_mfma_f32_16x16x32_bf16 v[90:93], v[186:189], v[202:205], v[90:93]
	v_mfma_f32_16x16x32_bf16 v[82:85], v[178:181], v[210:213], v[82:85]
	v_mfma_f32_16x16x32_bf16 v[74:77], v[186:189], v[210:213], v[74:77]
	v_mfma_f32_16x16x32_bf16 v[70:73], v[178:181], v[218:221], v[70:73]
	v_mfma_f32_16x16x32_bf16 v[66:69], v[186:189], v[218:221], v[66:69]
	s_setprio 0
	s_barrier

; #define PG8_STAGE(bufoff, gbase, voff) do { _Pragma("unroll") for (int _i = 0; _i < 2; ++_i) \
;         __builtin_amdgcn_global_load_lds((const unsigned*)((const char*)(gbase) + (voff)[_i]), (PG8_LAS unsigned*)(lds + (bufoff) + ldsw + _i * 8192), 16, 0, 0); } while (0)
; #define PG8_LDA(dst, b, h) do { _Pragma("unroll") for (int m = 0; m < 4; ++m) _Pragma("unroll") for (int k = 0; k < 2; ++k) dst[m][k] = *(const PG8_LAS bf16x8*)(lds + PG8_SA(b, h) + aoff + m * 2048 + k * 1024); } while (0)
; #define PG8_MMA(ai, bj, At, Bt) do { __builtin_amdgcn_s_setprio(1); _Pragma("unroll") for (int m = 0; m < 4; ++m) _Pragma("unroll") for (int n = 0; n < 2; ++n) _Pragma("unroll") for (int k = 0; k < 2; ++k) \
;         acc[ai][bj][m][n] = __builtin_amdgcn_mfma_f32_16x16x32_bf16(Bt[n][k], At[m][k], acc[ai][bj][m][n], 0, 0, 0); __builtin_amdgcn_s_setprio(0); } while (0)
; #define PG8_WAIT_V(n) asm volatile("s_waitcnt vmcnt(" #n ")" ::: "memory")
; #define PG8_WAIT_L(n) asm volatile("s_waitcnt lgkmcnt(" #n ")" ::: "memory")
; #define PG8_BAR __builtin_amdgcn_s_barrier()
; #define PG8_SCHED __builtin_amdgcn_sched_barrier(0)
; template <class Epi, class Sched, bool ALIGN_EPI = false, bool SP2 = false>
; __device__ __forceinline__ void gemm_phase(PG8_LAS unsigned char* lds, const Gemm g, const Sched& S, const Epi& E) {
;     ...
;             PG8_LDA(At, 0, 1); PG8_STAGE(PG8_SB(0, 0), b2, voffB); PG8_STAGE(PG8_SB(0, 1), b2 + hstep, voffB); PG8_STAGE(PG8_SA(0, 0), a2, voffA);
;             PG8_WAIT_V(8); PG8_WAIT_L(0); PG8_BAR; PG8_MMA(1, 0, At, B0); PG8_MMA(1, 1, At, B1); PG8_BAR; PG8_SCHED;
	s_add_i32 s69, s57, s42
	v_lshl_add_u64 v[146:147], s[30:31], 0, v[132:133]
	s_mov_b32 m0, s69
	ds_read_b128 v[190:193], v152 offset:16384
	ds_read_b128 v[194:197], v152 offset:17408
	ds_read_b128 v[198:201], v152 offset:18432
	ds_read_b128 v[202:205], v152 offset:19456
	ds_read_b128 v[206:209], v152 offset:20480
	ds_read_b128 v[210:213], v152 offset:21504
	ds_read_b128 v[214:217], v152 offset:22528
	ds_read_b128 v[218:221], v152 offset:23552
	global_load_lds_dwordx4 v[146:147], off
	s_add_i32 m0, s69, 0x2000
	s_add_u32 s70, s30, 0x40000
	v_lshl_add_u64 v[170:171], s[30:31], 0, v[136:137]
	s_addc_u32 s71, s31, 0
	s_add_i32 s69, s58, s42
	global_load_lds_dwordx4 v[170:171], off
	v_lshl_add_u64 v[222:223], s[70:71], 0, v[132:133]
	s_mov_b32 m0, s69
	v_lshl_add_u64 v[224:225], s[34:35], 0, v[134:135]
	global_load_lds_dwordx4 v[222:223], off
	v_lshl_add_u64 v[222:223], s[70:71], 0, v[136:137]
	s_add_i32 m0, s69, 0x2000
	s_nop 0
	global_load_lds_dwordx4 v[222:223], off
	v_lshl_add_u64 v[222:223], s[34:35], 0, v[130:131]
	s_mov_b32 m0, s27
	s_nop 0
	global_load_lds_dwordx4 v[222:223], off
	s_mov_b32 m0, s43
	s_nop 0
	global_load_lds_dwordx4 v[224:225], off
	s_waitcnt vmcnt(24)
	s_waitcnt lgkmcnt(0)
	s_barrier
	s_setprio 1
	s_waitcnt lgkmcnt(0)
	v_mfma_f32_16x16x32_bf16 v[62:65], v[154:157], v[190:193], 0
	v_mfma_f32_16x16x32_bf16 v[58:61], v[162:165], v[190:193], 0
	v_mfma_f32_16x16x32_bf16 v[54:57], v[154:157], v[198:201], 0
	v_mfma_f32_16x16x32_bf16 v[46:49], v[162:165], v[198:201], 0
	v_mfma_f32_16x16x32_bf16 v[38:41], v[154:157], v[206:209], 0
	v_mfma_f32_16x16x32_bf16 v[30:33], v[162:165], v[206:209], 0
	v_mfma_f32_16x16x32_bf16 v[22:25], v[154:157], v[214:217], 0
	v_mfma_f32_16x16x32_bf16 v[14:17], v[162:165], v[214:217], 0
	v_mfma_f32_16x16x32_bf16 v[62:65], v[158:161], v[194:197], v[62:65]
	v_mfma_f32_16x16x32_bf16 v[58:61], v[166:169], v[194:197], v[58:61]
	v_mfma_f32_16x16x32_bf16 v[54:57], v[158:161], v[202:205], v[54:57]
	v_mfma_f32_16x16x32_bf16 v[46:49], v[166:169], v[202:205], v[46:49]
	v_mfma_f32_16x16x32_bf16 v[38:41], v[158:161], v[210:213], v[38:41]
	v_mfma_f32_16x16x32_bf16 v[30:33], v[166:169], v[210:213], v[30:33]
	v_mfma_f32_16x16x32_bf16 v[22:25], v[158:161], v[218:221], v[22:25]
	v_mfma_f32_16x16x32_bf16 v[14:17], v[166:169], v[218:221], v[14:17]
	s_setprio 0
	s_setprio 1
	v_mfma_f32_16x16x32_bf16 v[50:53], v[174:177], v[190:193], 0
	v_mfma_f32_16x16x32_bf16 v[42:45], v[182:185], v[190:193], 0
	v_mfma_f32_16x16x32_bf16 v[34:37], v[174:177], v[198:201], 0
	v_mfma_f32_16x16x32_bf16 v[26:29], v[182:185], v[198:201], 0
	v_mfma_f32_16x16x32_bf16 v[18:21], v[174:177], v[206:209], 0
	v_mfma_f32_16x16x32_bf16 v[10:13], v[182:185], v[206:209], 0
	v_mfma_f32_16x16x32_bf16 v[6:9], v[174:177], v[214:217], 0
	v_mfma_f32_16x16x32_bf16 v[2:5], v[182:185], v[214:217], 0
	v_mfma_f32_16x16x32_bf16 v[50:53], v[178:181], v[194:197], v[50:53]
	v_mfma_f32_16x16x32_bf16 v[42:45], v[186:189], v[194:197], v[42:45]
	v_mfma_f32_16x16x32_bf16 v[34:37], v[178:181], v[202:205], v[34:37]
	v_mfma_f32_16x16x32_bf16 v[26:29], v[186:189], v[202:205], v[26:29]
	v_mfma_f32_16x16x32_bf16 v[18:21], v[178:181], v[210:213], v[18:21]
	v_mfma_f32_16x16x32_bf16 v[10:13], v[186:189], v[210:213], v[10:13]
	v_mfma_f32_16x16x32_bf16 v[6:9], v[178:181], v[218:221], v[6:9]
	v_mfma_f32_16x16x32_bf16 v[2:5], v[186:189], v[218:221], v[2:5]
	s_setprio 0
	s_barrier

; #define PG8_STAGE(bufoff, gbase, voff) do { _Pragma("unroll") for (int _i = 0; _i < 2; ++_i) \
;         __builtin_amdgcn_global_load_lds((const unsigned*)((const char*)(gbase) + (voff)[_i]), (PG8_LAS unsigned*)(lds + (bufoff) + ldsw + _i * 8192), 16, 0, 0); } while (0)
; #define PG8_LDA(dst, b, h) do { _Pragma("unroll") for (int m = 0; m < 4; ++m) _Pragma("unroll") for (int k = 0; k < 2; ++k) dst[m][k] = *(const PG8_LAS bf16x8*)(lds + PG8_SA(b, h) + aoff + m * 2048 + k * 1024); } while (0)
; #define PG8_LDB(dst, b, h) do { _Pragma("unroll") for (int n = 0; n < 2; ++n) _Pragma("unroll") for (int k = 0; k < 2; ++k) dst[n][k] = *(const PG8_LAS bf16x8*)(lds + PG8_SB(b, h) + boff + n * 2048 + k * 1024); } while (0)
; #define PG8_SCHED __builtin_amdgcn_sched_barrier(0)
; template <class Epi, class Sched, bool ALIGN_EPI = false, bool SP2 = false>
; __device__ __forceinline__ void gemm_phase(PG8_LAS unsigned char* lds, const Gemm g, const Sched& S, const Epi& E) {
;     ...
;             PG8_LDB(B0, 1, 0); PG8_LDB(B1, 1, 1); PG8_SCHED; PG8_LDA(At, 1, 0); PG8_STAGE(PG8_SA(0, 1), a2 + hstep, voffA);
	s_add_i32 s69, 0, 0x18000
	v_add_u32_e32 v153, s69, v148
	s_add_i32 s70, 0, 0x1c000
	ds_read_b128 v[154:157], v153
	ds_read_b128 v[158:161], v153 offset:1024
	ds_read_b128 v[162:165], v153 offset:2048
	ds_read_b128 v[166:169], v153 offset:3072
	v_add_u32_e32 v153, s70, v148
	ds_read_b128 v[174:177], v153
	ds_read_b128 v[178:181], v153 offset:1024
	ds_read_b128 v[182:185], v153 offset:2048
	ds_read_b128 v[186:189], v153 offset:3072

; #define PG8_STAGE(bufoff, gbase, voff) do { _Pragma("unroll") for (int _i = 0; _i < 2; ++_i) \
;         __builtin_amdgcn_global_load_lds((const unsigned*)((const char*)(gbase) + (voff)[_i]), (PG8_LAS unsigned*)(lds + (bufoff) + ldsw + _i * 8192), 16, 0, 0); } while (0)
; #define PG8_LDA(dst, b, h) do { _Pragma("unroll") for (int m = 0; m < 4; ++m) _Pragma("unroll") for (int k = 0; k < 2; ++k) dst[m][k] = *(const PG8_LAS bf16x8*)(lds + PG8_SA(b, h) + aoff + m * 2048 + k * 1024); } while (0)
; #define PG8_LDB(dst, b, h) do { _Pragma("unroll") for (int n = 0; n < 2; ++n) _Pragma("unroll") for (int k = 0; k < 2; ++k) dst[n][k] = *(const PG8_LAS bf16x8*)(lds + PG8_SB(b, h) + boff + n * 2048 + k * 1024); } while (0)
; #define PG8_MMA(ai, bj, At, Bt) do { __builtin_amdgcn_s_setprio(1); _Pragma("unroll") for (int m = 0; m < 4; ++m) _Pragma("unroll") for (int n = 0; n < 2; ++n) _Pragma("unroll") for (int k = 0; k < 2; ++k) \
;         acc[ai][bj][m][n] = __builtin_amdgcn_mfma_f32_16x16x32_bf16(Bt[n][k], At[m][k], acc[ai][bj][m][n], 0, 0, 0); __builtin_amdgcn_s_setprio(0); } while (0)
; #define PG8_WAIT_V(n) asm volatile("s_waitcnt vmcnt(" #n ")" ::: "memory")
; #define PG8_WAIT_L(n) asm volatile("s_waitcnt lgkmcnt(" #n ")" ::: "memory")
; #define PG8_BAR __builtin_amdgcn_s_barrier()
; #define PG8_SCHED __builtin_amdgcn_sched_barrier(0)
; template <class Epi, class Sched, bool ALIGN_EPI = false, bool SP2 = false>
; __device__ __forceinline__ void gemm_phase(PG8_LAS unsigned char* lds, const Gemm g, const Sched& S, const Epi& E) {
;     ...
;             PG8_LDB(B0, 1, 0); PG8_LDB(B1, 1, 1); PG8_SCHED; PG8_LDA(At, 1, 0); PG8_STAGE(PG8_SA(0, 1), a2 + hstep, voffA);
;             PG8_WAIT_V(8); PG8_WAIT_L(0); PG8_BAR; PG8_MMA(0, 0, At, B0); PG8_MMA(0, 1, At, B1); PG8_BAR; PG8_SCHED;
	s_add_u32 s34, s34, 0x40000
	s_addc_u32 s35, s35, 0
	s_mov_b32 m0, s44
	v_lshl_add_u64 v[226:227], s[34:35], 0, v[130:131]
	ds_read_b128 v[190:193], v152 offset:32768
	ds_read_b128 v[194:197], v152 offset:33792
	ds_read_b128 v[198:201], v152 offset:34816
	ds_read_b128 v[202:205], v152 offset:35840
	ds_read_b128 v[206:209], v152 offset:36864
	ds_read_b128 v[210:213], v152 offset:37888
	ds_read_b128 v[214:217], v152 offset:38912
	ds_read_b128 v[218:221], v152 offset:39936
	global_load_lds_dwordx4 v[226:227], off
	v_lshl_add_u64 v[226:227], s[34:35], 0, v[134:135]
	s_mov_b32 m0, s45
	s_nop 0
	global_load_lds_dwordx4 v[226:227], off
	s_waitcnt vmcnt(8)
	s_waitcnt lgkmcnt(0)
	s_barrier
	s_setprio 1
	s_waitcnt lgkmcnt(0)
	v_mfma_f32_16x16x32_bf16 v[126:129], v[154:157], v[190:193], v[126:129]
	v_mfma_f32_16x16x32_bf16 v[122:125], v[162:165], v[190:193], v[122:125]
	v_mfma_f32_16x16x32_bf16 v[118:121], v[154:157], v[198:201], v[118:121]
	v_mfma_f32_16x16x32_bf16 v[110:113], v[162:165], v[198:201], v[110:113]
	v_mfma_f32_16x16x32_bf16 v[102:105], v[154:157], v[206:209], v[102:105]
	v_mfma_f32_16x16x32_bf16 v[94:97], v[162:165], v[206:209], v[94:97]
	v_mfma_f32_16x16x32_bf16 v[86:89], v[154:157], v[214:217], v[86:89]
	v_mfma_f32_16x16x32_bf16 v[78:81], v[162:165], v[214:217], v[78:81]
	v_mfma_f32_16x16x32_bf16 v[126:129], v[158:161], v[194:197], v[126:129]
	v_mfma_f32_16x16x32_bf16 v[122:125], v[166:169], v[194:197], v[122:125]
	v_mfma_f32_16x16x32_bf16 v[118:121], v[158:161], v[202:205], v[118:121]
	v_mfma_f32_16x16x32_bf16 v[110:113], v[166:169], v[202:205], v[110:113]
	v_mfma_f32_16x16x32_bf16 v[102:105], v[158:161], v[210:213], v[102:105]
	v_mfma_f32_16x16x32_bf16 v[94:97], v[166:169], v[210:213], v[94:97]
	v_mfma_f32_16x16x32_bf16 v[86:89], v[158:161], v[218:221], v[86:89]
	v_mfma_f32_16x16x32_bf16 v[78:81], v[166:169], v[218:221], v[78:81]
	s_setprio 0
	s_setprio 1
	v_mfma_f32_16x16x32_bf16 v[114:117], v[174:177], v[190:193], v[114:117]
	v_mfma_f32_16x16x32_bf16 v[106:109], v[182:185], v[190:193], v[106:109]
	v_mfma_f32_16x16x32_bf16 v[98:101], v[174:177], v[198:201], v[98:101]
	v_mfma_f32_16x16x32_bf16 v[90:93], v[182:185], v[198:201], v[90:93]
	v_mfma_f32_16x16x32_bf16 v[82:85], v[174:177], v[206:209], v[82:85]
	v_mfma_f32_16x16x32_bf16 v[74:77], v[182:185], v[206:209], v[74:77]
	v_mfma_f32_16x16x32_bf16 v[70:73], v[174:177], v[214:217], v[70:73]
	v_mfma_f32_16x16x32_bf16 v[66:69], v[182:185], v[214:217], v[66:69]
	v_mfma_f32_16x16x32_bf16 v[114:117], v[178:181], v[194:197], v[114:117]
	v_mfma_f32_16x16x32_bf16 v[106:109], v[186:189], v[194:197], v[106:109]
	v_mfma_f32_16x16x32_bf16 v[98:101], v[178:181], v[202:205], v[98:101]
	v_mfma_f32_16x16x32_bf16 v[90:93], v[186:189], v[202:205], v[90:93]
	v_mfma_f32_16x16x32_bf16 v[82:85], v[178:181], v[210:213], v[82:85]
	v_mfma_f32_16x16x32_bf16 v[74:77], v[186:189], v[210:213], v[74:77]
	v_mfma_f32_16x16x32_bf16 v[70:73], v[178:181], v[218:221], v[70:73]
	v_mfma_f32_16x16x32_bf16 v[66:69], v[186:189], v[218:221], v[66:69]
	s_setprio 0
	s_barrier

; #define PG8_STAGE(bufoff, gbase, voff) do { _Pragma("unroll") for (int _i = 0; _i < 2; ++_i) \
;         __builtin_amdgcn_global_load_lds((const unsigned*)((const char*)(gbase) + (voff)[_i]), (PG8_LAS unsigned*)(lds + (bufoff) + ldsw + _i * 8192), 16, 0, 0); } while (0)
; #define PG8_LDA(dst, b, h) do { _Pragma("unroll") for (int m = 0; m < 4; ++m) _Pragma("unroll") for (int k = 0; k < 2; ++k) dst[m][k] = *(const PG8_LAS bf16x8*)(lds + PG8_SA(b, h) + aoff + m * 2048 + k * 1024); } while (0)
; #define PG8_MMA(ai, bj, At, Bt) do { __builtin_amdgcn_s_setprio(1); _Pragma("unroll") for (int m = 0; m < 4; ++m) _Pragma("unroll") for (int n = 0; n < 2; ++n) _Pragma("unroll") for (int k = 0; k < 2; ++k) \
;         acc[ai][bj][m][n] = __builtin_amdgcn_mfma_f32_16x16x32_bf16(Bt[n][k], At[m][k], acc[ai][bj][m][n], 0, 0, 0); __builtin_amdgcn_s_setprio(0); } while (0)
; #define PG8_WAIT_V(n) asm volatile("s_waitcnt vmcnt(" #n ")" ::: "memory")
; #define PG8_WAIT_L(n) asm volatile("s_waitcnt lgkmcnt(" #n ")" ::: "memory")
; #define PG8_BAR __builtin_amdgcn_s_barrier()
; #define PG8_SCHED __builtin_amdgcn_sched_barrier(0)
; template <class Epi, class Sched, bool ALIGN_EPI = false, bool SP2 = false>
; __device__ __forceinline__ void gemm_phase(PG8_LAS unsigned char* lds, const Gemm g, const Sched& S, const Epi& E) {
;     ...
;             PG8_LDA(At, 1, 1); PG8_STAGE(PG8_SB(1, 0), b3, voffB); PG8_STAGE(PG8_SB(1, 1), b3 + hstep, voffB); PG8_STAGE(PG8_SA(1, 0), a3, voffA);
;             PG8_WAIT_V(8); PG8_WAIT_L(0); PG8_BAR; PG8_MMA(1, 0, At, B0); PG8_MMA(1, 1, At, B1); PG8_BAR; PG8_SCHED;
	s_add_i32 s34, s69, s42
	v_lshl_add_u64 v[146:147], v[146:147], 0, s[8:9]
	s_mov_b32 m0, s34
	ds_read_b128 v[190:193], v152 offset:49152
	ds_read_b128 v[194:197], v152 offset:50176
	ds_read_b128 v[198:201], v152 offset:51200
	ds_read_b128 v[202:205], v152 offset:52224
	ds_read_b128 v[206:209], v152 offset:53248
	ds_read_b128 v[210:213], v152 offset:54272
	ds_read_b128 v[214:217], v152 offset:55296
	ds_read_b128 v[218:221], v152 offset:56320
	global_load_lds_dwordx4 v[146:147], off
	s_add_i32 m0, s34, 0x2000
	s_add_u32 s30, s30, 0x40080
	v_lshl_add_u64 v[146:147], v[170:171], 0, s[8:9]
	s_addc_u32 s31, s31, 0
	s_add_i32 s34, s70, s42
	global_load_lds_dwordx4 v[146:147], off
	v_lshl_add_u64 v[146:147], s[30:31], 0, v[132:133]
	s_mov_b32 m0, s34
	s_nop 0
	global_load_lds_dwordx4 v[146:147], off
	v_lshl_add_u64 v[146:147], s[30:31], 0, v[136:137]
	s_add_i32 m0, s34, 0x2000
	s_nop 0
	global_load_lds_dwordx4 v[146:147], off
	v_lshl_add_u64 v[146:147], v[222:223], 0, s[8:9]
	s_mov_b32 m0, s53
	s_nop 0
	global_load_lds_dwordx4 v[146:147], off
	v_lshl_add_u64 v[146:147], v[224:225], 0, s[8:9]
	s_mov_b32 m0, s54
	s_nop 0
	global_load_lds_dwordx4 v[146:147], off
	s_waitcnt vmcnt(8)
	s_waitcnt lgkmcnt(0)
	s_barrier
	s_setprio 1
	s_waitcnt lgkmcnt(0)
	v_mfma_f32_16x16x32_bf16 v[62:65], v[154:157], v[190:193], v[62:65]
	v_mfma_f32_16x16x32_bf16 v[58:61], v[162:165], v[190:193], v[58:61]
	v_mfma_f32_16x16x32_bf16 v[54:57], v[154:157], v[198:201], v[54:57]
	v_mfma_f32_16x16x32_bf16 v[46:49], v[162:165], v[198:201], v[46:49]
	v_mfma_f32_16x16x32_bf16 v[38:41], v[154:157], v[206:209], v[38:41]
	v_mfma_f32_16x16x32_bf16 v[30:33], v[162:165], v[206:209], v[30:33]
	v_mfma_f32_16x16x32_bf16 v[22:25], v[154:157], v[214:217], v[22:25]
	v_mfma_f32_16x16x32_bf16 v[14:17], v[162:165], v[214:217], v[14:17]
	v_mfma_f32_16x16x32_bf16 v[62:65], v[158:161], v[194:197], v[62:65]
	v_mfma_f32_16x16x32_bf16 v[58:61], v[166:169], v[194:197], v[58:61]
	v_mfma_f32_16x16x32_bf16 v[54:57], v[158:161], v[202:205], v[54:57]
	v_mfma_f32_16x16x32_bf16 v[46:49], v[166:169], v[202:205], v[46:49]
	v_mfma_f32_16x16x32_bf16 v[38:41], v[158:161], v[210:213], v[38:41]
	v_mfma_f32_16x16x32_bf16 v[30:33], v[166:169], v[210:213], v[30:33]
	v_mfma_f32_16x16x32_bf16 v[22:25], v[158:161], v[218:221], v[22:25]
	v_mfma_f32_16x16x32_bf16 v[14:17], v[166:169], v[218:221], v[14:17]
	s_setprio 0
	s_setprio 1
	v_mfma_f32_16x16x32_bf16 v[50:53], v[174:177], v[190:193], v[50:53]
	v_mfma_f32_16x16x32_bf16 v[42:45], v[182:185], v[190:193], v[42:45]
	v_mfma_f32_16x16x32_bf16 v[34:37], v[174:177], v[198:201], v[34:37]
	v_mfma_f32_16x16x32_bf16 v[26:29], v[182:185], v[198:201], v[26:29]
	v_mfma_f32_16x16x32_bf16 v[18:21], v[174:177], v[206:209], v[18:21]
	v_mfma_f32_16x16x32_bf16 v[10:13], v[182:185], v[206:209], v[10:13]
	v_mfma_f32_16x16x32_bf16 v[6:9], v[174:177], v[214:217], v[6:9]
	v_mfma_f32_16x16x32_bf16 v[2:5], v[182:185], v[214:217], v[2:5]
	v_mfma_f32_16x16x32_bf16 v[50:53], v[178:181], v[194:197], v[50:53]
	v_mfma_f32_16x16x32_bf16 v[42:45], v[186:189], v[194:197], v[42:45]
	v_mfma_f32_16x16x32_bf16 v[34:37], v[178:181], v[202:205], v[34:37]
	v_mfma_f32_16x16x32_bf16 v[26:29], v[186:189], v[202:205], v[26:29]
	v_mfma_f32_16x16x32_bf16 v[18:21], v[178:181], v[210:213], v[18:21]
	v_mfma_f32_16x16x32_bf16 v[10:13], v[186:189], v[210:213], v[10:13]
	v_mfma_f32_16x16x32_bf16 v[6:9], v[178:181], v[218:221], v[6:9]
	v_mfma_f32_16x16x32_bf16 v[2:5], v[186:189], v[218:221], v[2:5]
	s_setprio 0
	s_barrier

; template <class Epi, class Sched, bool ALIGN_EPI = false, bool SP2 = false>
; __device__ __forceinline__ void gemm_phase(PG8_LAS unsigned char* lds, const Gemm g, const Sched& S, const Epi& E) {
;     ...
;         for (int t = 0; t < nt; t += 2) {
;             const bool last = (t == nt - 2);
;             const char* a1 = cA + (size_t)(t + 1) * kstep;
;             const char* a2 = last ? nA : cA + (size_t)(t + 2) * kstep; const char* b2 = last ? nB : cB + (size_t)(t + 2) * kstep;
;             const char* a3 = a2 + kstep; const char* b3 = b2 + kstep;
	s_add_i32 s68, s68, 2
	s_add_u32 s28, s28, 0x100
	s_addc_u32 s29, s29, 0
	s_add_u32 s66, s66, 0x100
	s_addc_u32 s67, s67, 0

; #define PG8_STAGE(bufoff, gbase, voff) do { _Pragma("unroll") for (int _i = 0; _i < 2; ++_i) \
;         __builtin_amdgcn_global_load_lds((const unsigned*)((const char*)(gbase) + (voff)[_i]), (PG8_LAS unsigned*)(lds + (bufoff) + ldsw + _i * 8192), 16, 0, 0); } while (0)
; #define PG8_LDA(dst, b, h) do { _Pragma("unroll") for (int m = 0; m < 4; ++m) _Pragma("unroll") for (int k = 0; k < 2; ++k) dst[m][k] = *(const PG8_LAS bf16x8*)(lds + PG8_SA(b, h) + aoff + m * 2048 + k * 1024); } while (0)
; #define PG8_LDB(dst, b, h) do { _Pragma("unroll") for (int n = 0; n < 2; ++n) _Pragma("unroll") for (int k = 0; k < 2; ++k) dst[n][k] = *(const PG8_LAS bf16x8*)(lds + PG8_SB(b, h) + boff + n * 2048 + k * 1024); } while (0)
; #define PG8_SCHED __builtin_amdgcn_sched_barrier(0)
; template <class Epi, class Sched, bool ALIGN_EPI = false, bool SP2 = false>
; __device__ __forceinline__ void gemm_phase(PG8_LAS unsigned char* lds, const Gemm g, const Sched& S, const Epi& E) {
;     ...
;         const bool has_next = S.next(ui + 1, nxt);
;         const char* nA = has_next ? (const char*)g.A + (size_t)nxt.pm * tstep : cA; const char* nB = has_next ? (const char*)g.Bt + (size_t)nxt.pn * tstep : cB;
; #pragma nounroll
;         for (int t = 0; t < nt; t += 2) {
;             const bool last = (t == nt - 2);
;             const char* a1 = cA + (size_t)(t + 1) * kstep;
;             const char* a2 = last ? nA : cA + (size_t)(t + 2) * kstep; const char* b2 = last ? nB : cB + (size_t)(t + 2) * kstep;
;             const char* a3 = a2 + kstep; const char* b3 = b2 + kstep;
;             if (last && has_next) S.a_ready(nxt);
;             if constexpr (SP2) {
;             PG8_LDB(B0, 0, 0); PG8_LDB(B1, 0, 1); PG8_SCHED; PG8_LDA(At, 0, 0); PG8_STAGE(PG8_SA(1, 1), a1 + hstep, voffA);
.LBB0_1590:
	s_ashr_i32 s13, s12, 31
	s_lshl_b64 s[14:15], s[12:13], 19
	s_add_u32 s14, s26, s14
	s_addc_u32 s15, s27, s15
	s_and_b64 s[16:17], s[2:3], exec
	s_cselect_b32 s13, s15, s21
	s_cselect_b32 s52, s14, s20
	s_ashr_i32 s11, s10, 31
	s_lshl_b64 s[16:17], s[10:11], 19
	s_add_u32 s16, s28, s16
	s_addc_u32 s17, s29, s17
	s_and_b64 s[24:25], s[2:3], exec
	s_cselect_b32 s11, s17, s23
	s_cselect_b32 s53, s16, s22
	s_add_u32 s20, s20, 0x40080
	s_addc_u32 s21, s21, 0
	s_add_u32 s54, s22, 0x100
	s_addc_u32 s55, s23, 0
	s_mov_b32 s56, -2
	ds_read_b128 v[152:155], v149
	ds_read_b128 v[156:159], v149 offset:1024
	ds_read_b128 v[160:163], v149 offset:2048
	ds_read_b128 v[164:167], v149 offset:3072
	ds_read_b128 v[168:171], v150
	ds_read_b128 v[174:177], v150 offset:1024
	ds_read_b128 v[178:181], v150 offset:2048
	ds_read_b128 v[182:185], v150 offset:3072
	s_add_u32 s22, s20, 0xfffc0080
	s_addc_u32 s23, s21, -1
	s_cmp_eq_u32 s56, 12
	s_cselect_b32 s25, s13, s23
	s_cselect_b32 s24, s52, s22
	s_cselect_b32 s23, s11, s55
	s_cselect_b32 s22, s53, s54

; #define PG8_STAGE(bufoff, gbase, voff) do { _Pragma("unroll") for (int _i = 0; _i < 2; ++_i) \
;         __builtin_amdgcn_global_load_lds((const unsigned*)((const char*)(gbase) + (voff)[_i]), (PG8_LAS unsigned*)(lds + (bufoff) + ldsw + _i * 8192), 16, 0, 0); } while (0)
; #define PG8_LDA(dst, b, h) do { _Pragma("unroll") for (int m = 0; m < 4; ++m) _Pragma("unroll") for (int k = 0; k < 2; ++k) dst[m][k] = *(const PG8_LAS bf16x8*)(lds + PG8_SA(b, h) + aoff + m * 2048 + k * 1024); } while (0)
; #define PG8_LDB(dst, b, h) do { _Pragma("unroll") for (int n = 0; n < 2; ++n) _Pragma("unroll") for (int k = 0; k < 2; ++k) dst[n][k] = *(const PG8_LAS bf16x8*)(lds + PG8_SB(b, h) + boff + n * 2048 + k * 1024); } while (0)
; #define PG8_MMA(ai, bj, At, Bt) do { __builtin_amdgcn_s_setprio(1); _Pragma("unroll") for (int m = 0; m < 4; ++m) _Pragma("unroll") for (int n = 0; n < 2; ++n) _Pragma("unroll") for (int k = 0; k < 2; ++k) \
;         acc[ai][bj][m][n] = __builtin_amdgcn_mfma_f32_16x16x32_bf16(Bt[n][k], At[m][k], acc[ai][bj][m][n], 0, 0, 0); __builtin_amdgcn_s_setprio(0); } while (0)
; #define PG8_WAIT_V(n) asm volatile("s_waitcnt vmcnt(" #n ")" ::: "memory")
; #define PG8_WAIT_L(n) asm volatile("s_waitcnt lgkmcnt(" #n ")" ::: "memory")
; #define PG8_BAR __builtin_amdgcn_s_barrier()
; #define PG8_SCHED __builtin_amdgcn_sched_barrier(0)
; template <class Epi, class Sched, bool ALIGN_EPI = false, bool SP2 = false>
; __device__ __forceinline__ void gemm_phase(PG8_LAS unsigned char* lds, const Gemm g, const Sched& S, const Epi& E) {
;     ...
;             PG8_LDB(B0, 0, 0); PG8_LDB(B1, 0, 1); PG8_SCHED; PG8_LDA(At, 0, 0); PG8_STAGE(PG8_SA(1, 1), a1 + hstep, voffA);
;             PG8_WAIT_V(8); PG8_WAIT_L(0); PG8_BAR; PG8_MMA(0, 0, At, B0); PG8_MMA(0, 1, At, B1); PG8_BAR; PG8_SCHED;
	v_lshl_add_u64 v[218:219], s[20:21], 0, v[140:141]
	s_add_i32 m0, s34, 0xc000
	ds_read_b128 v[186:189], v151
	ds_read_b128 v[190:193], v151 offset:1024
	ds_read_b128 v[194:197], v151 offset:2048
	ds_read_b128 v[198:201], v151 offset:3072
	ds_read_b128 v[202:205], v151 offset:4096
	ds_read_b128 v[206:209], v151 offset:5120
	ds_read_b128 v[210:213], v151 offset:6144
	ds_read_b128 v[214:217], v151 offset:7168
	global_load_lds_dwordx4 v[218:219], off
	v_lshl_add_u64 v[218:219], s[20:21], 0, v[142:143]
	s_add_i32 m0, s34, 0xe000
	s_nop 0
	global_load_lds_dwordx4 v[218:219], off
	s_waitcnt vmcnt(16)
	s_waitcnt lgkmcnt(0)
	s_barrier
	s_setprio 1
	s_waitcnt lgkmcnt(0)
	v_mfma_f32_16x16x32_bf16 v[126:129], v[152:155], v[186:189], 0
	v_mfma_f32_16x16x32_bf16 v[122:125], v[160:163], v[186:189], 0
	v_mfma_f32_16x16x32_bf16 v[110:113], v[152:155], v[194:197], 0
	v_mfma_f32_16x16x32_bf16 v[106:109], v[160:163], v[194:197], 0
	v_mfma_f32_16x16x32_bf16 v[94:97], v[152:155], v[202:205], 0
	v_mfma_f32_16x16x32_bf16 v[90:93], v[160:163], v[202:205], 0
	v_mfma_f32_16x16x32_bf16 v[78:81], v[152:155], v[210:213], 0
	v_mfma_f32_16x16x32_bf16 v[74:77], v[160:163], v[210:213], 0
	v_mfma_f32_16x16x32_bf16 v[126:129], v[156:159], v[190:193], v[126:129]
	v_mfma_f32_16x16x32_bf16 v[122:125], v[164:167], v[190:193], v[122:125]
	v_mfma_f32_16x16x32_bf16 v[110:113], v[156:159], v[198:201], v[110:113]
	v_mfma_f32_16x16x32_bf16 v[106:109], v[164:167], v[198:201], v[106:109]
	v_mfma_f32_16x16x32_bf16 v[94:97], v[156:159], v[206:209], v[94:97]
	v_mfma_f32_16x16x32_bf16 v[90:93], v[164:167], v[206:209], v[90:93]
	v_mfma_f32_16x16x32_bf16 v[78:81], v[156:159], v[214:217], v[78:81]
	v_mfma_f32_16x16x32_bf16 v[74:77], v[164:167], v[214:217], v[74:77]
	s_setprio 0
	s_setprio 1
	v_mfma_f32_16x16x32_bf16 v[118:121], v[168:171], v[186:189], 0
	v_mfma_f32_16x16x32_bf16 v[114:117], v[178:181], v[186:189], 0
	v_mfma_f32_16x16x32_bf16 v[102:105], v[168:171], v[194:197], 0
	v_mfma_f32_16x16x32_bf16 v[98:101], v[178:181], v[194:197], 0
	v_mfma_f32_16x16x32_bf16 v[86:89], v[168:171], v[202:205], 0
	v_mfma_f32_16x16x32_bf16 v[82:85], v[178:181], v[202:205], 0
	v_mfma_f32_16x16x32_bf16 v[70:73], v[168:171], v[210:213], 0
	v_mfma_f32_16x16x32_bf16 v[66:69], v[178:181], v[210:213], 0
	v_mfma_f32_16x16x32_bf16 v[118:121], v[174:177], v[190:193], v[118:121]
	v_mfma_f32_16x16x32_bf16 v[114:117], v[182:185], v[190:193], v[114:117]
	v_mfma_f32_16x16x32_bf16 v[102:105], v[174:177], v[198:201], v[102:105]
	v_mfma_f32_16x16x32_bf16 v[98:101], v[182:185], v[198:201], v[98:101]
	v_mfma_f32_16x16x32_bf16 v[86:89], v[174:177], v[206:209], v[86:89]
	v_mfma_f32_16x16x32_bf16 v[82:85], v[182:185], v[206:209], v[82:85]
	v_mfma_f32_16x16x32_bf16 v[70:73], v[174:177], v[214:217], v[70:73]
	v_mfma_f32_16x16x32_bf16 v[66:69], v[182:185], v[214:217], v[66:69]
	s_setprio 0
	s_barrier

; #define PG8_STAGE(bufoff, gbase, voff) do { _Pragma("unroll") for (int _i = 0; _i < 2; ++_i) \
;         __builtin_amdgcn_global_load_lds((const unsigned*)((const char*)(gbase) + (voff)[_i]), (PG8_LAS unsigned*)(lds + (bufoff) + ldsw + _i * 8192), 16, 0, 0); } while (0)
; #define PG8_LDA(dst, b, h) do { _Pragma("unroll") for (int m = 0; m < 4; ++m) _Pragma("unroll") for (int k = 0; k < 2; ++k) dst[m][k] = *(const PG8_LAS bf16x8*)(lds + PG8_SA(b, h) + aoff + m * 2048 + k * 1024); } while (0)
; #define PG8_MMA(ai, bj, At, Bt) do { __builtin_amdgcn_s_setprio(1); _Pragma("unroll") for (int m = 0; m < 4; ++m) _Pragma("unroll") for (int n = 0; n < 2; ++n) _Pragma("unroll") for (int k = 0; k < 2; ++k) \
;         acc[ai][bj][m][n] = __builtin_amdgcn_mfma_f32_16x16x32_bf16(Bt[n][k], At[m][k], acc[ai][bj][m][n], 0, 0, 0); __builtin_amdgcn_s_setprio(0); } while (0)
; #define PG8_WAIT_V(n) asm volatile("s_waitcnt vmcnt(" #n ")" ::: "memory")
; #define PG8_WAIT_L(n) asm volatile("s_waitcnt lgkmcnt(" #n ")" ::: "memory")
; #define PG8_BAR __builtin_amdgcn_s_barrier()
; #define PG8_SCHED __builtin_amdgcn_sched_barrier(0)
; template <class Epi, class Sched, bool ALIGN_EPI = false, bool SP2 = false>
; __device__ __forceinline__ void gemm_phase(PG8_LAS unsigned char* lds, const Gemm g, const Sched& S, const Epi& E) {
;     ...
;             PG8_LDA(At, 0, 1); PG8_STAGE(PG8_SB(0, 0), b2, voffB); PG8_STAGE(PG8_SB(0, 1), b2 + hstep, voffB); PG8_STAGE(PG8_SA(0, 0), a2, voffA);
;             PG8_WAIT_V(8); PG8_WAIT_L(0); PG8_BAR; PG8_MMA(1, 0, At, B0); PG8_MMA(1, 1, At, B1); PG8_BAR; PG8_SCHED;
	s_add_i32 s57, s45, s30
	v_lshl_add_u64 v[218:219], s[22:23], 0, v[134:135]
	s_mov_b32 m0, s57
	ds_read_b128 v[186:189], v151 offset:16384
	ds_read_b128 v[190:193], v151 offset:17408
	ds_read_b128 v[194:197], v151 offset:18432
	ds_read_b128 v[198:201], v151 offset:19456
	ds_read_b128 v[202:205], v151 offset:20480
	ds_read_b128 v[206:209], v151 offset:21504
	ds_read_b128 v[210:213], v151 offset:22528
	ds_read_b128 v[214:217], v151 offset:23552
	global_load_lds_dwordx4 v[218:219], off
	s_add_i32 m0, s57, 0x2000
	s_add_u32 s58, s22, 0x40000
	v_lshl_add_u64 v[220:221], s[22:23], 0, v[130:131]
	s_addc_u32 s59, s23, 0
	s_add_i32 s57, s48, s30
	global_load_lds_dwordx4 v[220:221], off
	v_lshl_add_u64 v[222:223], s[58:59], 0, v[134:135]
	s_mov_b32 m0, s57
	v_lshl_add_u64 v[224:225], s[24:25], 0, v[132:133]
	global_load_lds_dwordx4 v[222:223], off
	v_lshl_add_u64 v[222:223], s[58:59], 0, v[130:131]
	s_add_i32 m0, s57, 0x2000
	s_nop 0
	global_load_lds_dwordx4 v[222:223], off
	v_lshl_add_u64 v[222:223], s[24:25], 0, v[136:137]
	s_mov_b32 m0, s34
	s_nop 0
	global_load_lds_dwordx4 v[222:223], off
	s_mov_b32 m0, s35
	s_nop 0
	global_load_lds_dwordx4 v[224:225], off
	s_waitcnt vmcnt(16)
	s_waitcnt lgkmcnt(0)
	s_barrier
	s_setprio 1
	s_waitcnt lgkmcnt(0)
	v_mfma_f32_16x16x32_bf16 v[62:65], v[152:155], v[186:189], 0
	v_mfma_f32_16x16x32_bf16 v[58:61], v[160:163], v[186:189], 0
	v_mfma_f32_16x16x32_bf16 v[46:49], v[152:155], v[194:197], 0
	v_mfma_f32_16x16x32_bf16 v[42:45], v[160:163], v[194:197], 0
	v_mfma_f32_16x16x32_bf16 v[30:33], v[152:155], v[202:205], 0
	v_mfma_f32_16x16x32_bf16 v[26:29], v[160:163], v[202:205], 0
	v_mfma_f32_16x16x32_bf16 v[14:17], v[152:155], v[210:213], 0
	v_mfma_f32_16x16x32_bf16 v[10:13], v[160:163], v[210:213], 0
	v_mfma_f32_16x16x32_bf16 v[62:65], v[156:159], v[190:193], v[62:65]
	v_mfma_f32_16x16x32_bf16 v[58:61], v[164:167], v[190:193], v[58:61]
	v_mfma_f32_16x16x32_bf16 v[46:49], v[156:159], v[198:201], v[46:49]
	v_mfma_f32_16x16x32_bf16 v[42:45], v[164:167], v[198:201], v[42:45]
	v_mfma_f32_16x16x32_bf16 v[30:33], v[156:159], v[206:209], v[30:33]
	v_mfma_f32_16x16x32_bf16 v[26:29], v[164:167], v[206:209], v[26:29]
	v_mfma_f32_16x16x32_bf16 v[14:17], v[156:159], v[214:217], v[14:17]
	v_mfma_f32_16x16x32_bf16 v[10:13], v[164:167], v[214:217], v[10:13]
	s_setprio 0
	s_setprio 1
	v_mfma_f32_16x16x32_bf16 v[54:57], v[168:171], v[186:189], 0
	v_mfma_f32_16x16x32_bf16 v[50:53], v[178:181], v[186:189], 0
	v_mfma_f32_16x16x32_bf16 v[38:41], v[168:171], v[194:197], 0
	v_mfma_f32_16x16x32_bf16 v[34:37], v[178:181], v[194:197], 0
	v_mfma_f32_16x16x32_bf16 v[22:25], v[168:171], v[202:205], 0
	v_mfma_f32_16x16x32_bf16 v[18:21], v[178:181], v[202:205], 0
	v_mfma_f32_16x16x32_bf16 v[6:9], v[168:171], v[210:213], 0
	v_mfma_f32_16x16x32_bf16 v[2:5], v[178:181], v[210:213], 0
	v_mfma_f32_16x16x32_bf16 v[54:57], v[174:177], v[190:193], v[54:57]
	v_mfma_f32_16x16x32_bf16 v[50:53], v[182:185], v[190:193], v[50:53]
	v_mfma_f32_16x16x32_bf16 v[38:41], v[174:177], v[198:201], v[38:41]
	v_mfma_f32_16x16x32_bf16 v[34:37], v[182:185], v[198:201], v[34:37]
	v_mfma_f32_16x16x32_bf16 v[22:25], v[174:177], v[206:209], v[22:25]
	v_mfma_f32_16x16x32_bf16 v[18:21], v[182:185], v[206:209], v[18:21]
	v_mfma_f32_16x16x32_bf16 v[6:9], v[174:177], v[214:217], v[6:9]
	v_mfma_f32_16x16x32_bf16 v[2:5], v[182:185], v[214:217], v[2:5]
	s_setprio 0
	s_barrier

; #define PG8_STAGE(bufoff, gbase, voff) do { _Pragma("unroll") for (int _i = 0; _i < 2; ++_i) \
;         __builtin_amdgcn_global_load_lds((const unsigned*)((const char*)(gbase) + (voff)[_i]), (PG8_LAS unsigned*)(lds + (bufoff) + ldsw + _i * 8192), 16, 0, 0); } while (0)
; #define PG8_LDA(dst, b, h) do { _Pragma("unroll") for (int m = 0; m < 4; ++m) _Pragma("unroll") for (int k = 0; k < 2; ++k) dst[m][k] = *(const PG8_LAS bf16x8*)(lds + PG8_SA(b, h) + aoff + m * 2048 + k * 1024); } while (0)
; #define PG8_LDB(dst, b, h) do { _Pragma("unroll") for (int n = 0; n < 2; ++n) _Pragma("unroll") for (int k = 0; k < 2; ++k) dst[n][k] = *(const PG8_LAS bf16x8*)(lds + PG8_SB(b, h) + boff + n * 2048 + k * 1024); } while (0)
; #define PG8_SCHED __builtin_amdgcn_sched_barrier(0)
; template <class Epi, class Sched, bool ALIGN_EPI = false, bool SP2 = false>
; __device__ __forceinline__ void gemm_phase(PG8_LAS unsigned char* lds, const Gemm g, const Sched& S, const Epi& E) {
;     ...
;             PG8_LDB(B0, 1, 0); PG8_LDB(B1, 1, 1); PG8_SCHED; PG8_LDA(At, 1, 0); PG8_STAGE(PG8_SA(0, 1), a2 + hstep, voffA);
	s_add_i32 s57, 0, 0x18000
	s_add_i32 s58, 0, 0x1c000
	v_add_u32_e32 v164, s57, v148
	v_add_u32_e32 v182, s58, v148
	ds_read_b128 v[152:155], v164
	ds_read_b128 v[156:159], v164 offset:1024
	ds_read_b128 v[160:163], v164 offset:2048
	ds_read_b128 v[164:167], v164 offset:3072
	ds_read_b128 v[168:171], v182
	ds_read_b128 v[174:177], v182 offset:1024
	ds_read_b128 v[178:181], v182 offset:2048
	ds_read_b128 v[182:185], v182 offset:3072

; #define PG8_STAGE(bufoff, gbase, voff) do { _Pragma("unroll") for (int _i = 0; _i < 2; ++_i) \
;         __builtin_amdgcn_global_load_lds((const unsigned*)((const char*)(gbase) + (voff)[_i]), (PG8_LAS unsigned*)(lds + (bufoff) + ldsw + _i * 8192), 16, 0, 0); } while (0)
; #define PG8_LDA(dst, b, h) do { _Pragma("unroll") for (int m = 0; m < 4; ++m) _Pragma("unroll") for (int k = 0; k < 2; ++k) dst[m][k] = *(const PG8_LAS bf16x8*)(lds + PG8_SA(b, h) + aoff + m * 2048 + k * 1024); } while (0)
; #define PG8_LDB(dst, b, h) do { _Pragma("unroll") for (int n = 0; n < 2; ++n) _Pragma("unroll") for (int k = 0; k < 2; ++k) dst[n][k] = *(const PG8_LAS bf16x8*)(lds + PG8_SB(b, h) + boff + n * 2048 + k * 1024); } while (0)
; #define PG8_MMA(ai, bj, At, Bt) do { __builtin_amdgcn_s_setprio(1); _Pragma("unroll") for (int m = 0; m < 4; ++m) _Pragma("unroll") for (int n = 0; n < 2; ++n) _Pragma("unroll") for (int k = 0; k < 2; ++k) \
;         acc[ai][bj][m][n] = __builtin_amdgcn_mfma_f32_16x16x32_bf16(Bt[n][k], At[m][k], acc[ai][bj][m][n], 0, 0, 0); __builtin_amdgcn_s_setprio(0); } while (0)
; #define PG8_WAIT_V(n) asm volatile("s_waitcnt vmcnt(" #n ")" ::: "memory")
; #define PG8_WAIT_L(n) asm volatile("s_waitcnt lgkmcnt(" #n ")" ::: "memory")
; #define PG8_BAR __builtin_amdgcn_s_barrier()
; #define PG8_SCHED __builtin_amdgcn_sched_barrier(0)
; template <class Epi, class Sched, bool ALIGN_EPI = false, bool SP2 = false>
; __device__ __forceinline__ void gemm_phase(PG8_LAS unsigned char* lds, const Gemm g, const Sched& S, const Epi& E) {
;     ...
;             PG8_LDB(B0, 1, 0); PG8_LDB(B1, 1, 1); PG8_SCHED; PG8_LDA(At, 1, 0); PG8_STAGE(PG8_SA(0, 1), a2 + hstep, voffA);
;             PG8_WAIT_V(8); PG8_WAIT_L(0); PG8_BAR; PG8_MMA(0, 0, At, B0); PG8_MMA(0, 1, At, B1); PG8_BAR; PG8_SCHED;
	s_add_u32 s24, s24, 0x40000
	s_addc_u32 s25, s25, 0
	s_mov_b32 m0, s38
	v_lshl_add_u64 v[226:227], s[24:25], 0, v[136:137]
	ds_read_b128 v[186:189], v151 offset:32768
	ds_read_b128 v[190:193], v151 offset:33792
	ds_read_b128 v[194:197], v151 offset:34816
	ds_read_b128 v[198:201], v151 offset:35840
	ds_read_b128 v[202:205], v151 offset:36864
	ds_read_b128 v[206:209], v151 offset:37888
	ds_read_b128 v[210:213], v151 offset:38912
	ds_read_b128 v[214:217], v151 offset:39936
	global_load_lds_dwordx4 v[226:227], off
	v_lshl_add_u64 v[226:227], s[24:25], 0, v[132:133]
	s_mov_b32 m0, s39
	s_nop 0
	global_load_lds_dwordx4 v[226:227], off
	s_waitcnt vmcnt(8)
	s_waitcnt lgkmcnt(0)
	s_barrier
	s_setprio 1
	s_waitcnt lgkmcnt(0)
	v_mfma_f32_16x16x32_bf16 v[126:129], v[152:155], v[186:189], v[126:129]
	v_mfma_f32_16x16x32_bf16 v[122:125], v[160:163], v[186:189], v[122:125]
	v_mfma_f32_16x16x32_bf16 v[110:113], v[152:155], v[194:197], v[110:113]
	v_mfma_f32_16x16x32_bf16 v[106:109], v[160:163], v[194:197], v[106:109]
	v_mfma_f32_16x16x32_bf16 v[94:97], v[152:155], v[202:205], v[94:97]
	v_mfma_f32_16x16x32_bf16 v[90:93], v[160:163], v[202:205], v[90:93]
	v_mfma_f32_16x16x32_bf16 v[78:81], v[152:155], v[210:213], v[78:81]
	v_mfma_f32_16x16x32_bf16 v[74:77], v[160:163], v[210:213], v[74:77]
	v_mfma_f32_16x16x32_bf16 v[126:129], v[156:159], v[190:193], v[126:129]
	v_mfma_f32_16x16x32_bf16 v[122:125], v[164:167], v[190:193], v[122:125]
	v_mfma_f32_16x16x32_bf16 v[110:113], v[156:159], v[198:201], v[110:113]
	v_mfma_f32_16x16x32_bf16 v[106:109], v[164:167], v[198:201], v[106:109]
	v_mfma_f32_16x16x32_bf16 v[94:97], v[156:159], v[206:209], v[94:97]
	v_mfma_f32_16x16x32_bf16 v[90:93], v[164:167], v[206:209], v[90:93]
	v_mfma_f32_16x16x32_bf16 v[78:81], v[156:159], v[214:217], v[78:81]
	v_mfma_f32_16x16x32_bf16 v[74:77], v[164:167], v[214:217], v[74:77]
	s_setprio 0
	s_setprio 1
	v_mfma_f32_16x16x32_bf16 v[118:121], v[168:171], v[186:189], v[118:121]
	v_mfma_f32_16x16x32_bf16 v[114:117], v[178:181], v[186:189], v[114:117]
	v_mfma_f32_16x16x32_bf16 v[102:105], v[168:171], v[194:197], v[102:105]
	v_mfma_f32_16x16x32_bf16 v[98:101], v[178:181], v[194:197], v[98:101]
	v_mfma_f32_16x16x32_bf16 v[86:89], v[168:171], v[202:205], v[86:89]
	v_mfma_f32_16x16x32_bf16 v[82:85], v[178:181], v[202:205], v[82:85]
	v_mfma_f32_16x16x32_bf16 v[70:73], v[168:171], v[210:213], v[70:73]
	v_mfma_f32_16x16x32_bf16 v[66:69], v[178:181], v[210:213], v[66:69]
	v_mfma_f32_16x16x32_bf16 v[118:121], v[174:177], v[190:193], v[118:121]
	v_mfma_f32_16x16x32_bf16 v[114:117], v[182:185], v[190:193], v[114:117]
	v_mfma_f32_16x16x32_bf16 v[102:105], v[174:177], v[198:201], v[102:105]
	v_mfma_f32_16x16x32_bf16 v[98:101], v[182:185], v[198:201], v[98:101]
	v_mfma_f32_16x16x32_bf16 v[86:89], v[174:177], v[206:209], v[86:89]
	v_mfma_f32_16x16x32_bf16 v[82:85], v[182:185], v[206:209], v[82:85]
	v_mfma_f32_16x16x32_bf16 v[70:73], v[174:177], v[214:217], v[70:73]
	v_mfma_f32_16x16x32_bf16 v[66:69], v[182:185], v[214:217], v[66:69]
	s_setprio 0
	s_barrier

; #define PG8_STAGE(bufoff, gbase, voff) do { _Pragma("unroll") for (int _i = 0; _i < 2; ++_i) \
;         __builtin_amdgcn_global_load_lds((const unsigned*)((const char*)(gbase) + (voff)[_i]), (PG8_LAS unsigned*)(lds + (bufoff) + ldsw + _i * 8192), 16, 0, 0); } while (0)
; #define PG8_LDA(dst, b, h) do { _Pragma("unroll") for (int m = 0; m < 4; ++m) _Pragma("unroll") for (int k = 0; k < 2; ++k) dst[m][k] = *(const PG8_LAS bf16x8*)(lds + PG8_SA(b, h) + aoff + m * 2048 + k * 1024); } while (0)
; #define PG8_MMA(ai, bj, At, Bt) do { __builtin_amdgcn_s_setprio(1); _Pragma("unroll") for (int m = 0; m < 4; ++m) _Pragma("unroll") for (int n = 0; n < 2; ++n) _Pragma("unroll") for (int k = 0; k < 2; ++k) \
;         acc[ai][bj][m][n] = __builtin_amdgcn_mfma_f32_16x16x32_bf16(Bt[n][k], At[m][k], acc[ai][bj][m][n], 0, 0, 0); __builtin_amdgcn_s_setprio(0); } while (0)
; #define PG8_WAIT_V(n) asm volatile("s_waitcnt vmcnt(" #n ")" ::: "memory")
; #define PG8_WAIT_L(n) asm volatile("s_waitcnt lgkmcnt(" #n ")" ::: "memory")
; #define PG8_BAR __builtin_amdgcn_s_barrier()
; #define PG8_SCHED __builtin_amdgcn_sched_barrier(0)
; template <class Epi, class Sched, bool ALIGN_EPI = false, bool SP2 = false>
; __device__ __forceinline__ void gemm_phase(PG8_LAS unsigned char* lds, const Gemm g, const Sched& S, const Epi& E) {
;     ...
;             PG8_LDA(At, 1, 1); PG8_STAGE(PG8_SB(1, 0), b3, voffB); PG8_STAGE(PG8_SB(1, 1), b3 + hstep, voffB); PG8_STAGE(PG8_SA(1, 0), a3, voffA);
;             PG8_WAIT_V(8); PG8_WAIT_L(0); PG8_BAR; PG8_MMA(1, 0, At, B0); PG8_MMA(1, 1, At, B1); PG8_BAR; PG8_SCHED;
	s_add_i32 s24, s57, s30
	v_lshl_add_u64 v[218:219], v[218:219], 0, s[6:7]
	s_mov_b32 m0, s24
	ds_read_b128 v[186:189], v151 offset:49152
	ds_read_b128 v[190:193], v151 offset:50176
	ds_read_b128 v[194:197], v151 offset:51200
	ds_read_b128 v[198:201], v151 offset:52224
	ds_read_b128 v[202:205], v151 offset:53248
	ds_read_b128 v[206:209], v151 offset:54272
	ds_read_b128 v[210:213], v151 offset:55296
	ds_read_b128 v[214:217], v151 offset:56320
	global_load_lds_dwordx4 v[218:219], off
	s_add_i32 m0, s24, 0x2000
	s_add_u32 s22, s22, 0x40080
	v_lshl_add_u64 v[218:219], v[220:221], 0, s[6:7]
	s_addc_u32 s23, s23, 0
	s_add_i32 s24, s58, s30
	global_load_lds_dwordx4 v[218:219], off
	v_lshl_add_u64 v[218:219], s[22:23], 0, v[134:135]
	s_mov_b32 m0, s24
	s_nop 0
	global_load_lds_dwordx4 v[218:219], off
	v_lshl_add_u64 v[218:219], s[22:23], 0, v[130:131]
	s_add_i32 m0, s24, 0x2000
	s_nop 0
	global_load_lds_dwordx4 v[218:219], off
	v_lshl_add_u64 v[218:219], v[222:223], 0, s[6:7]
	s_mov_b32 m0, s41
	s_nop 0
	global_load_lds_dwordx4 v[218:219], off
	v_lshl_add_u64 v[218:219], v[224:225], 0, s[6:7]
	s_mov_b32 m0, s42
	s_nop 0
	global_load_lds_dwordx4 v[218:219], off
	s_waitcnt vmcnt(8)
	s_waitcnt lgkmcnt(0)
	s_barrier
	s_setprio 1
	s_waitcnt lgkmcnt(0)
	v_mfma_f32_16x16x32_bf16 v[62:65], v[152:155], v[186:189], v[62:65]
	v_mfma_f32_16x16x32_bf16 v[58:61], v[160:163], v[186:189], v[58:61]
	v_mfma_f32_16x16x32_bf16 v[46:49], v[152:155], v[194:197], v[46:49]
	v_mfma_f32_16x16x32_bf16 v[42:45], v[160:163], v[194:197], v[42:45]
	v_mfma_f32_16x16x32_bf16 v[30:33], v[152:155], v[202:205], v[30:33]
	v_mfma_f32_16x16x32_bf16 v[26:29], v[160:163], v[202:205], v[26:29]
	v_mfma_f32_16x16x32_bf16 v[14:17], v[152:155], v[210:213], v[14:17]
	v_mfma_f32_16x16x32_bf16 v[10:13], v[160:163], v[210:213], v[10:13]
	v_mfma_f32_16x16x32_bf16 v[62:65], v[156:159], v[190:193], v[62:65]
	v_mfma_f32_16x16x32_bf16 v[58:61], v[164:167], v[190:193], v[58:61]
	v_mfma_f32_16x16x32_bf16 v[46:49], v[156:159], v[198:201], v[46:49]
	v_mfma_f32_16x16x32_bf16 v[42:45], v[164:167], v[198:201], v[42:45]
	v_mfma_f32_16x16x32_bf16 v[30:33], v[156:159], v[206:209], v[30:33]
	v_mfma_f32_16x16x32_bf16 v[26:29], v[164:167], v[206:209], v[26:29]
	v_mfma_f32_16x16x32_bf16 v[14:17], v[156:159], v[214:217], v[14:17]
	v_mfma_f32_16x16x32_bf16 v[10:13], v[164:167], v[214:217], v[10:13]
	s_setprio 0
	s_setprio 1
	v_mfma_f32_16x16x32_bf16 v[54:57], v[168:171], v[186:189], v[54:57]
	v_mfma_f32_16x16x32_bf16 v[50:53], v[178:181], v[186:189], v[50:53]
	v_mfma_f32_16x16x32_bf16 v[38:41], v[168:171], v[194:197], v[38:41]
	v_mfma_f32_16x16x32_bf16 v[34:37], v[178:181], v[194:197], v[34:37]
	v_mfma_f32_16x16x32_bf16 v[22:25], v[168:171], v[202:205], v[22:25]
	v_mfma_f32_16x16x32_bf16 v[18:21], v[178:181], v[202:205], v[18:21]
	v_mfma_f32_16x16x32_bf16 v[6:9], v[168:171], v[210:213], v[6:9]
	v_mfma_f32_16x16x32_bf16 v[2:5], v[178:181], v[210:213], v[2:5]
	v_mfma_f32_16x16x32_bf16 v[54:57], v[174:177], v[190:193], v[54:57]
	v_mfma_f32_16x16x32_bf16 v[50:53], v[182:185], v[190:193], v[50:53]
	v_mfma_f32_16x16x32_bf16 v[38:41], v[174:177], v[198:201], v[38:41]
	v_mfma_f32_16x16x32_bf16 v[34:37], v[182:185], v[198:201], v[34:37]
	v_mfma_f32_16x16x32_bf16 v[22:25], v[174:177], v[206:209], v[22:25]
	v_mfma_f32_16x16x32_bf16 v[18:21], v[182:185], v[206:209], v[18:21]
	v_mfma_f32_16x16x32_bf16 v[6:9], v[174:177], v[214:217], v[6:9]
	v_mfma_f32_16x16x32_bf16 v[2:5], v[182:185], v[214:217], v[2:5]
	s_setprio 0
	s_barrier

; template <class Epi, class Sched, bool ALIGN_EPI = false, bool SP2 = false>
; __device__ __forceinline__ void gemm_phase(PG8_LAS unsigned char* lds, const Gemm g, const Sched& S, const Epi& E) {
;     ...
;         for (int t = 0; t < nt; t += 2) {
;             const bool last = (t == nt - 2);
;             const char* a1 = cA + (size_t)(t + 1) * kstep;
;             const char* a2 = last ? nA : cA + (size_t)(t + 2) * kstep; const char* b2 = last ? nB : cB + (size_t)(t + 2) * kstep;
;             const char* a3 = a2 + kstep; const char* b3 = b2 + kstep;
	s_add_i32 s56, s56, 2
	s_add_u32 s20, s20, 0x100
	s_addc_u32 s21, s21, 0
	s_add_u32 s54, s54, 0x100
	s_addc_u32 s55, s55, 0

; #define PG8_STAGE(bufoff, gbase, voff) do { _Pragma("unroll") for (int _i = 0; _i < 2; ++_i) \
;         __builtin_amdgcn_global_load_lds((const unsigned*)((const char*)(gbase) + (voff)[_i]), (PG8_LAS unsigned*)(lds + (bufoff) + ldsw + _i * 8192), 16, 0, 0); } while (0)
; #define PG8_LDA(dst, b, h) do { _Pragma("unroll") for (int m = 0; m < 4; ++m) _Pragma("unroll") for (int k = 0; k < 2; ++k) dst[m][k] = *(const PG8_LAS bf16x8*)(lds + PG8_SA(b, h) + aoff + m * 2048 + k * 1024); } while (0)
; #define PG8_LDB(dst, b, h) do { _Pragma("unroll") for (int n = 0; n < 2; ++n) _Pragma("unroll") for (int k = 0; k < 2; ++k) dst[n][k] = *(const PG8_LAS bf16x8*)(lds + PG8_SB(b, h) + boff + n * 2048 + k * 1024); } while (0)
; #define PG8_SCHED __builtin_amdgcn_sched_barrier(0)
; template <class Epi, class Sched, bool ALIGN_EPI = false, bool SP2 = false>
; __device__ __forceinline__ void gemm_phase(PG8_LAS unsigned char* lds, const Gemm g, const Sched& S, const Epi& E) {
;     ...
;         const bool has_next = S.next(ui + 1, nxt);
;         const char* nA = has_next ? (const char*)g.A + (size_t)nxt.pm * tstep : cA; const char* nB = has_next ? (const char*)g.Bt + (size_t)nxt.pn * tstep : cB;
; #pragma nounroll
;         for (int t = 0; t < nt; t += 2) {
;             const bool last = (t == nt - 2);
;             const char* a1 = cA + (size_t)(t + 1) * kstep;
;             const char* a2 = last ? nA : cA + (size_t)(t + 2) * kstep; const char* b2 = last ? nB : cB + (size_t)(t + 2) * kstep;
;             const char* a3 = a2 + kstep; const char* b3 = b2 + kstep;
;             if (last && has_next) S.a_ready(nxt);
;             if constexpr (SP2) {
;             PG8_LDB(B0, 0, 0); PG8_LDB(B1, 0, 1); PG8_SCHED; PG8_LDA(At, 0, 0); PG8_STAGE(PG8_SA(1, 1), a1 + hstep, voffA);
.LBB0_1687:
	s_add_u32 s22, s22, 0xb0080
	s_addc_u32 s23, s23, 0
	s_add_u32 s60, s24, 0x100
	s_addc_u32 s61, s25, 0
	s_mov_b32 s62, -2
	ds_read_b128 v[154:157], v150
	ds_read_b128 v[158:161], v150 offset:1024
	ds_read_b128 v[162:165], v150 offset:2048
	ds_read_b128 v[166:169], v150 offset:3072
	ds_read_b128 v[174:177], v151
	ds_read_b128 v[178:181], v151 offset:1024
	ds_read_b128 v[182:185], v151 offset:2048
	ds_read_b128 v[186:189], v151 offset:3072
	s_add_u32 s24, s22, 0xfff50080
	s_addc_u32 s25, s23, -1
	s_cmp_eq_u32 s62, 40
	s_cselect_b32 s27, s5, s25
	s_cselect_b32 s26, s4, s24
	s_cselect_b32 s25, s21, s61
	s_cselect_b32 s24, s20, s60

; #define PG8_STAGE(bufoff, gbase, voff) do { _Pragma("unroll") for (int _i = 0; _i < 2; ++_i) \
;         __builtin_amdgcn_global_load_lds((const unsigned*)((const char*)(gbase) + (voff)[_i]), (PG8_LAS unsigned*)(lds + (bufoff) + ldsw + _i * 8192), 16, 0, 0); } while (0)
; #define PG8_LDA(dst, b, h) do { _Pragma("unroll") for (int m = 0; m < 4; ++m) _Pragma("unroll") for (int k = 0; k < 2; ++k) dst[m][k] = *(const PG8_LAS bf16x8*)(lds + PG8_SA(b, h) + aoff + m * 2048 + k * 1024); } while (0)
; #define PG8_LDB(dst, b, h) do { _Pragma("unroll") for (int n = 0; n < 2; ++n) _Pragma("unroll") for (int k = 0; k < 2; ++k) dst[n][k] = *(const PG8_LAS bf16x8*)(lds + PG8_SB(b, h) + boff + n * 2048 + k * 1024); } while (0)
; #define PG8_MMA(ai, bj, At, Bt) do { __builtin_amdgcn_s_setprio(1); _Pragma("unroll") for (int m = 0; m < 4; ++m) _Pragma("unroll") for (int n = 0; n < 2; ++n) _Pragma("unroll") for (int k = 0; k < 2; ++k) \
;         acc[ai][bj][m][n] = __builtin_amdgcn_mfma_f32_16x16x32_bf16(Bt[n][k], At[m][k], acc[ai][bj][m][n], 0, 0, 0); __builtin_amdgcn_s_setprio(0); } while (0)
; #define PG8_WAIT_V(n) asm volatile("s_waitcnt vmcnt(" #n ")" ::: "memory")
; #define PG8_WAIT_L(n) asm volatile("s_waitcnt lgkmcnt(" #n ")" ::: "memory")
; #define PG8_BAR __builtin_amdgcn_s_barrier()
; #define PG8_SCHED __builtin_amdgcn_sched_barrier(0)
; template <class Epi, class Sched, bool ALIGN_EPI = false, bool SP2 = false>
; __device__ __forceinline__ void gemm_phase(PG8_LAS unsigned char* lds, const Gemm g, const Sched& S, const Epi& E) {
;     ...
;             PG8_LDB(B0, 0, 0); PG8_LDB(B1, 0, 1); PG8_SCHED; PG8_LDA(At, 0, 0); PG8_STAGE(PG8_SA(1, 1), a1 + hstep, voffA);
;             PG8_WAIT_V(8); PG8_WAIT_L(0); PG8_BAR; PG8_MMA(0, 0, At, B0); PG8_MMA(0, 1, At, B1); PG8_BAR; PG8_SCHED;
	v_lshl_add_u64 v[146:147], s[22:23], 0, v[138:139]
	s_add_i32 m0, s35, 0xc000
	ds_read_b128 v[190:193], v152
	ds_read_b128 v[194:197], v152 offset:1024
	ds_read_b128 v[198:201], v152 offset:2048
	ds_read_b128 v[202:205], v152 offset:3072
	ds_read_b128 v[206:209], v152 offset:4096
	ds_read_b128 v[210:213], v152 offset:5120
	ds_read_b128 v[214:217], v152 offset:6144
	ds_read_b128 v[218:221], v152 offset:7168
	global_load_lds_dwordx4 v[146:147], off
	v_lshl_add_u64 v[146:147], s[22:23], 0, v[140:141]
	s_add_i32 m0, s35, 0xe000
	s_nop 0
	global_load_lds_dwordx4 v[146:147], off
	s_waitcnt vmcnt(24)
	s_waitcnt lgkmcnt(0)
	s_barrier
	s_setprio 1
	s_waitcnt lgkmcnt(0)
	v_mfma_f32_16x16x32_bf16 v[126:129], v[154:157], v[190:193], 0
	v_mfma_f32_16x16x32_bf16 v[122:125], v[162:165], v[190:193], 0
	v_mfma_f32_16x16x32_bf16 v[118:121], v[154:157], v[198:201], 0
	v_mfma_f32_16x16x32_bf16 v[110:113], v[162:165], v[198:201], 0
	v_mfma_f32_16x16x32_bf16 v[102:105], v[154:157], v[206:209], 0
	v_mfma_f32_16x16x32_bf16 v[94:97], v[162:165], v[206:209], 0
	v_mfma_f32_16x16x32_bf16 v[86:89], v[154:157], v[214:217], 0
	v_mfma_f32_16x16x32_bf16 v[78:81], v[162:165], v[214:217], 0
	v_mfma_f32_16x16x32_bf16 v[126:129], v[158:161], v[194:197], v[126:129]
	v_mfma_f32_16x16x32_bf16 v[122:125], v[166:169], v[194:197], v[122:125]
	v_mfma_f32_16x16x32_bf16 v[118:121], v[158:161], v[202:205], v[118:121]
	v_mfma_f32_16x16x32_bf16 v[110:113], v[166:169], v[202:205], v[110:113]
	v_mfma_f32_16x16x32_bf16 v[102:105], v[158:161], v[210:213], v[102:105]
	v_mfma_f32_16x16x32_bf16 v[94:97], v[166:169], v[210:213], v[94:97]
	v_mfma_f32_16x16x32_bf16 v[86:89], v[158:161], v[218:221], v[86:89]
	v_mfma_f32_16x16x32_bf16 v[78:81], v[166:169], v[218:221], v[78:81]
	s_setprio 0
	s_setprio 1
	v_mfma_f32_16x16x32_bf16 v[114:117], v[174:177], v[190:193], 0
	v_mfma_f32_16x16x32_bf16 v[106:109], v[182:185], v[190:193], 0
	v_mfma_f32_16x16x32_bf16 v[98:101], v[174:177], v[198:201], 0
	v_mfma_f32_16x16x32_bf16 v[90:93], v[182:185], v[198:201], 0
	v_mfma_f32_16x16x32_bf16 v[82:85], v[174:177], v[206:209], 0
	v_mfma_f32_16x16x32_bf16 v[74:77], v[182:185], v[206:209], 0
	v_mfma_f32_16x16x32_bf16 v[70:73], v[174:177], v[214:217], 0
	v_mfma_f32_16x16x32_bf16 v[66:69], v[182:185], v[214:217], 0
	v_mfma_f32_16x16x32_bf16 v[114:117], v[178:181], v[194:197], v[114:117]
	v_mfma_f32_16x16x32_bf16 v[106:109], v[186:189], v[194:197], v[106:109]
	v_mfma_f32_16x16x32_bf16 v[98:101], v[178:181], v[202:205], v[98:101]
	v_mfma_f32_16x16x32_bf16 v[90:93], v[186:189], v[202:205], v[90:93]
	v_mfma_f32_16x16x32_bf16 v[82:85], v[178:181], v[210:213], v[82:85]
	v_mfma_f32_16x16x32_bf16 v[74:77], v[186:189], v[210:213], v[74:77]
	v_mfma_f32_16x16x32_bf16 v[70:73], v[178:181], v[218:221], v[70:73]
	v_mfma_f32_16x16x32_bf16 v[66:69], v[186:189], v[218:221], v[66:69]
	s_setprio 0
	s_barrier

; #define PG8_STAGE(bufoff, gbase, voff) do { _Pragma("unroll") for (int _i = 0; _i < 2; ++_i) \
;         __builtin_amdgcn_global_load_lds((const unsigned*)((const char*)(gbase) + (voff)[_i]), (PG8_LAS unsigned*)(lds + (bufoff) + ldsw + _i * 8192), 16, 0, 0); } while (0)
; #define PG8_LDA(dst, b, h) do { _Pragma("unroll") for (int m = 0; m < 4; ++m) _Pragma("unroll") for (int k = 0; k < 2; ++k) dst[m][k] = *(const PG8_LAS bf16x8*)(lds + PG8_SA(b, h) + aoff + m * 2048 + k * 1024); } while (0)
; #define PG8_MMA(ai, bj, At, Bt) do { __builtin_amdgcn_s_setprio(1); _Pragma("unroll") for (int m = 0; m < 4; ++m) _Pragma("unroll") for (int n = 0; n < 2; ++n) _Pragma("unroll") for (int k = 0; k < 2; ++k) \
;         acc[ai][bj][m][n] = __builtin_amdgcn_mfma_f32_16x16x32_bf16(Bt[n][k], At[m][k], acc[ai][bj][m][n], 0, 0, 0); __builtin_amdgcn_s_setprio(0); } while (0)
; #define PG8_WAIT_V(n) asm volatile("s_waitcnt vmcnt(" #n ")" ::: "memory")
; #define PG8_WAIT_L(n) asm volatile("s_waitcnt lgkmcnt(" #n ")" ::: "memory")
; #define PG8_BAR __builtin_amdgcn_s_barrier()
; #define PG8_SCHED __builtin_amdgcn_sched_barrier(0)
; template <class Epi, class Sched, bool ALIGN_EPI = false, bool SP2 = false>
; __device__ __forceinline__ void gemm_phase(PG8_LAS unsigned char* lds, const Gemm g, const Sched& S, const Epi& E) {
;     ...
;             PG8_LDA(At, 0, 1); PG8_STAGE(PG8_SB(0, 0), b2, voffB); PG8_STAGE(PG8_SB(0, 1), b2 + hstep, voffB); PG8_STAGE(PG8_SA(0, 0), a2, voffA);
;             PG8_WAIT_V(8); PG8_WAIT_L(0); PG8_BAR; PG8_MMA(1, 0, At, B0); PG8_MMA(1, 1, At, B1); PG8_BAR; PG8_SCHED;
	s_add_i32 s63, s48, s34
	v_lshl_add_u64 v[146:147], s[24:25], 0, v[132:133]
	s_mov_b32 m0, s63
	ds_read_b128 v[190:193], v152 offset:16384
	ds_read_b128 v[194:197], v152 offset:17408
	ds_read_b128 v[198:201], v152 offset:18432
	ds_read_b128 v[202:205], v152 offset:19456
	ds_read_b128 v[206:209], v152 offset:20480
	ds_read_b128 v[210:213], v152 offset:21504
	ds_read_b128 v[214:217], v152 offset:22528
	ds_read_b128 v[218:221], v152 offset:23552
	global_load_lds_dwordx4 v[146:147], off
	s_add_i32 m0, s63, 0x2000
	s_add_u32 s64, s24, 0xb0000
	v_lshl_add_u64 v[170:171], s[24:25], 0, v[136:137]
	s_addc_u32 s65, s25, 0
	s_add_i32 s63, s49, s34
	global_load_lds_dwordx4 v[170:171], off
	v_lshl_add_u64 v[222:223], s[64:65], 0, v[132:133]
	s_mov_b32 m0, s63
	v_lshl_add_u64 v[224:225], s[26:27], 0, v[134:135]
	global_load_lds_dwordx4 v[222:223], off
	v_lshl_add_u64 v[222:223], s[64:65], 0, v[136:137]
	s_add_i32 m0, s63, 0x2000
	s_nop 0
	global_load_lds_dwordx4 v[222:223], off
	v_lshl_add_u64 v[222:223], s[26:27], 0, v[130:131]
	s_mov_b32 m0, s35
	s_nop 0
	global_load_lds_dwordx4 v[222:223], off
	s_mov_b32 m0, s38
	s_nop 0
	global_load_lds_dwordx4 v[224:225], off
	s_waitcnt vmcnt(24)
	s_waitcnt lgkmcnt(0)
	s_barrier
	s_setprio 1
	s_waitcnt lgkmcnt(0)
	v_mfma_f32_16x16x32_bf16 v[62:65], v[154:157], v[190:193], 0
	v_mfma_f32_16x16x32_bf16 v[58:61], v[162:165], v[190:193], 0
	v_mfma_f32_16x16x32_bf16 v[54:57], v[154:157], v[198:201], 0
	v_mfma_f32_16x16x32_bf16 v[46:49], v[162:165], v[198:201], 0
	v_mfma_f32_16x16x32_bf16 v[38:41], v[154:157], v[206:209], 0
	v_mfma_f32_16x16x32_bf16 v[30:33], v[162:165], v[206:209], 0
	v_mfma_f32_16x16x32_bf16 v[22:25], v[154:157], v[214:217], 0
	v_mfma_f32_16x16x32_bf16 v[14:17], v[162:165], v[214:217], 0
	v_mfma_f32_16x16x32_bf16 v[62:65], v[158:161], v[194:197], v[62:65]
	v_mfma_f32_16x16x32_bf16 v[58:61], v[166:169], v[194:197], v[58:61]
	v_mfma_f32_16x16x32_bf16 v[54:57], v[158:161], v[202:205], v[54:57]
	v_mfma_f32_16x16x32_bf16 v[46:49], v[166:169], v[202:205], v[46:49]
	v_mfma_f32_16x16x32_bf16 v[38:41], v[158:161], v[210:213], v[38:41]
	v_mfma_f32_16x16x32_bf16 v[30:33], v[166:169], v[210:213], v[30:33]
	v_mfma_f32_16x16x32_bf16 v[22:25], v[158:161], v[218:221], v[22:25]
	v_mfma_f32_16x16x32_bf16 v[14:17], v[166:169], v[218:221], v[14:17]
	s_setprio 0
	s_setprio 1
	v_mfma_f32_16x16x32_bf16 v[50:53], v[174:177], v[190:193], 0
	v_mfma_f32_16x16x32_bf16 v[42:45], v[182:185], v[190:193], 0
	v_mfma_f32_16x16x32_bf16 v[34:37], v[174:177], v[198:201], 0
	v_mfma_f32_16x16x32_bf16 v[26:29], v[182:185], v[198:201], 0
	v_mfma_f32_16x16x32_bf16 v[18:21], v[174:177], v[206:209], 0
	v_mfma_f32_16x16x32_bf16 v[10:13], v[182:185], v[206:209], 0
	v_mfma_f32_16x16x32_bf16 v[6:9], v[174:177], v[214:217], 0
	v_mfma_f32_16x16x32_bf16 v[2:5], v[182:185], v[214:217], 0
	v_mfma_f32_16x16x32_bf16 v[50:53], v[178:181], v[194:197], v[50:53]
	v_mfma_f32_16x16x32_bf16 v[42:45], v[186:189], v[194:197], v[42:45]
	v_mfma_f32_16x16x32_bf16 v[34:37], v[178:181], v[202:205], v[34:37]
	v_mfma_f32_16x16x32_bf16 v[26:29], v[186:189], v[202:205], v[26:29]
	v_mfma_f32_16x16x32_bf16 v[18:21], v[178:181], v[210:213], v[18:21]
	v_mfma_f32_16x16x32_bf16 v[10:13], v[186:189], v[210:213], v[10:13]
	v_mfma_f32_16x16x32_bf16 v[6:9], v[178:181], v[218:221], v[6:9]
	v_mfma_f32_16x16x32_bf16 v[2:5], v[186:189], v[218:221], v[2:5]
	s_setprio 0
	s_barrier

; #define PG8_STAGE(bufoff, gbase, voff) do { _Pragma("unroll") for (int _i = 0; _i < 2; ++_i) \
;         __builtin_amdgcn_global_load_lds((const unsigned*)((const char*)(gbase) + (voff)[_i]), (PG8_LAS unsigned*)(lds + (bufoff) + ldsw + _i * 8192), 16, 0, 0); } while (0)
; #define PG8_LDA(dst, b, h) do { _Pragma("unroll") for (int m = 0; m < 4; ++m) _Pragma("unroll") for (int k = 0; k < 2; ++k) dst[m][k] = *(const PG8_LAS bf16x8*)(lds + PG8_SA(b, h) + aoff + m * 2048 + k * 1024); } while (0)
; #define PG8_LDB(dst, b, h) do { _Pragma("unroll") for (int n = 0; n < 2; ++n) _Pragma("unroll") for (int k = 0; k < 2; ++k) dst[n][k] = *(const PG8_LAS bf16x8*)(lds + PG8_SB(b, h) + boff + n * 2048 + k * 1024); } while (0)
; #define PG8_SCHED __builtin_amdgcn_sched_barrier(0)
; template <class Epi, class Sched, bool ALIGN_EPI = false, bool SP2 = false>
; __device__ __forceinline__ void gemm_phase(PG8_LAS unsigned char* lds, const Gemm g, const Sched& S, const Epi& E) {
;     ...
;             PG8_LDB(B0, 1, 0); PG8_LDB(B1, 1, 1); PG8_SCHED; PG8_LDA(At, 1, 0); PG8_STAGE(PG8_SA(0, 1), a2 + hstep, voffA);
	s_add_i32 s63, 0, 0x18000
	v_add_u32_e32 v153, s63, v148
	s_add_i32 s64, 0, 0x1c000
	ds_read_b128 v[154:157], v153
	ds_read_b128 v[158:161], v153 offset:1024
	ds_read_b128 v[162:165], v153 offset:2048
	ds_read_b128 v[166:169], v153 offset:3072
	v_add_u32_e32 v153, s64, v148
	ds_read_b128 v[174:177], v153
	ds_read_b128 v[178:181], v153 offset:1024
	ds_read_b128 v[182:185], v153 offset:2048
	ds_read_b128 v[186:189], v153 offset:3072

; #define PG8_STAGE(bufoff, gbase, voff) do { _Pragma("unroll") for (int _i = 0; _i < 2; ++_i) \
;         __builtin_amdgcn_global_load_lds((const unsigned*)((const char*)(gbase) + (voff)[_i]), (PG8_LAS unsigned*)(lds + (bufoff) + ldsw + _i * 8192), 16, 0, 0); } while (0)
; #define PG8_LDA(dst, b, h) do { _Pragma("unroll") for (int m = 0; m < 4; ++m) _Pragma("unroll") for (int k = 0; k < 2; ++k) dst[m][k] = *(const PG8_LAS bf16x8*)(lds + PG8_SA(b, h) + aoff + m * 2048 + k * 1024); } while (0)
; #define PG8_LDB(dst, b, h) do { _Pragma("unroll") for (int n = 0; n < 2; ++n) _Pragma("unroll") for (int k = 0; k < 2; ++k) dst[n][k] = *(const PG8_LAS bf16x8*)(lds + PG8_SB(b, h) + boff + n * 2048 + k * 1024); } while (0)
; #define PG8_MMA(ai, bj, At, Bt) do { __builtin_amdgcn_s_setprio(1); _Pragma("unroll") for (int m = 0; m < 4; ++m) _Pragma("unroll") for (int n = 0; n < 2; ++n) _Pragma("unroll") for (int k = 0; k < 2; ++k) \
;         acc[ai][bj][m][n] = __builtin_amdgcn_mfma_f32_16x16x32_bf16(Bt[n][k], At[m][k], acc[ai][bj][m][n], 0, 0, 0); __builtin_amdgcn_s_setprio(0); } while (0)
; #define PG8_WAIT_V(n) asm volatile("s_waitcnt vmcnt(" #n ")" ::: "memory")
; #define PG8_WAIT_L(n) asm volatile("s_waitcnt lgkmcnt(" #n ")" ::: "memory")
; #define PG8_BAR __builtin_amdgcn_s_barrier()
; #define PG8_SCHED __builtin_amdgcn_sched_barrier(0)
; template <class Epi, class Sched, bool ALIGN_EPI = false, bool SP2 = false>
; __device__ __forceinline__ void gemm_phase(PG8_LAS unsigned char* lds, const Gemm g, const Sched& S, const Epi& E) {
;     ...
;             PG8_LDB(B0, 1, 0); PG8_LDB(B1, 1, 1); PG8_SCHED; PG8_LDA(At, 1, 0); PG8_STAGE(PG8_SA(0, 1), a2 + hstep, voffA);
;             PG8_WAIT_V(8); PG8_WAIT_L(0); PG8_BAR; PG8_MMA(0, 0, At, B0); PG8_MMA(0, 1, At, B1); PG8_BAR; PG8_SCHED;
	s_add_u32 s26, s26, 0xb0000
	s_addc_u32 s27, s27, 0
	s_mov_b32 m0, s39
	v_lshl_add_u64 v[226:227], s[26:27], 0, v[130:131]
	ds_read_b128 v[190:193], v152 offset:32768
	ds_read_b128 v[194:197], v152 offset:33792
	ds_read_b128 v[198:201], v152 offset:34816
	ds_read_b128 v[202:205], v152 offset:35840
	ds_read_b128 v[206:209], v152 offset:36864
	ds_read_b128 v[210:213], v152 offset:37888
	ds_read_b128 v[214:217], v152 offset:38912
	ds_read_b128 v[218:221], v152 offset:39936
	global_load_lds_dwordx4 v[226:227], off
	v_lshl_add_u64 v[226:227], s[26:27], 0, v[134:135]
	s_mov_b32 m0, s40
	s_nop 0
	global_load_lds_dwordx4 v[226:227], off
	s_waitcnt vmcnt(8)
	s_waitcnt lgkmcnt(0)
	s_barrier
	s_setprio 1
	s_waitcnt lgkmcnt(0)
	v_mfma_f32_16x16x32_bf16 v[126:129], v[154:157], v[190:193], v[126:129]
	v_mfma_f32_16x16x32_bf16 v[122:125], v[162:165], v[190:193], v[122:125]
	v_mfma_f32_16x16x32_bf16 v[118:121], v[154:157], v[198:201], v[118:121]
	v_mfma_f32_16x16x32_bf16 v[110:113], v[162:165], v[198:201], v[110:113]
	v_mfma_f32_16x16x32_bf16 v[102:105], v[154:157], v[206:209], v[102:105]
	v_mfma_f32_16x16x32_bf16 v[94:97], v[162:165], v[206:209], v[94:97]
	v_mfma_f32_16x16x32_bf16 v[86:89], v[154:157], v[214:217], v[86:89]
	v_mfma_f32_16x16x32_bf16 v[78:81], v[162:165], v[214:217], v[78:81]
	v_mfma_f32_16x16x32_bf16 v[126:129], v[158:161], v[194:197], v[126:129]
	v_mfma_f32_16x16x32_bf16 v[122:125], v[166:169], v[194:197], v[122:125]
	v_mfma_f32_16x16x32_bf16 v[118:121], v[158:161], v[202:205], v[118:121]
	v_mfma_f32_16x16x32_bf16 v[110:113], v[166:169], v[202:205], v[110:113]
	v_mfma_f32_16x16x32_bf16 v[102:105], v[158:161], v[210:213], v[102:105]
	v_mfma_f32_16x16x32_bf16 v[94:97], v[166:169], v[210:213], v[94:97]
	v_mfma_f32_16x16x32_bf16 v[86:89], v[158:161], v[218:221], v[86:89]
	v_mfma_f32_16x16x32_bf16 v[78:81], v[166:169], v[218:221], v[78:81]
	s_setprio 0
	s_setprio 1
	v_mfma_f32_16x16x32_bf16 v[114:117], v[174:177], v[190:193], v[114:117]
	v_mfma_f32_16x16x32_bf16 v[106:109], v[182:185], v[190:193], v[106:109]
	v_mfma_f32_16x16x32_bf16 v[98:101], v[174:177], v[198:201], v[98:101]
	v_mfma_f32_16x16x32_bf16 v[90:93], v[182:185], v[198:201], v[90:93]
	v_mfma_f32_16x16x32_bf16 v[82:85], v[174:177], v[206:209], v[82:85]
	v_mfma_f32_16x16x32_bf16 v[74:77], v[182:185], v[206:209], v[74:77]
	v_mfma_f32_16x16x32_bf16 v[70:73], v[174:177], v[214:217], v[70:73]
	v_mfma_f32_16x16x32_bf16 v[66:69], v[182:185], v[214:217], v[66:69]
	v_mfma_f32_16x16x32_bf16 v[114:117], v[178:181], v[194:197], v[114:117]
	v_mfma_f32_16x16x32_bf16 v[106:109], v[186:189], v[194:197], v[106:109]
	v_mfma_f32_16x16x32_bf16 v[98:101], v[178:181], v[202:205], v[98:101]
	v_mfma_f32_16x16x32_bf16 v[90:93], v[186:189], v[202:205], v[90:93]
	v_mfma_f32_16x16x32_bf16 v[82:85], v[178:181], v[210:213], v[82:85]
	v_mfma_f32_16x16x32_bf16 v[74:77], v[186:189], v[210:213], v[74:77]
	v_mfma_f32_16x16x32_bf16 v[70:73], v[178:181], v[218:221], v[70:73]
	v_mfma_f32_16x16x32_bf16 v[66:69], v[186:189], v[218:221], v[66:69]
	s_setprio 0
	s_barrier

; #define PG8_STAGE(bufoff, gbase, voff) do { _Pragma("unroll") for (int _i = 0; _i < 2; ++_i) \
;         __builtin_amdgcn_global_load_lds((const unsigned*)((const char*)(gbase) + (voff)[_i]), (PG8_LAS unsigned*)(lds + (bufoff) + ldsw + _i * 8192), 16, 0, 0); } while (0)
; #define PG8_LDA(dst, b, h) do { _Pragma("unroll") for (int m = 0; m < 4; ++m) _Pragma("unroll") for (int k = 0; k < 2; ++k) dst[m][k] = *(const PG8_LAS bf16x8*)(lds + PG8_SA(b, h) + aoff + m * 2048 + k * 1024); } while (0)
; #define PG8_MMA(ai, bj, At, Bt) do { __builtin_amdgcn_s_setprio(1); _Pragma("unroll") for (int m = 0; m < 4; ++m) _Pragma("unroll") for (int n = 0; n < 2; ++n) _Pragma("unroll") for (int k = 0; k < 2; ++k) \
;         acc[ai][bj][m][n] = __builtin_amdgcn_mfma_f32_16x16x32_bf16(Bt[n][k], At[m][k], acc[ai][bj][m][n], 0, 0, 0); __builtin_amdgcn_s_setprio(0); } while (0)
; #define PG8_WAIT_V(n) asm volatile("s_waitcnt vmcnt(" #n ")" ::: "memory")
; #define PG8_WAIT_L(n) asm volatile("s_waitcnt lgkmcnt(" #n ")" ::: "memory")
; #define PG8_BAR __builtin_amdgcn_s_barrier()
; #define PG8_SCHED __builtin_amdgcn_sched_barrier(0)
; template <class Epi, class Sched, bool ALIGN_EPI = false, bool SP2 = false>
; __device__ __forceinline__ void gemm_phase(PG8_LAS unsigned char* lds, const Gemm g, const Sched& S, const Epi& E) {
;     ...
;             PG8_LDA(At, 1, 1); PG8_STAGE(PG8_SB(1, 0), b3, voffB); PG8_STAGE(PG8_SB(1, 1), b3 + hstep, voffB); PG8_STAGE(PG8_SA(1, 0), a3, voffA);
;             PG8_WAIT_V(8); PG8_WAIT_L(0); PG8_BAR; PG8_MMA(1, 0, At, B0); PG8_MMA(1, 1, At, B1); PG8_BAR; PG8_SCHED;
	s_add_i32 s26, s63, s34
	v_lshl_add_u64 v[146:147], v[146:147], 0, s[8:9]
	s_mov_b32 m0, s26
	ds_read_b128 v[190:193], v152 offset:49152
	ds_read_b128 v[194:197], v152 offset:50176
	ds_read_b128 v[198:201], v152 offset:51200
	ds_read_b128 v[202:205], v152 offset:52224
	ds_read_b128 v[206:209], v152 offset:53248
	ds_read_b128 v[210:213], v152 offset:54272
	ds_read_b128 v[214:217], v152 offset:55296
	ds_read_b128 v[218:221], v152 offset:56320
	global_load_lds_dwordx4 v[146:147], off
	s_add_i32 m0, s26, 0x2000
	s_add_u32 s24, s24, 0xb0080
	v_lshl_add_u64 v[146:147], v[170:171], 0, s[8:9]
	s_addc_u32 s25, s25, 0
	s_add_i32 s26, s64, s34
	global_load_lds_dwordx4 v[146:147], off
	v_lshl_add_u64 v[146:147], s[24:25], 0, v[132:133]
	s_mov_b32 m0, s26
	s_nop 0
	global_load_lds_dwordx4 v[146:147], off
	v_lshl_add_u64 v[146:147], s[24:25], 0, v[136:137]
	s_add_i32 m0, s26, 0x2000
	s_nop 0
	global_load_lds_dwordx4 v[146:147], off
	v_lshl_add_u64 v[146:147], v[222:223], 0, s[8:9]
	s_mov_b32 m0, s42
	s_nop 0
	global_load_lds_dwordx4 v[146:147], off
	v_lshl_add_u64 v[146:147], v[224:225], 0, s[8:9]
	s_mov_b32 m0, s43
	s_nop 0
	global_load_lds_dwordx4 v[146:147], off
	s_waitcnt vmcnt(8)
	s_waitcnt lgkmcnt(0)
	s_barrier
	s_setprio 1
	s_waitcnt lgkmcnt(0)
	v_mfma_f32_16x16x32_bf16 v[62:65], v[154:157], v[190:193], v[62:65]
	v_mfma_f32_16x16x32_bf16 v[58:61], v[162:165], v[190:193], v[58:61]
	v_mfma_f32_16x16x32_bf16 v[54:57], v[154:157], v[198:201], v[54:57]
	v_mfma_f32_16x16x32_bf16 v[46:49], v[162:165], v[198:201], v[46:49]
	v_mfma_f32_16x16x32_bf16 v[38:41], v[154:157], v[206:209], v[38:41]
	v_mfma_f32_16x16x32_bf16 v[30:33], v[162:165], v[206:209], v[30:33]
	v_mfma_f32_16x16x32_bf16 v[22:25], v[154:157], v[214:217], v[22:25]
	v_mfma_f32_16x16x32_bf16 v[14:17], v[162:165], v[214:217], v[14:17]
	v_mfma_f32_16x16x32_bf16 v[62:65], v[158:161], v[194:197], v[62:65]
	v_mfma_f32_16x16x32_bf16 v[58:61], v[166:169], v[194:197], v[58:61]
	v_mfma_f32_16x16x32_bf16 v[54:57], v[158:161], v[202:205], v[54:57]
	v_mfma_f32_16x16x32_bf16 v[46:49], v[166:169], v[202:205], v[46:49]
	v_mfma_f32_16x16x32_bf16 v[38:41], v[158:161], v[210:213], v[38:41]
	v_mfma_f32_16x16x32_bf16 v[30:33], v[166:169], v[210:213], v[30:33]
	v_mfma_f32_16x16x32_bf16 v[22:25], v[158:161], v[218:221], v[22:25]
	v_mfma_f32_16x16x32_bf16 v[14:17], v[166:169], v[218:221], v[14:17]
	s_setprio 0
	s_setprio 1
	v_mfma_f32_16x16x32_bf16 v[50:53], v[174:177], v[190:193], v[50:53]
	v_mfma_f32_16x16x32_bf16 v[42:45], v[182:185], v[190:193], v[42:45]
	v_mfma_f32_16x16x32_bf16 v[34:37], v[174:177], v[198:201], v[34:37]
	v_mfma_f32_16x16x32_bf16 v[26:29], v[182:185], v[198:201], v[26:29]
	v_mfma_f32_16x16x32_bf16 v[18:21], v[174:177], v[206:209], v[18:21]
	v_mfma_f32_16x16x32_bf16 v[10:13], v[182:185], v[206:209], v[10:13]
	v_mfma_f32_16x16x32_bf16 v[6:9], v[174:177], v[214:217], v[6:9]
	v_mfma_f32_16x16x32_bf16 v[2:5], v[182:185], v[214:217], v[2:5]
	v_mfma_f32_16x16x32_bf16 v[50:53], v[178:181], v[194:197], v[50:53]
	v_mfma_f32_16x16x32_bf16 v[42:45], v[186:189], v[194:197], v[42:45]
	v_mfma_f32_16x16x32_bf16 v[34:37], v[178:181], v[202:205], v[34:37]
	v_mfma_f32_16x16x32_bf16 v[26:29], v[186:189], v[202:205], v[26:29]
	v_mfma_f32_16x16x32_bf16 v[18:21], v[178:181], v[210:213], v[18:21]
	v_mfma_f32_16x16x32_bf16 v[10:13], v[186:189], v[210:213], v[10:13]
	v_mfma_f32_16x16x32_bf16 v[6:9], v[178:181], v[218:221], v[6:9]
	v_mfma_f32_16x16x32_bf16 v[2:5], v[186:189], v[218:221], v[2:5]
	s_setprio 0
	s_barrier

; template <class Epi, class Sched, bool ALIGN_EPI = false, bool SP2 = false>
; __device__ __forceinline__ void gemm_phase(PG8_LAS unsigned char* lds, const Gemm g, const Sched& S, const Epi& E) {
;     ...
;         for (int t = 0; t < nt; t += 2) {
;             const bool last = (t == nt - 2);
;             const char* a1 = cA + (size_t)(t + 1) * kstep;
;             const char* a2 = last ? nA : cA + (size_t)(t + 2) * kstep; const char* b2 = last ? nB : cB + (size_t)(t + 2) * kstep;
;             const char* a3 = a2 + kstep; const char* b3 = b2 + kstep;
	s_add_i32 s62, s62, 2
	s_add_u32 s22, s22, 0x100
	s_addc_u32 s23, s23, 0
	s_add_u32 s60, s60, 0x100
	s_addc_u32 s61, s61, 0
